# sc1 write-through on 16B epilogue stores of P1,P3,P5,P6,P10 (cheaper L2 writeback at grid barriers)
# speedup vs baseline: 1.0061x; 1.0039x over previous
; __device__ __forceinline__ unsigned pkh(float lo, float hi) { f32x2 v = {lo, hi}; h16x2 h = __builtin_convertvector(v, h16x2); return __builtin_bit_cast(unsigned, h); }
;     __device__ __forceinline__ void operator()(f32x4 (&acc)[2][2][4][2], const Unit& u, const Order& S, int wr, int wc, int fr_, int fq_, LAS unsigned char*, int) const {
;     ...
;                 const int row = row0 + ai * HALF + m * 16;
;                 const float sc = __builtin_amdgcn_rsqf(ss_in[row] * (1.0f / DM) + EPS);
;                 float sq = 0.f;
; #pragma unroll
;                 for (int bj = 0; bj < 2; ++bj) {
;                     f32x4 v0 = acc[ai][bj][m][0] * sc, v1 = acc[ai][bj][m][1] * sc;
;                     if (act) { const f32x2 a0 = gelu_tanh2((f32x2){v0[0], v0[1]}), a1 = gelu_tanh2((f32x2){v0[2], v0[3]}), a2 = gelu_tanh2((f32x2){v1[0], v1[1]}), a3 = gelu_tanh2((f32x2){v1[2], v1[3]});
;                         v0 = (f32x4){a0.x, a0.y, a1.x, a1.y}; v1 = (f32x4){a2.x, a2.y, a3.x, a3.y}; }
;                     sq += (v0[0] * v0[0] + v0[1] * v0[1]) + (v0[2] * v0[2] + v0[3] * v0[3]) + (v1[0] * v1[0] + v1[1] * v1[1]) + (v1[2] * v1[2] + v1[3] * v1[3]);
;                     u32x4 w; w.x = pkh(v0[0], v0[1]); w.y = pkh(v0[2], v0[3]); w.z = pkh(v1[0], v1[1]); w.w = pkh(v1[2], v1[3]);
;                     *(u32x4*)(P + (size_t)row * NA + col0 + bj * HALF) = w;
;                 }
;                 if (stat && !dry) { sq += __shfl_xor(sq, 16); sq += __shfl_xor(sq, 32); if (fq == 0) atomicAdd(ssv + row, sq); }
.LBB0_184:
	s_lshl_b32 s3, s2, 8
	s_or_b32 s3, s3, s52
	v_lshl_add_u32 v122, v158, 3, s3
	v_mov_b64_e32 v[142:143], s[58:59]
	v_ashrrev_i32_e32 v123, 31, v122
	v_mad_i64_i32 v[142:143], s[4:5], v134, s61, v[142:143]
	v_cvt_pk_f16_f32 v162, v126, v127
	v_cvt_pk_f16_f32 v163, v128, v129
	v_cvt_pk_f16_f32 v164, v138, v139
	v_cvt_pk_f16_f32 v165, v124, v125
	v_lshl_add_u64 v[142:143], v[122:123], 1, v[142:143]
	v_mov_b32_e32 v141, v140
	global_store_dwordx4 v[142:143], v[162:165], off sc1
	v_cndmask_b32_e64 v159, 0, 1, s[6:7]
	v_pk_mul_f32 v[118:119], v[118:119], v[140:141]
	v_mov_b32_e32 v162, v140
	v_mov_b32_e32 v163, v140
	v_pk_mul_f32 v[120:121], v[120:121], v[162:163]
	v_pk_mul_f32 v[116:117], v[116:117], v[162:163]
	v_cmp_ne_u32_e64 s[4:5], 1, v159
	s_andn2_b64 vcc, exec, s[6:7]
	v_pk_mul_f32 v[114:115], v[114:115], v[140:141]
	s_cbranch_vccnz .LBB0_186
	v_pk_mul_f32 v[140:141], v[120:121], v[120:121]
	v_pk_mul_f32 v[162:163], v[118:119], v[118:119]
	v_mov_b64_e32 v[164:165], s[30:31]
	v_pk_mul_f32 v[168:169], v[116:117], v[116:117]
	v_pk_mul_f32 v[170:171], v[114:115], v[114:115]
	v_pk_fma_f32 v[162:163], v[162:163], s[28:29], v[164:165] op_sel_hi:[1,0,0] neg_lo:[1,0,0] neg_hi:[1,0,0]
	v_pk_fma_f32 v[140:141], v[140:141], s[28:29], v[164:165] op_sel_hi:[1,0,0] neg_lo:[1,0,0] neg_hi:[1,0,0]
	v_pk_fma_f32 v[170:171], v[170:171], s[28:29], v[164:165] op_sel_hi:[1,0,0] neg_lo:[1,0,0] neg_hi:[1,0,0]
	v_pk_fma_f32 v[164:165], v[168:169], s[28:29], v[164:165] op_sel_hi:[1,0,0] neg_lo:[1,0,0] neg_hi:[1,0,0]
	v_pk_mul_f32 v[162:163], v[118:119], v[162:163]
	v_pk_mul_f32 v[140:141], v[120:121], v[140:141]
	v_pk_mul_f32 v[170:171], v[114:115], v[170:171]
	v_pk_mul_f32 v[164:165], v[116:117], v[164:165]
	v_exp_f32_e32 v162, v162
	v_exp_f32_e32 v163, v163
	v_exp_f32_e32 v140, v140
	v_exp_f32_e32 v141, v141
	v_exp_f32_e32 v170, v170
	v_exp_f32_e32 v171, v171
	v_exp_f32_e32 v164, v164
	v_exp_f32_e32 v165, v165
	v_pk_add_f32 v[162:163], v[162:163], 1.0 op_sel_hi:[1,0]
	v_pk_add_f32 v[140:141], v[140:141], 1.0 op_sel_hi:[1,0]
	v_pk_add_f32 v[168:169], v[170:171], 1.0 op_sel_hi:[1,0]
	v_pk_add_f32 v[164:165], v[164:165], 1.0 op_sel_hi:[1,0]
	v_rcp_f32_e32 v162, v162
	v_rcp_f32_e32 v163, v163
	v_rcp_f32_e32 v140, v140
	v_rcp_f32_e32 v141, v141
	v_rcp_f32_e32 v168, v168
	v_rcp_f32_e32 v164, v164
	v_rcp_f32_e32 v165, v165
	v_rcp_f32_e32 v169, v169
	v_pk_mul_f32 v[120:121], v[120:121], v[140:141]
	v_pk_mul_f32 v[118:119], v[118:119], v[162:163]
	v_pk_mul_f32 v[116:117], v[116:117], v[164:165]
	v_pk_mul_f32 v[114:115], v[114:115], v[168:169]
.LBB0_186:
	s_add_i32 s2, s2, -6
	s_cmp_gt_u32 s2, -4
	s_cselect_b64 s[40:41], -1, 0
	s_cmp_lt_u32 s2, -3
	v_cmp_eq_u32_e64 s[2:3], 0, v158
	v_cvt_pk_f16_f32 v162, v118, v119
	v_cvt_pk_f16_f32 v163, v120, v121
	v_cvt_pk_f16_f32 v164, v114, v115
	v_cvt_pk_f16_f32 v165, v116, v117
	global_store_dwordx4 v[142:143], v[162:165], off offset:256 sc1
	s_cbranch_scc1 .LBB0_190
	v_mul_f32_e32 v127, v127, v127
	v_mul_f32_e32 v117, v117, v117
	v_mul_f32_e32 v115, v115, v115
	v_fmac_f32_e32 v127, v126, v126
	v_mul_f32_e32 v126, v129, v129
	v_fmac_f32_e32 v117, v116, v116
	v_fmac_f32_e32 v115, v114, v114
	v_mul_f32_e32 v114, v119, v119
	v_mul_f32_e32 v116, v121, v121
	v_fmac_f32_e32 v126, v128, v128
	v_fmac_f32_e32 v114, v118, v118
	v_fmac_f32_e32 v116, v120, v120
	v_add_f32_e32 v126, v127, v126
	v_mul_f32_e32 v127, v139, v139
	v_add_f32_e32 v114, v114, v116
	v_and_b32_e32 v116, 64, v157
	v_fmac_f32_e32 v127, v138, v138
	v_mul_f32_e32 v125, v125, v125
	v_add_f32_e32 v114, v115, v114
	v_xor_b32_e32 v115, 16, v157
	v_add_u32_e32 v116, 64, v116
	v_add_f32_e32 v126, v127, v126
	v_fmac_f32_e32 v125, v124, v124
	v_cmp_lt_i32_e32 vcc, v115, v116
	v_add_f32_e32 v124, v125, v126
	v_add_f32_e32 v114, v117, v114
	v_cndmask_b32_e32 v115, v157, v115, vcc
	v_add_f32_e32 v114, v124, v114
	v_lshlrev_b32_e32 v115, 2, v115
	ds_bpermute_b32 v115, v115, v114
	s_waitcnt lgkmcnt(0)
	v_add_f32_e32 v114, v114, v115
	v_xor_b32_e32 v115, 32, v157
	v_cmp_lt_i32_e32 vcc, v115, v116
	s_nop 1
	v_cndmask_b32_e32 v115, v157, v115, vcc
	v_lshlrev_b32_e32 v115, 2, v115
	ds_bpermute_b32 v115, v115, v114
	s_and_saveexec_b64 s[6:7], s[2:3]
	s_cbranch_execz .LBB0_189
	v_lshl_add_u64 v[116:117], v[134:135], 2, s[12:13]
	s_waitcnt lgkmcnt(0)
	v_add_f32_e32 v114, v114, v115
	global_atomic_add_f32 v[116:117], v114, off

; __device__ __forceinline__ unsigned pkh(float lo, float hi) { f32x2 v = {lo, hi}; h16x2 h = __builtin_convertvector(v, h16x2); return __builtin_bit_cast(unsigned, h); }
;     __device__ __forceinline__ void operator()(f32x4 (&acc)[2][2][4][2], const Unit& u, const Order& S, int wr, int wc, int fr_, int fq_, LAS unsigned char*, int) const {
;     ...
;                 const int row = row0 + ai * HALF + m * 16;
;                 const float sc = __builtin_amdgcn_rsqf(ss_in[row] * (1.0f / DM) + EPS);
;                 float sq = 0.f;
; #pragma unroll
;                 for (int bj = 0; bj < 2; ++bj) {
;                     f32x4 v0 = acc[ai][bj][m][0] * sc, v1 = acc[ai][bj][m][1] * sc;
;                     if (act) { const f32x2 a0 = gelu_tanh2((f32x2){v0[0], v0[1]}), a1 = gelu_tanh2((f32x2){v0[2], v0[3]}), a2 = gelu_tanh2((f32x2){v1[0], v1[1]}), a3 = gelu_tanh2((f32x2){v1[2], v1[3]});
;                         v0 = (f32x4){a0.x, a0.y, a1.x, a1.y}; v1 = (f32x4){a2.x, a2.y, a3.x, a3.y}; }
;                     sq += (v0[0] * v0[0] + v0[1] * v0[1]) + (v0[2] * v0[2] + v0[3] * v0[3]) + (v1[0] * v1[0] + v1[1] * v1[1]) + (v1[2] * v1[2] + v1[3] * v1[3]);
;                     u32x4 w; w.x = pkh(v0[0], v0[1]); w.y = pkh(v0[2], v0[3]); w.z = pkh(v1[0], v1[1]); w.w = pkh(v1[2], v1[3]);
;                     *(u32x4*)(P + (size_t)row * NA + col0 + bj * HALF) = w;
;                 }
;                 if (stat && !dry) { sq += __shfl_xor(sq, 16); sq += __shfl_xor(sq, 32); if (fq == 0) atomicAdd(ssv + row, sq); }
.LBB0_192:
	v_add_u32_e32 v114, 16, v134
	v_mov_b64_e32 v[118:119], s[58:59]
	v_mov_b32_e32 v117, v116
	v_mad_i64_i32 v[118:119], s[6:7], v114, s61, v[118:119]
	v_mov_b32_e32 v120, v116
	v_mov_b32_e32 v121, v116
	v_cvt_pk_f16_f32 v124, v110, v111
	v_cvt_pk_f16_f32 v125, v112, v113
	v_cvt_pk_f16_f32 v126, v106, v107
	v_cvt_pk_f16_f32 v127, v108, v109
	v_lshl_add_u64 v[118:119], v[122:123], 1, v[118:119]
	v_pk_mul_f32 v[104:105], v[104:105], v[120:121]
	v_pk_mul_f32 v[102:103], v[102:103], v[116:117]
	v_pk_mul_f32 v[100:101], v[100:101], v[120:121]
	s_and_b64 vcc, exec, s[4:5]
	v_pk_mul_f32 v[98:99], v[98:99], v[116:117]
	global_store_dwordx4 v[118:119], v[124:127], off sc1
	s_cbranch_vccnz .LBB0_194
	v_pk_mul_f32 v[116:117], v[104:105], v[104:105]
	v_pk_mul_f32 v[120:121], v[102:103], v[102:103]
	v_mov_b64_e32 v[124:125], s[30:31]
	v_pk_mul_f32 v[126:127], v[100:101], v[100:101]
	v_pk_mul_f32 v[128:129], v[98:99], v[98:99]
	v_pk_fma_f32 v[120:121], v[120:121], s[28:29], v[124:125] op_sel_hi:[1,0,0] neg_lo:[1,0,0] neg_hi:[1,0,0]
	v_pk_fma_f32 v[116:117], v[116:117], s[28:29], v[124:125] op_sel_hi:[1,0,0] neg_lo:[1,0,0] neg_hi:[1,0,0]
	v_pk_fma_f32 v[128:129], v[128:129], s[28:29], v[124:125] op_sel_hi:[1,0,0] neg_lo:[1,0,0] neg_hi:[1,0,0]
	v_pk_fma_f32 v[124:125], v[126:127], s[28:29], v[124:125] op_sel_hi:[1,0,0] neg_lo:[1,0,0] neg_hi:[1,0,0]
	v_pk_mul_f32 v[120:121], v[102:103], v[120:121]
	v_pk_mul_f32 v[116:117], v[104:105], v[116:117]
	v_pk_mul_f32 v[128:129], v[98:99], v[128:129]
	v_pk_mul_f32 v[124:125], v[100:101], v[124:125]
	v_exp_f32_e32 v120, v120
	v_exp_f32_e32 v121, v121
	v_exp_f32_e32 v116, v116
	v_exp_f32_e32 v117, v117
	v_exp_f32_e32 v128, v128
	v_exp_f32_e32 v129, v129
	v_exp_f32_e32 v124, v124
	v_exp_f32_e32 v125, v125
	v_pk_add_f32 v[120:121], v[120:121], 1.0 op_sel_hi:[1,0]
	v_pk_add_f32 v[116:117], v[116:117], 1.0 op_sel_hi:[1,0]
	v_pk_add_f32 v[126:127], v[128:129], 1.0 op_sel_hi:[1,0]
	v_pk_add_f32 v[124:125], v[124:125], 1.0 op_sel_hi:[1,0]
	v_rcp_f32_e32 v120, v120
	v_rcp_f32_e32 v121, v121
	v_rcp_f32_e32 v116, v116
	v_rcp_f32_e32 v117, v117
	v_rcp_f32_e32 v126, v126
	v_rcp_f32_e32 v124, v124
	v_rcp_f32_e32 v125, v125
	v_rcp_f32_e32 v127, v127
	v_pk_mul_f32 v[104:105], v[104:105], v[116:117]
	v_pk_mul_f32 v[102:103], v[102:103], v[120:121]
	v_pk_mul_f32 v[100:101], v[100:101], v[124:125]
	v_pk_mul_f32 v[98:99], v[98:99], v[126:127]
.LBB0_194:
	s_waitcnt lgkmcnt(0)
	v_cndmask_b32_e64 v115, 0, 1, s[40:41]
	v_cvt_pk_f16_f32 v124, v102, v103
	v_cvt_pk_f16_f32 v125, v104, v105
	v_cvt_pk_f16_f32 v126, v98, v99
	v_cvt_pk_f16_f32 v127, v100, v101
	v_cmp_ne_u32_e64 s[6:7], 1, v115
	s_andn2_b64 vcc, exec, s[40:41]
	global_store_dwordx4 v[118:119], v[124:127], off offset:256 sc1
	s_cbranch_vccnz .LBB0_198
	v_mul_f32_e32 v111, v111, v111
	v_mul_f32_e32 v101, v101, v101
	v_mul_f32_e32 v99, v99, v99
	v_fmac_f32_e32 v111, v110, v110
	v_mul_f32_e32 v110, v113, v113
	v_fmac_f32_e32 v101, v100, v100
	v_fmac_f32_e32 v99, v98, v98
	v_mul_f32_e32 v98, v103, v103
	v_mul_f32_e32 v100, v105, v105
	v_fmac_f32_e32 v110, v112, v112
	v_mul_f32_e32 v107, v107, v107
	v_fmac_f32_e32 v98, v102, v102
	v_fmac_f32_e32 v100, v104, v104
	v_add_f32_e32 v110, v111, v110
	v_fmac_f32_e32 v107, v106, v106
	v_add_f32_e32 v98, v98, v100
	v_and_b32_e32 v100, 64, v157
	v_add_f32_e32 v106, v107, v110
	v_mul_f32_e32 v107, v109, v109
	v_add_f32_e32 v98, v99, v98
	v_xor_b32_e32 v99, 16, v157
	v_add_u32_e32 v100, 64, v100
	v_fmac_f32_e32 v107, v108, v108
	v_cmp_lt_i32_e32 vcc, v99, v100
	v_add_f32_e32 v106, v107, v106
	v_add_f32_e32 v98, v101, v98
	v_cndmask_b32_e32 v99, v157, v99, vcc
	v_add_f32_e32 v98, v106, v98
	v_lshlrev_b32_e32 v99, 2, v99
	ds_bpermute_b32 v99, v99, v98
	s_waitcnt lgkmcnt(0)
	v_add_f32_e32 v98, v98, v99
	v_xor_b32_e32 v99, 32, v157
	v_cmp_lt_i32_e32 vcc, v99, v100
	s_nop 1
	v_cndmask_b32_e32 v99, v157, v99, vcc
	v_lshlrev_b32_e32 v99, 2, v99
	ds_bpermute_b32 v99, v99, v98
	s_and_saveexec_b64 s[40:41], s[2:3]
	s_cbranch_execz .LBB0_197
	v_ashrrev_i32_e32 v115, 31, v114
	v_lshl_add_u64 v[100:101], v[114:115], 2, s[12:13]
	s_waitcnt lgkmcnt(0)
	v_add_f32_e32 v98, v98, v99
	global_atomic_add_f32 v[100:101], v98, off

; __device__ __forceinline__ unsigned pkh(float lo, float hi) { f32x2 v = {lo, hi}; h16x2 h = __builtin_convertvector(v, h16x2); return __builtin_bit_cast(unsigned, h); }
;     __device__ __forceinline__ void operator()(f32x4 (&acc)[2][2][4][2], const Unit& u, const Order& S, int wr, int wc, int fr_, int fq_, LAS unsigned char*, int) const {
;     ...
;                 const int row = row0 + ai * HALF + m * 16;
;                 const float sc = __builtin_amdgcn_rsqf(ss_in[row] * (1.0f / DM) + EPS);
;                 float sq = 0.f;
; #pragma unroll
;                 for (int bj = 0; bj < 2; ++bj) {
;                     f32x4 v0 = acc[ai][bj][m][0] * sc, v1 = acc[ai][bj][m][1] * sc;
;                     if (act) { const f32x2 a0 = gelu_tanh2((f32x2){v0[0], v0[1]}), a1 = gelu_tanh2((f32x2){v0[2], v0[3]}), a2 = gelu_tanh2((f32x2){v1[0], v1[1]}), a3 = gelu_tanh2((f32x2){v1[2], v1[3]});
;                         v0 = (f32x4){a0.x, a0.y, a1.x, a1.y}; v1 = (f32x4){a2.x, a2.y, a3.x, a3.y}; }
;                     sq += (v0[0] * v0[0] + v0[1] * v0[1]) + (v0[2] * v0[2] + v0[3] * v0[3]) + (v1[0] * v1[0] + v1[1] * v1[1]) + (v1[2] * v1[2] + v1[3] * v1[3]);
;                     u32x4 w; w.x = pkh(v0[0], v0[1]); w.y = pkh(v0[2], v0[3]); w.z = pkh(v1[0], v1[1]); w.w = pkh(v1[2], v1[3]);
;                     *(u32x4*)(P + (size_t)row * NA + col0 + bj * HALF) = w;
;                 }
;                 if (stat && !dry) { sq += __shfl_xor(sq, 16); sq += __shfl_xor(sq, 32); if (fq == 0) atomicAdd(ssv + row, sq); }
.LBB0_200:
	v_add_u32_e32 v98, 32, v134
	v_mov_b64_e32 v[102:103], s[58:59]
	v_mad_i64_i32 v[102:103], s[40:41], v98, s61, v[102:103]
	v_cvt_pk_f16_f32 v104, v94, v95
	v_cvt_pk_f16_f32 v105, v96, v97
	v_cvt_pk_f16_f32 v106, v90, v91
	v_cvt_pk_f16_f32 v107, v92, v93
	v_lshl_add_u64 v[102:103], v[122:123], 1, v[102:103]
	v_mov_b32_e32 v101, v100
	global_store_dwordx4 v[102:103], v[104:107], off sc1
	v_pk_mul_f32 v[86:87], v[86:87], v[100:101]
	s_and_b64 vcc, exec, s[4:5]
	v_mov_b32_e32 v104, v100
	v_mov_b32_e32 v105, v100
	v_pk_mul_f32 v[88:89], v[88:89], v[104:105]
	v_pk_mul_f32 v[84:85], v[84:85], v[104:105]
	v_pk_mul_f32 v[82:83], v[82:83], v[100:101]
	s_cbranch_vccnz .LBB0_202
	v_pk_mul_f32 v[100:101], v[88:89], v[88:89]
	v_pk_mul_f32 v[104:105], v[86:87], v[86:87]
	v_mov_b64_e32 v[106:107], s[30:31]
	v_pk_mul_f32 v[108:109], v[84:85], v[84:85]
	v_pk_mul_f32 v[110:111], v[82:83], v[82:83]
	v_pk_fma_f32 v[104:105], v[104:105], s[28:29], v[106:107] op_sel_hi:[1,0,0] neg_lo:[1,0,0] neg_hi:[1,0,0]
	v_pk_fma_f32 v[100:101], v[100:101], s[28:29], v[106:107] op_sel_hi:[1,0,0] neg_lo:[1,0,0] neg_hi:[1,0,0]
	v_pk_fma_f32 v[110:111], v[110:111], s[28:29], v[106:107] op_sel_hi:[1,0,0] neg_lo:[1,0,0] neg_hi:[1,0,0]
	v_pk_fma_f32 v[106:107], v[108:109], s[28:29], v[106:107] op_sel_hi:[1,0,0] neg_lo:[1,0,0] neg_hi:[1,0,0]
	v_pk_mul_f32 v[104:105], v[86:87], v[104:105]
	v_pk_mul_f32 v[100:101], v[88:89], v[100:101]
	v_pk_mul_f32 v[110:111], v[82:83], v[110:111]
	v_pk_mul_f32 v[106:107], v[84:85], v[106:107]
	v_exp_f32_e32 v104, v104
	v_exp_f32_e32 v105, v105
	v_exp_f32_e32 v100, v100
	v_exp_f32_e32 v101, v101
	v_exp_f32_e32 v110, v110
	v_exp_f32_e32 v111, v111
	v_exp_f32_e32 v106, v106
	v_exp_f32_e32 v107, v107
	v_pk_add_f32 v[104:105], v[104:105], 1.0 op_sel_hi:[1,0]
	v_pk_add_f32 v[100:101], v[100:101], 1.0 op_sel_hi:[1,0]
	v_pk_add_f32 v[108:109], v[110:111], 1.0 op_sel_hi:[1,0]
	v_pk_add_f32 v[106:107], v[106:107], 1.0 op_sel_hi:[1,0]
	v_rcp_f32_e32 v104, v104
	v_rcp_f32_e32 v105, v105
	v_rcp_f32_e32 v100, v100
	v_rcp_f32_e32 v101, v101
	v_rcp_f32_e32 v108, v108
	v_rcp_f32_e32 v106, v106
	v_rcp_f32_e32 v107, v107
	v_rcp_f32_e32 v109, v109
	v_pk_mul_f32 v[88:89], v[88:89], v[100:101]
	v_pk_mul_f32 v[86:87], v[86:87], v[104:105]
	v_pk_mul_f32 v[84:85], v[84:85], v[106:107]
	v_pk_mul_f32 v[82:83], v[82:83], v[108:109]
.LBB0_202:
	v_cvt_pk_f16_f32 v104, v86, v87
	v_cvt_pk_f16_f32 v105, v88, v89
	v_cvt_pk_f16_f32 v106, v82, v83
	v_cvt_pk_f16_f32 v107, v84, v85
	s_and_b64 vcc, exec, s[6:7]
	global_store_dwordx4 v[102:103], v[104:107], off offset:256 sc1
	s_cbranch_vccnz .LBB0_206
	v_mul_f32_e32 v95, v95, v95
	v_mul_f32_e32 v85, v85, v85
	v_mul_f32_e32 v83, v83, v83
	v_fmac_f32_e32 v95, v94, v94
	v_mul_f32_e32 v94, v97, v97
	v_fmac_f32_e32 v85, v84, v84
	v_fmac_f32_e32 v83, v82, v82
	v_mul_f32_e32 v82, v87, v87
	v_mul_f32_e32 v84, v89, v89
	v_fmac_f32_e32 v94, v96, v96
	v_mul_f32_e32 v91, v91, v91
	v_fmac_f32_e32 v82, v86, v86
	v_fmac_f32_e32 v84, v88, v88
	v_add_f32_e32 v94, v95, v94
	v_fmac_f32_e32 v91, v90, v90
	v_add_f32_e32 v82, v82, v84
	v_and_b32_e32 v84, 64, v157
	v_add_f32_e32 v90, v91, v94
	v_mul_f32_e32 v91, v93, v93
	v_add_f32_e32 v82, v83, v82
	v_xor_b32_e32 v83, 16, v157
	v_add_u32_e32 v84, 64, v84
	v_fmac_f32_e32 v91, v92, v92
	v_cmp_lt_i32_e32 vcc, v83, v84
	v_add_f32_e32 v90, v91, v90
	v_add_f32_e32 v82, v85, v82
	v_cndmask_b32_e32 v83, v157, v83, vcc
	v_add_f32_e32 v82, v90, v82
	v_lshlrev_b32_e32 v83, 2, v83
	ds_bpermute_b32 v83, v83, v82
	s_waitcnt lgkmcnt(0)
	v_add_f32_e32 v82, v82, v83
	v_xor_b32_e32 v83, 32, v157
	v_cmp_lt_i32_e32 vcc, v83, v84
	s_nop 1
	v_cndmask_b32_e32 v83, v157, v83, vcc
	v_lshlrev_b32_e32 v83, 2, v83
	ds_bpermute_b32 v83, v83, v82
	s_and_saveexec_b64 s[40:41], s[2:3]
	s_cbranch_execz .LBB0_205
	v_ashrrev_i32_e32 v99, 31, v98
	v_lshl_add_u64 v[84:85], v[98:99], 2, s[12:13]
	s_waitcnt lgkmcnt(0)
	v_add_f32_e32 v82, v82, v83
	global_atomic_add_f32 v[84:85], v82, off

; __device__ __forceinline__ unsigned pkh(float lo, float hi) { f32x2 v = {lo, hi}; h16x2 h = __builtin_convertvector(v, h16x2); return __builtin_bit_cast(unsigned, h); }
;     __device__ __forceinline__ void operator()(f32x4 (&acc)[2][2][4][2], const Unit& u, const Order& S, int wr, int wc, int fr_, int fq_, LAS unsigned char*, int) const {
;     ...
;                 const int row = row0 + ai * HALF + m * 16;
;                 const float sc = __builtin_amdgcn_rsqf(ss_in[row] * (1.0f / DM) + EPS);
;                 float sq = 0.f;
; #pragma unroll
;                 for (int bj = 0; bj < 2; ++bj) {
;                     f32x4 v0 = acc[ai][bj][m][0] * sc, v1 = acc[ai][bj][m][1] * sc;
;                     if (act) { const f32x2 a0 = gelu_tanh2((f32x2){v0[0], v0[1]}), a1 = gelu_tanh2((f32x2){v0[2], v0[3]}), a2 = gelu_tanh2((f32x2){v1[0], v1[1]}), a3 = gelu_tanh2((f32x2){v1[2], v1[3]});
;                         v0 = (f32x4){a0.x, a0.y, a1.x, a1.y}; v1 = (f32x4){a2.x, a2.y, a3.x, a3.y}; }
;                     sq += (v0[0] * v0[0] + v0[1] * v0[1]) + (v0[2] * v0[2] + v0[3] * v0[3]) + (v1[0] * v1[0] + v1[1] * v1[1]) + (v1[2] * v1[2] + v1[3] * v1[3]);
;                     u32x4 w; w.x = pkh(v0[0], v0[1]); w.y = pkh(v0[2], v0[3]); w.z = pkh(v1[0], v1[1]); w.w = pkh(v1[2], v1[3]);
;                     *(u32x4*)(P + (size_t)row * NA + col0 + bj * HALF) = w;
;                 }
;                 if (stat && !dry) { sq += __shfl_xor(sq, 16); sq += __shfl_xor(sq, 32); if (fq == 0) atomicAdd(ssv + row, sq); }
.LBB0_208:
	v_add_u32_e32 v82, 48, v134
	v_mov_b64_e32 v[86:87], s[58:59]
	v_mad_i64_i32 v[86:87], s[40:41], v82, s61, v[86:87]
	v_cvt_pk_f16_f32 v88, v78, v79
	v_cvt_pk_f16_f32 v89, v80, v81
	v_cvt_pk_f16_f32 v90, v74, v75
	v_cvt_pk_f16_f32 v91, v76, v77
	v_lshl_add_u64 v[86:87], v[122:123], 1, v[86:87]
	v_mov_b32_e32 v85, v84
	global_store_dwordx4 v[86:87], v[88:91], off sc1
	v_pk_mul_f32 v[70:71], v[70:71], v[84:85]
	s_and_b64 vcc, exec, s[4:5]
	v_mov_b32_e32 v88, v84
	v_mov_b32_e32 v89, v84
	v_pk_mul_f32 v[72:73], v[72:73], v[88:89]
	v_pk_mul_f32 v[68:69], v[68:69], v[88:89]
	v_pk_mul_f32 v[66:67], v[66:67], v[84:85]
	s_cbranch_vccnz .LBB0_210
	v_pk_mul_f32 v[84:85], v[72:73], v[72:73]
	v_pk_mul_f32 v[88:89], v[70:71], v[70:71]
	v_mov_b64_e32 v[90:91], s[30:31]
	v_pk_mul_f32 v[92:93], v[68:69], v[68:69]
	v_pk_mul_f32 v[94:95], v[66:67], v[66:67]
	v_pk_fma_f32 v[88:89], v[88:89], s[28:29], v[90:91] op_sel_hi:[1,0,0] neg_lo:[1,0,0] neg_hi:[1,0,0]
	v_pk_fma_f32 v[84:85], v[84:85], s[28:29], v[90:91] op_sel_hi:[1,0,0] neg_lo:[1,0,0] neg_hi:[1,0,0]
	v_pk_fma_f32 v[94:95], v[94:95], s[28:29], v[90:91] op_sel_hi:[1,0,0] neg_lo:[1,0,0] neg_hi:[1,0,0]
	v_pk_fma_f32 v[90:91], v[92:93], s[28:29], v[90:91] op_sel_hi:[1,0,0] neg_lo:[1,0,0] neg_hi:[1,0,0]
	v_pk_mul_f32 v[88:89], v[70:71], v[88:89]
	v_pk_mul_f32 v[84:85], v[72:73], v[84:85]
	v_pk_mul_f32 v[94:95], v[66:67], v[94:95]
	v_pk_mul_f32 v[90:91], v[68:69], v[90:91]
	v_exp_f32_e32 v88, v88
	v_exp_f32_e32 v89, v89
	v_exp_f32_e32 v84, v84
	v_exp_f32_e32 v85, v85
	v_exp_f32_e32 v94, v94
	v_exp_f32_e32 v95, v95
	v_exp_f32_e32 v90, v90
	v_exp_f32_e32 v91, v91
	v_pk_add_f32 v[88:89], v[88:89], 1.0 op_sel_hi:[1,0]
	v_pk_add_f32 v[84:85], v[84:85], 1.0 op_sel_hi:[1,0]
	v_pk_add_f32 v[92:93], v[94:95], 1.0 op_sel_hi:[1,0]
	v_pk_add_f32 v[90:91], v[90:91], 1.0 op_sel_hi:[1,0]
	v_rcp_f32_e32 v88, v88
	v_rcp_f32_e32 v89, v89
	v_rcp_f32_e32 v84, v84
	v_rcp_f32_e32 v85, v85
	v_rcp_f32_e32 v92, v92
	v_rcp_f32_e32 v90, v90
	v_rcp_f32_e32 v91, v91
	v_rcp_f32_e32 v93, v93
	v_pk_mul_f32 v[72:73], v[72:73], v[84:85]
	v_pk_mul_f32 v[70:71], v[70:71], v[88:89]
	v_pk_mul_f32 v[68:69], v[68:69], v[90:91]
	v_pk_mul_f32 v[66:67], v[66:67], v[92:93]
.LBB0_210:
	v_cvt_pk_f16_f32 v88, v70, v71
	v_cvt_pk_f16_f32 v89, v72, v73
	v_cvt_pk_f16_f32 v90, v66, v67
	v_cvt_pk_f16_f32 v91, v68, v69
	s_and_b64 vcc, exec, s[6:7]
	global_store_dwordx4 v[86:87], v[88:91], off offset:256 sc1
	s_cbranch_vccnz .LBB0_214
	v_mul_f32_e32 v79, v79, v79
	v_mul_f32_e32 v69, v69, v69
	v_mul_f32_e32 v67, v67, v67
	v_fmac_f32_e32 v79, v78, v78
	v_mul_f32_e32 v78, v81, v81
	v_fmac_f32_e32 v69, v68, v68
	v_fmac_f32_e32 v67, v66, v66
	v_mul_f32_e32 v66, v71, v71
	v_mul_f32_e32 v68, v73, v73
	v_fmac_f32_e32 v78, v80, v80
	v_mul_f32_e32 v75, v75, v75
	v_fmac_f32_e32 v66, v70, v70
	v_fmac_f32_e32 v68, v72, v72
	v_add_f32_e32 v78, v79, v78
	v_fmac_f32_e32 v75, v74, v74
	v_add_f32_e32 v66, v66, v68
	v_and_b32_e32 v68, 64, v157
	v_add_f32_e32 v74, v75, v78
	v_mul_f32_e32 v75, v77, v77
	v_add_f32_e32 v66, v67, v66
	v_xor_b32_e32 v67, 16, v157
	v_add_u32_e32 v68, 64, v68
	v_fmac_f32_e32 v75, v76, v76
	v_cmp_lt_i32_e32 vcc, v67, v68
	v_add_f32_e32 v74, v75, v74
	v_add_f32_e32 v66, v69, v66
	v_cndmask_b32_e32 v67, v157, v67, vcc
	v_add_f32_e32 v66, v74, v66
	v_lshlrev_b32_e32 v67, 2, v67
	ds_bpermute_b32 v67, v67, v66
	s_waitcnt lgkmcnt(0)
	v_add_f32_e32 v66, v66, v67
	v_xor_b32_e32 v67, 32, v157
	v_cmp_lt_i32_e32 vcc, v67, v68
	s_nop 1
	v_cndmask_b32_e32 v67, v157, v67, vcc
	v_lshlrev_b32_e32 v67, 2, v67
	ds_bpermute_b32 v67, v67, v66
	s_and_saveexec_b64 s[40:41], s[2:3]
	s_cbranch_execz .LBB0_213
	v_ashrrev_i32_e32 v83, 31, v82
	v_lshl_add_u64 v[68:69], v[82:83], 2, s[12:13]
	s_waitcnt lgkmcnt(0)
	v_add_f32_e32 v66, v66, v67
	global_atomic_add_f32 v[68:69], v66, off

; __device__ __forceinline__ unsigned pkh(float lo, float hi) { f32x2 v = {lo, hi}; h16x2 h = __builtin_convertvector(v, h16x2); return __builtin_bit_cast(unsigned, h); }
;     __device__ __forceinline__ void operator()(f32x4 (&acc)[2][2][4][2], const Unit& u, const Order& S, int wr, int wc, int fr_, int fq_, LAS unsigned char*, int) const {
;     ...
;                 const int row = row0 + ai * HALF + m * 16;
;                 const float sc = __builtin_amdgcn_rsqf(ss_in[row] * (1.0f / DM) + EPS);
;                 float sq = 0.f;
; #pragma unroll
;                 for (int bj = 0; bj < 2; ++bj) {
;                     f32x4 v0 = acc[ai][bj][m][0] * sc, v1 = acc[ai][bj][m][1] * sc;
;                     if (act) { const f32x2 a0 = gelu_tanh2((f32x2){v0[0], v0[1]}), a1 = gelu_tanh2((f32x2){v0[2], v0[3]}), a2 = gelu_tanh2((f32x2){v1[0], v1[1]}), a3 = gelu_tanh2((f32x2){v1[2], v1[3]});
;                         v0 = (f32x4){a0.x, a0.y, a1.x, a1.y}; v1 = (f32x4){a2.x, a2.y, a3.x, a3.y}; }
;                     sq += (v0[0] * v0[0] + v0[1] * v0[1]) + (v0[2] * v0[2] + v0[3] * v0[3]) + (v1[0] * v1[0] + v1[1] * v1[1]) + (v1[2] * v1[2] + v1[3] * v1[3]);
;                     u32x4 w; w.x = pkh(v0[0], v0[1]); w.y = pkh(v0[2], v0[3]); w.z = pkh(v1[0], v1[1]); w.w = pkh(v1[2], v1[3]);
;                     *(u32x4*)(P + (size_t)row * NA + col0 + bj * HALF) = w;
;                 }
;                 if (stat && !dry) { sq += __shfl_xor(sq, 16); sq += __shfl_xor(sq, 32); if (fq == 0) atomicAdd(ssv + row, sq); }
.LBB0_216:
	v_add_u32_e32 v66, 0x80, v134
	v_mov_b64_e32 v[70:71], s[58:59]
	v_mad_i64_i32 v[70:71], s[40:41], v66, s61, v[70:71]
	v_cvt_pk_f16_f32 v72, v62, v63
	v_cvt_pk_f16_f32 v73, v64, v65
	v_cvt_pk_f16_f32 v74, v58, v59
	v_cvt_pk_f16_f32 v75, v60, v61
	v_lshl_add_u64 v[70:71], v[122:123], 1, v[70:71]
	v_mov_b32_e32 v69, v68
	global_store_dwordx4 v[70:71], v[72:75], off sc1
	v_pk_mul_f32 v[54:55], v[54:55], v[68:69]
	s_and_b64 vcc, exec, s[4:5]
	v_mov_b32_e32 v72, v68
	v_mov_b32_e32 v73, v68
	v_pk_mul_f32 v[56:57], v[56:57], v[72:73]
	v_pk_mul_f32 v[52:53], v[52:53], v[72:73]
	v_pk_mul_f32 v[50:51], v[50:51], v[68:69]
	s_cbranch_vccnz .LBB0_218
	v_pk_mul_f32 v[68:69], v[56:57], v[56:57]
	v_pk_mul_f32 v[72:73], v[54:55], v[54:55]
	v_mov_b64_e32 v[74:75], s[30:31]
	v_pk_mul_f32 v[76:77], v[52:53], v[52:53]
	v_pk_mul_f32 v[78:79], v[50:51], v[50:51]
	v_pk_fma_f32 v[72:73], v[72:73], s[28:29], v[74:75] op_sel_hi:[1,0,0] neg_lo:[1,0,0] neg_hi:[1,0,0]
	v_pk_fma_f32 v[68:69], v[68:69], s[28:29], v[74:75] op_sel_hi:[1,0,0] neg_lo:[1,0,0] neg_hi:[1,0,0]
	v_pk_fma_f32 v[78:79], v[78:79], s[28:29], v[74:75] op_sel_hi:[1,0,0] neg_lo:[1,0,0] neg_hi:[1,0,0]
	v_pk_fma_f32 v[74:75], v[76:77], s[28:29], v[74:75] op_sel_hi:[1,0,0] neg_lo:[1,0,0] neg_hi:[1,0,0]
	v_pk_mul_f32 v[72:73], v[54:55], v[72:73]
	v_pk_mul_f32 v[68:69], v[56:57], v[68:69]
	v_pk_mul_f32 v[78:79], v[50:51], v[78:79]
	v_pk_mul_f32 v[74:75], v[52:53], v[74:75]
	v_exp_f32_e32 v72, v72
	v_exp_f32_e32 v73, v73
	v_exp_f32_e32 v68, v68
	v_exp_f32_e32 v69, v69
	v_exp_f32_e32 v78, v78
	v_exp_f32_e32 v79, v79
	v_exp_f32_e32 v74, v74
	v_exp_f32_e32 v75, v75
	v_pk_add_f32 v[72:73], v[72:73], 1.0 op_sel_hi:[1,0]
	v_pk_add_f32 v[68:69], v[68:69], 1.0 op_sel_hi:[1,0]
	v_pk_add_f32 v[76:77], v[78:79], 1.0 op_sel_hi:[1,0]
	v_pk_add_f32 v[74:75], v[74:75], 1.0 op_sel_hi:[1,0]
	v_rcp_f32_e32 v72, v72
	v_rcp_f32_e32 v73, v73
	v_rcp_f32_e32 v68, v68
	v_rcp_f32_e32 v69, v69
	v_rcp_f32_e32 v76, v76
	v_rcp_f32_e32 v74, v74
	v_rcp_f32_e32 v75, v75
	v_rcp_f32_e32 v77, v77
	v_pk_mul_f32 v[56:57], v[56:57], v[68:69]
	v_pk_mul_f32 v[54:55], v[54:55], v[72:73]
	v_pk_mul_f32 v[52:53], v[52:53], v[74:75]
	v_pk_mul_f32 v[50:51], v[50:51], v[76:77]
.LBB0_218:
	v_cvt_pk_f16_f32 v72, v54, v55
	v_cvt_pk_f16_f32 v73, v56, v57
	v_cvt_pk_f16_f32 v74, v50, v51
	v_cvt_pk_f16_f32 v75, v52, v53
	s_and_b64 vcc, exec, s[6:7]
	global_store_dwordx4 v[70:71], v[72:75], off offset:256 sc1
	s_cbranch_vccnz .LBB0_222
	v_mul_f32_e32 v63, v63, v63
	v_mul_f32_e32 v53, v53, v53
	v_mul_f32_e32 v51, v51, v51
	v_fmac_f32_e32 v63, v62, v62
	v_mul_f32_e32 v62, v65, v65
	v_fmac_f32_e32 v53, v52, v52
	v_fmac_f32_e32 v51, v50, v50
	v_mul_f32_e32 v50, v55, v55
	v_mul_f32_e32 v52, v57, v57
	v_fmac_f32_e32 v62, v64, v64
	v_mul_f32_e32 v59, v59, v59
	v_fmac_f32_e32 v50, v54, v54
	v_fmac_f32_e32 v52, v56, v56
	v_add_f32_e32 v62, v63, v62
	v_fmac_f32_e32 v59, v58, v58
	v_add_f32_e32 v50, v50, v52
	v_and_b32_e32 v52, 64, v157
	v_add_f32_e32 v58, v59, v62
	v_mul_f32_e32 v59, v61, v61
	v_add_f32_e32 v50, v51, v50
	v_xor_b32_e32 v51, 16, v157
	v_add_u32_e32 v52, 64, v52
	v_fmac_f32_e32 v59, v60, v60
	v_cmp_lt_i32_e32 vcc, v51, v52
	v_add_f32_e32 v58, v59, v58
	v_add_f32_e32 v50, v53, v50
	v_cndmask_b32_e32 v51, v157, v51, vcc
	v_add_f32_e32 v50, v58, v50
	v_lshlrev_b32_e32 v51, 2, v51
	ds_bpermute_b32 v51, v51, v50
	s_waitcnt lgkmcnt(0)
	v_add_f32_e32 v50, v50, v51
	v_xor_b32_e32 v51, 32, v157
	v_cmp_lt_i32_e32 vcc, v51, v52
	s_nop 1
	v_cndmask_b32_e32 v51, v157, v51, vcc
	v_lshlrev_b32_e32 v51, 2, v51
	ds_bpermute_b32 v51, v51, v50
	s_and_saveexec_b64 s[40:41], s[2:3]
	s_cbranch_execz .LBB0_221
	v_ashrrev_i32_e32 v67, 31, v66
	v_lshl_add_u64 v[52:53], v[66:67], 2, s[12:13]
	s_waitcnt lgkmcnt(0)
	v_add_f32_e32 v50, v50, v51
	global_atomic_add_f32 v[52:53], v50, off

; __device__ __forceinline__ unsigned pkh(float lo, float hi) { f32x2 v = {lo, hi}; h16x2 h = __builtin_convertvector(v, h16x2); return __builtin_bit_cast(unsigned, h); }
;     __device__ __forceinline__ void operator()(f32x4 (&acc)[2][2][4][2], const Unit& u, const Order& S, int wr, int wc, int fr_, int fq_, LAS unsigned char*, int) const {
;     ...
;                 const int row = row0 + ai * HALF + m * 16;
;                 const float sc = __builtin_amdgcn_rsqf(ss_in[row] * (1.0f / DM) + EPS);
;                 float sq = 0.f;
; #pragma unroll
;                 for (int bj = 0; bj < 2; ++bj) {
;                     f32x4 v0 = acc[ai][bj][m][0] * sc, v1 = acc[ai][bj][m][1] * sc;
;                     if (act) { const f32x2 a0 = gelu_tanh2((f32x2){v0[0], v0[1]}), a1 = gelu_tanh2((f32x2){v0[2], v0[3]}), a2 = gelu_tanh2((f32x2){v1[0], v1[1]}), a3 = gelu_tanh2((f32x2){v1[2], v1[3]});
;                         v0 = (f32x4){a0.x, a0.y, a1.x, a1.y}; v1 = (f32x4){a2.x, a2.y, a3.x, a3.y}; }
;                     sq += (v0[0] * v0[0] + v0[1] * v0[1]) + (v0[2] * v0[2] + v0[3] * v0[3]) + (v1[0] * v1[0] + v1[1] * v1[1]) + (v1[2] * v1[2] + v1[3] * v1[3]);
;                     u32x4 w; w.x = pkh(v0[0], v0[1]); w.y = pkh(v0[2], v0[3]); w.z = pkh(v1[0], v1[1]); w.w = pkh(v1[2], v1[3]);
;                     *(u32x4*)(P + (size_t)row * NA + col0 + bj * HALF) = w;
;                 }
;                 if (stat && !dry) { sq += __shfl_xor(sq, 16); sq += __shfl_xor(sq, 32); if (fq == 0) atomicAdd(ssv + row, sq); }
.LBB0_224:
	v_add_u32_e32 v50, 0x90, v134
	v_mov_b64_e32 v[54:55], s[58:59]
	v_mad_i64_i32 v[54:55], s[40:41], v50, s61, v[54:55]
	v_cvt_pk_f16_f32 v56, v46, v47
	v_cvt_pk_f16_f32 v57, v48, v49
	v_cvt_pk_f16_f32 v58, v42, v43
	v_cvt_pk_f16_f32 v59, v44, v45
	v_lshl_add_u64 v[54:55], v[122:123], 1, v[54:55]
	v_mov_b32_e32 v53, v52
	global_store_dwordx4 v[54:55], v[56:59], off sc1
	v_pk_mul_f32 v[38:39], v[38:39], v[52:53]
	s_and_b64 vcc, exec, s[4:5]
	v_mov_b32_e32 v56, v52
	v_mov_b32_e32 v57, v52
	v_pk_mul_f32 v[40:41], v[40:41], v[56:57]
	v_pk_mul_f32 v[36:37], v[36:37], v[56:57]
	v_pk_mul_f32 v[34:35], v[34:35], v[52:53]
	s_cbranch_vccnz .LBB0_226
	v_pk_mul_f32 v[52:53], v[40:41], v[40:41]
	v_pk_mul_f32 v[56:57], v[38:39], v[38:39]
	v_mov_b64_e32 v[58:59], s[30:31]
	v_pk_mul_f32 v[60:61], v[36:37], v[36:37]
	v_pk_mul_f32 v[62:63], v[34:35], v[34:35]
	v_pk_fma_f32 v[56:57], v[56:57], s[28:29], v[58:59] op_sel_hi:[1,0,0] neg_lo:[1,0,0] neg_hi:[1,0,0]
	v_pk_fma_f32 v[52:53], v[52:53], s[28:29], v[58:59] op_sel_hi:[1,0,0] neg_lo:[1,0,0] neg_hi:[1,0,0]
	v_pk_fma_f32 v[62:63], v[62:63], s[28:29], v[58:59] op_sel_hi:[1,0,0] neg_lo:[1,0,0] neg_hi:[1,0,0]
	v_pk_fma_f32 v[58:59], v[60:61], s[28:29], v[58:59] op_sel_hi:[1,0,0] neg_lo:[1,0,0] neg_hi:[1,0,0]
	v_pk_mul_f32 v[56:57], v[38:39], v[56:57]
	v_pk_mul_f32 v[52:53], v[40:41], v[52:53]
	v_pk_mul_f32 v[62:63], v[34:35], v[62:63]
	v_pk_mul_f32 v[58:59], v[36:37], v[58:59]
	v_exp_f32_e32 v56, v56
	v_exp_f32_e32 v57, v57
	v_exp_f32_e32 v52, v52
	v_exp_f32_e32 v53, v53
	v_exp_f32_e32 v62, v62
	v_exp_f32_e32 v63, v63
	v_exp_f32_e32 v58, v58
	v_exp_f32_e32 v59, v59
	v_pk_add_f32 v[56:57], v[56:57], 1.0 op_sel_hi:[1,0]
	v_pk_add_f32 v[52:53], v[52:53], 1.0 op_sel_hi:[1,0]
	v_pk_add_f32 v[60:61], v[62:63], 1.0 op_sel_hi:[1,0]
	v_pk_add_f32 v[58:59], v[58:59], 1.0 op_sel_hi:[1,0]
	v_rcp_f32_e32 v56, v56
	v_rcp_f32_e32 v57, v57
	v_rcp_f32_e32 v52, v52
	v_rcp_f32_e32 v53, v53
	v_rcp_f32_e32 v60, v60
	v_rcp_f32_e32 v58, v58
	v_rcp_f32_e32 v59, v59
	v_rcp_f32_e32 v61, v61
	v_pk_mul_f32 v[40:41], v[40:41], v[52:53]
	v_pk_mul_f32 v[38:39], v[38:39], v[56:57]
	v_pk_mul_f32 v[36:37], v[36:37], v[58:59]
	v_pk_mul_f32 v[34:35], v[34:35], v[60:61]
.LBB0_226:
	v_cvt_pk_f16_f32 v56, v38, v39
	v_cvt_pk_f16_f32 v57, v40, v41
	v_cvt_pk_f16_f32 v58, v34, v35
	v_cvt_pk_f16_f32 v59, v36, v37
	s_and_b64 vcc, exec, s[6:7]
	global_store_dwordx4 v[54:55], v[56:59], off offset:256 sc1
	s_cbranch_vccnz .LBB0_230
	v_mul_f32_e32 v47, v47, v47
	v_mul_f32_e32 v37, v37, v37
	v_mul_f32_e32 v35, v35, v35
	v_fmac_f32_e32 v47, v46, v46
	v_mul_f32_e32 v46, v49, v49
	v_fmac_f32_e32 v37, v36, v36
	v_fmac_f32_e32 v35, v34, v34
	v_mul_f32_e32 v34, v39, v39
	v_mul_f32_e32 v36, v41, v41
	v_fmac_f32_e32 v46, v48, v48
	v_mul_f32_e32 v43, v43, v43
	v_fmac_f32_e32 v34, v38, v38
	v_fmac_f32_e32 v36, v40, v40
	v_add_f32_e32 v46, v47, v46
	v_fmac_f32_e32 v43, v42, v42
	v_add_f32_e32 v34, v34, v36
	v_and_b32_e32 v36, 64, v157
	v_add_f32_e32 v42, v43, v46
	v_mul_f32_e32 v43, v45, v45
	v_add_f32_e32 v34, v35, v34
	v_xor_b32_e32 v35, 16, v157
	v_add_u32_e32 v36, 64, v36
	v_fmac_f32_e32 v43, v44, v44
	v_cmp_lt_i32_e32 vcc, v35, v36
	v_add_f32_e32 v42, v43, v42
	v_add_f32_e32 v34, v37, v34
	v_cndmask_b32_e32 v35, v157, v35, vcc
	v_add_f32_e32 v34, v42, v34
	v_lshlrev_b32_e32 v35, 2, v35
	ds_bpermute_b32 v35, v35, v34
	s_waitcnt lgkmcnt(0)
	v_add_f32_e32 v34, v34, v35
	v_xor_b32_e32 v35, 32, v157
	v_cmp_lt_i32_e32 vcc, v35, v36
	s_nop 1
	v_cndmask_b32_e32 v35, v157, v35, vcc
	v_lshlrev_b32_e32 v35, 2, v35
	ds_bpermute_b32 v35, v35, v34
	s_and_saveexec_b64 s[40:41], s[2:3]
	s_cbranch_execz .LBB0_229
	v_ashrrev_i32_e32 v51, 31, v50
	v_lshl_add_u64 v[36:37], v[50:51], 2, s[12:13]
	s_waitcnt lgkmcnt(0)
	v_add_f32_e32 v34, v34, v35
	global_atomic_add_f32 v[36:37], v34, off

; __device__ __forceinline__ unsigned pkh(float lo, float hi) { f32x2 v = {lo, hi}; h16x2 h = __builtin_convertvector(v, h16x2); return __builtin_bit_cast(unsigned, h); }
;     __device__ __forceinline__ void operator()(f32x4 (&acc)[2][2][4][2], const Unit& u, const Order& S, int wr, int wc, int fr_, int fq_, LAS unsigned char*, int) const {
;     ...
;                 const int row = row0 + ai * HALF + m * 16;
;                 const float sc = __builtin_amdgcn_rsqf(ss_in[row] * (1.0f / DM) + EPS);
;                 float sq = 0.f;
; #pragma unroll
;                 for (int bj = 0; bj < 2; ++bj) {
;                     f32x4 v0 = acc[ai][bj][m][0] * sc, v1 = acc[ai][bj][m][1] * sc;
;                     if (act) { const f32x2 a0 = gelu_tanh2((f32x2){v0[0], v0[1]}), a1 = gelu_tanh2((f32x2){v0[2], v0[3]}), a2 = gelu_tanh2((f32x2){v1[0], v1[1]}), a3 = gelu_tanh2((f32x2){v1[2], v1[3]});
;                         v0 = (f32x4){a0.x, a0.y, a1.x, a1.y}; v1 = (f32x4){a2.x, a2.y, a3.x, a3.y}; }
;                     sq += (v0[0] * v0[0] + v0[1] * v0[1]) + (v0[2] * v0[2] + v0[3] * v0[3]) + (v1[0] * v1[0] + v1[1] * v1[1]) + (v1[2] * v1[2] + v1[3] * v1[3]);
;                     u32x4 w; w.x = pkh(v0[0], v0[1]); w.y = pkh(v0[2], v0[3]); w.z = pkh(v1[0], v1[1]); w.w = pkh(v1[2], v1[3]);
;                     *(u32x4*)(P + (size_t)row * NA + col0 + bj * HALF) = w;
;                 }
;                 if (stat && !dry) { sq += __shfl_xor(sq, 16); sq += __shfl_xor(sq, 32); if (fq == 0) atomicAdd(ssv + row, sq); }
.LBB0_232:
	v_add_u32_e32 v34, 0xa0, v134
	v_mov_b64_e32 v[38:39], s[58:59]
	v_mad_i64_i32 v[38:39], s[40:41], v34, s61, v[38:39]
	v_cvt_pk_f16_f32 v40, v30, v31
	v_cvt_pk_f16_f32 v41, v32, v33
	v_cvt_pk_f16_f32 v42, v26, v27
	v_cvt_pk_f16_f32 v43, v28, v29
	v_lshl_add_u64 v[38:39], v[122:123], 1, v[38:39]
	v_mov_b32_e32 v37, v36
	global_store_dwordx4 v[38:39], v[40:43], off sc1
	v_pk_mul_f32 v[22:23], v[22:23], v[36:37]
	s_and_b64 vcc, exec, s[4:5]
	v_mov_b32_e32 v40, v36
	v_mov_b32_e32 v41, v36
	v_pk_mul_f32 v[24:25], v[24:25], v[40:41]
	v_pk_mul_f32 v[20:21], v[20:21], v[40:41]
	v_pk_mul_f32 v[18:19], v[18:19], v[36:37]
	s_cbranch_vccnz .LBB0_234
	v_pk_mul_f32 v[36:37], v[24:25], v[24:25]
	v_pk_mul_f32 v[40:41], v[22:23], v[22:23]
	v_mov_b64_e32 v[42:43], s[30:31]
	v_pk_mul_f32 v[44:45], v[20:21], v[20:21]
	v_pk_mul_f32 v[46:47], v[18:19], v[18:19]
	v_pk_fma_f32 v[40:41], v[40:41], s[28:29], v[42:43] op_sel_hi:[1,0,0] neg_lo:[1,0,0] neg_hi:[1,0,0]
	v_pk_fma_f32 v[36:37], v[36:37], s[28:29], v[42:43] op_sel_hi:[1,0,0] neg_lo:[1,0,0] neg_hi:[1,0,0]
	v_pk_fma_f32 v[46:47], v[46:47], s[28:29], v[42:43] op_sel_hi:[1,0,0] neg_lo:[1,0,0] neg_hi:[1,0,0]
	v_pk_fma_f32 v[42:43], v[44:45], s[28:29], v[42:43] op_sel_hi:[1,0,0] neg_lo:[1,0,0] neg_hi:[1,0,0]
	v_pk_mul_f32 v[40:41], v[22:23], v[40:41]
	v_pk_mul_f32 v[36:37], v[24:25], v[36:37]
	v_pk_mul_f32 v[46:47], v[18:19], v[46:47]
	v_pk_mul_f32 v[42:43], v[20:21], v[42:43]
	v_exp_f32_e32 v40, v40
	v_exp_f32_e32 v41, v41
	v_exp_f32_e32 v36, v36
	v_exp_f32_e32 v37, v37
	v_exp_f32_e32 v46, v46
	v_exp_f32_e32 v47, v47
	v_exp_f32_e32 v42, v42
	v_exp_f32_e32 v43, v43
	v_pk_add_f32 v[40:41], v[40:41], 1.0 op_sel_hi:[1,0]
	v_pk_add_f32 v[36:37], v[36:37], 1.0 op_sel_hi:[1,0]
	v_pk_add_f32 v[44:45], v[46:47], 1.0 op_sel_hi:[1,0]
	v_pk_add_f32 v[42:43], v[42:43], 1.0 op_sel_hi:[1,0]
	v_rcp_f32_e32 v40, v40
	v_rcp_f32_e32 v41, v41
	v_rcp_f32_e32 v36, v36
	v_rcp_f32_e32 v37, v37
	v_rcp_f32_e32 v44, v44
	v_rcp_f32_e32 v42, v42
	v_rcp_f32_e32 v43, v43
	v_rcp_f32_e32 v45, v45
	v_pk_mul_f32 v[24:25], v[24:25], v[36:37]
	v_pk_mul_f32 v[22:23], v[22:23], v[40:41]
	v_pk_mul_f32 v[20:21], v[20:21], v[42:43]
	v_pk_mul_f32 v[18:19], v[18:19], v[44:45]
.LBB0_234:
	v_cvt_pk_f16_f32 v40, v22, v23
	v_cvt_pk_f16_f32 v41, v24, v25
	v_cvt_pk_f16_f32 v42, v18, v19
	v_cvt_pk_f16_f32 v43, v20, v21
	s_and_b64 vcc, exec, s[6:7]
	global_store_dwordx4 v[38:39], v[40:43], off offset:256 sc1
	s_cbranch_vccnz .LBB0_238
	v_mul_f32_e32 v31, v31, v31
	v_mul_f32_e32 v21, v21, v21
	v_mul_f32_e32 v19, v19, v19
	v_fmac_f32_e32 v31, v30, v30
	v_mul_f32_e32 v30, v33, v33
	v_fmac_f32_e32 v21, v20, v20
	v_fmac_f32_e32 v19, v18, v18
	v_mul_f32_e32 v18, v23, v23
	v_mul_f32_e32 v20, v25, v25
	v_fmac_f32_e32 v30, v32, v32
	v_mul_f32_e32 v27, v27, v27
	v_fmac_f32_e32 v18, v22, v22
	v_fmac_f32_e32 v20, v24, v24
	v_add_f32_e32 v30, v31, v30
	v_fmac_f32_e32 v27, v26, v26
	v_add_f32_e32 v18, v18, v20
	v_and_b32_e32 v20, 64, v157
	v_add_f32_e32 v26, v27, v30
	v_mul_f32_e32 v27, v29, v29
	v_add_f32_e32 v18, v19, v18
	v_xor_b32_e32 v19, 16, v157
	v_add_u32_e32 v20, 64, v20
	v_fmac_f32_e32 v27, v28, v28
	v_cmp_lt_i32_e32 vcc, v19, v20
	v_add_f32_e32 v26, v27, v26
	v_add_f32_e32 v18, v21, v18
	v_cndmask_b32_e32 v19, v157, v19, vcc
	v_add_f32_e32 v18, v26, v18
	v_lshlrev_b32_e32 v19, 2, v19
	ds_bpermute_b32 v19, v19, v18
	s_waitcnt lgkmcnt(0)
	v_add_f32_e32 v18, v18, v19
	v_xor_b32_e32 v19, 32, v157
	v_cmp_lt_i32_e32 vcc, v19, v20
	s_nop 1
	v_cndmask_b32_e32 v19, v157, v19, vcc
	v_lshlrev_b32_e32 v19, 2, v19
	ds_bpermute_b32 v19, v19, v18
	s_and_saveexec_b64 s[40:41], s[2:3]
	s_cbranch_execz .LBB0_237
	v_ashrrev_i32_e32 v35, 31, v34
	v_lshl_add_u64 v[20:21], v[34:35], 2, s[12:13]
	s_waitcnt lgkmcnt(0)
	v_add_f32_e32 v18, v18, v19
	global_atomic_add_f32 v[20:21], v18, off

; __device__ __forceinline__ unsigned pkh(float lo, float hi) { f32x2 v = {lo, hi}; h16x2 h = __builtin_convertvector(v, h16x2); return __builtin_bit_cast(unsigned, h); }
;     __device__ __forceinline__ void operator()(f32x4 (&acc)[2][2][4][2], const Unit& u, const Order& S, int wr, int wc, int fr_, int fq_, LAS unsigned char*, int) const {
;     ...
;                 const int row = row0 + ai * HALF + m * 16;
;                 const float sc = __builtin_amdgcn_rsqf(ss_in[row] * (1.0f / DM) + EPS);
;                 float sq = 0.f;
; #pragma unroll
;                 for (int bj = 0; bj < 2; ++bj) {
;                     f32x4 v0 = acc[ai][bj][m][0] * sc, v1 = acc[ai][bj][m][1] * sc;
;                     if (act) { const f32x2 a0 = gelu_tanh2((f32x2){v0[0], v0[1]}), a1 = gelu_tanh2((f32x2){v0[2], v0[3]}), a2 = gelu_tanh2((f32x2){v1[0], v1[1]}), a3 = gelu_tanh2((f32x2){v1[2], v1[3]});
;                         v0 = (f32x4){a0.x, a0.y, a1.x, a1.y}; v1 = (f32x4){a2.x, a2.y, a3.x, a3.y}; }
;                     sq += (v0[0] * v0[0] + v0[1] * v0[1]) + (v0[2] * v0[2] + v0[3] * v0[3]) + (v1[0] * v1[0] + v1[1] * v1[1]) + (v1[2] * v1[2] + v1[3] * v1[3]);
;                     u32x4 w; w.x = pkh(v0[0], v0[1]); w.y = pkh(v0[2], v0[3]); w.z = pkh(v1[0], v1[1]); w.w = pkh(v1[2], v1[3]);
;                     *(u32x4*)(P + (size_t)row * NA + col0 + bj * HALF) = w;
;                 }
;                 if (stat && !dry) { sq += __shfl_xor(sq, 16); sq += __shfl_xor(sq, 32); if (fq == 0) atomicAdd(ssv + row, sq); }
.LBB0_240:
	v_add_u32_e32 v18, 0xb0, v134
	v_mov_b64_e32 v[22:23], s[58:59]
	v_mad_i64_i32 v[22:23], s[40:41], v18, s61, v[22:23]
	v_cvt_pk_f16_f32 v24, v14, v15
	v_cvt_pk_f16_f32 v25, v16, v17
	v_cvt_pk_f16_f32 v26, v10, v11
	v_cvt_pk_f16_f32 v27, v12, v13
	v_lshl_add_u64 v[22:23], v[122:123], 1, v[22:23]
	v_mov_b32_e32 v21, v20
	global_store_dwordx4 v[22:23], v[24:27], off sc1
	v_pk_mul_f32 v[6:7], v[6:7], v[20:21]
	s_and_b64 vcc, exec, s[4:5]
	v_mov_b32_e32 v24, v20
	v_mov_b32_e32 v25, v20
	v_pk_mul_f32 v[8:9], v[8:9], v[24:25]
	v_pk_mul_f32 v[4:5], v[4:5], v[24:25]
	v_pk_mul_f32 v[2:3], v[2:3], v[20:21]
	s_cbranch_vccnz .LBB0_242
	v_pk_mul_f32 v[20:21], v[8:9], v[8:9]
	v_pk_mul_f32 v[24:25], v[6:7], v[6:7]
	v_mov_b64_e32 v[26:27], s[30:31]
	v_pk_mul_f32 v[28:29], v[4:5], v[4:5]
	v_pk_mul_f32 v[30:31], v[2:3], v[2:3]
	v_pk_fma_f32 v[24:25], v[24:25], s[28:29], v[26:27] op_sel_hi:[1,0,0] neg_lo:[1,0,0] neg_hi:[1,0,0]
	v_pk_fma_f32 v[20:21], v[20:21], s[28:29], v[26:27] op_sel_hi:[1,0,0] neg_lo:[1,0,0] neg_hi:[1,0,0]
	v_pk_fma_f32 v[30:31], v[30:31], s[28:29], v[26:27] op_sel_hi:[1,0,0] neg_lo:[1,0,0] neg_hi:[1,0,0]
	v_pk_fma_f32 v[26:27], v[28:29], s[28:29], v[26:27] op_sel_hi:[1,0,0] neg_lo:[1,0,0] neg_hi:[1,0,0]
	v_pk_mul_f32 v[24:25], v[6:7], v[24:25]
	v_pk_mul_f32 v[20:21], v[8:9], v[20:21]
	v_pk_mul_f32 v[30:31], v[2:3], v[30:31]
	v_pk_mul_f32 v[26:27], v[4:5], v[26:27]
	v_exp_f32_e32 v24, v24
	v_exp_f32_e32 v25, v25
	v_exp_f32_e32 v20, v20
	v_exp_f32_e32 v21, v21
	v_exp_f32_e32 v30, v30
	v_exp_f32_e32 v31, v31
	v_exp_f32_e32 v26, v26
	v_exp_f32_e32 v27, v27
	v_pk_add_f32 v[24:25], v[24:25], 1.0 op_sel_hi:[1,0]
	v_pk_add_f32 v[20:21], v[20:21], 1.0 op_sel_hi:[1,0]
	v_pk_add_f32 v[28:29], v[30:31], 1.0 op_sel_hi:[1,0]
	v_pk_add_f32 v[26:27], v[26:27], 1.0 op_sel_hi:[1,0]
	v_rcp_f32_e32 v24, v24
	v_rcp_f32_e32 v25, v25
	v_rcp_f32_e32 v20, v20
	v_rcp_f32_e32 v21, v21
	v_rcp_f32_e32 v28, v28
	v_rcp_f32_e32 v26, v26
	v_rcp_f32_e32 v27, v27
	v_rcp_f32_e32 v29, v29
	v_pk_mul_f32 v[8:9], v[8:9], v[20:21]
	v_pk_mul_f32 v[6:7], v[6:7], v[24:25]
	v_pk_mul_f32 v[4:5], v[4:5], v[26:27]
	v_pk_mul_f32 v[2:3], v[2:3], v[28:29]
.LBB0_242:
	v_cvt_pk_f16_f32 v24, v6, v7
	v_cvt_pk_f16_f32 v25, v8, v9
	v_cvt_pk_f16_f32 v26, v2, v3
	v_cvt_pk_f16_f32 v27, v4, v5
	s_and_b64 vcc, exec, s[6:7]
	global_store_dwordx4 v[22:23], v[24:27], off offset:256 sc1
	s_cbranch_vccnz .LBB0_246
	v_mul_f32_e32 v15, v15, v15
	v_mul_f32_e32 v5, v5, v5
	v_mul_f32_e32 v3, v3, v3
	v_fmac_f32_e32 v15, v14, v14
	v_mul_f32_e32 v14, v17, v17
	v_fmac_f32_e32 v5, v4, v4
	v_fmac_f32_e32 v3, v2, v2
	v_mul_f32_e32 v2, v7, v7
	v_mul_f32_e32 v4, v9, v9
	v_fmac_f32_e32 v14, v16, v16
	v_mul_f32_e32 v11, v11, v11
	v_fmac_f32_e32 v2, v6, v6
	v_fmac_f32_e32 v4, v8, v8
	v_add_f32_e32 v14, v15, v14
	v_fmac_f32_e32 v11, v10, v10
	v_add_f32_e32 v2, v2, v4
	v_and_b32_e32 v4, 64, v157
	v_add_f32_e32 v10, v11, v14
	v_mul_f32_e32 v11, v13, v13
	v_add_f32_e32 v2, v3, v2
	v_xor_b32_e32 v3, 16, v157
	v_add_u32_e32 v4, 64, v4
	v_fmac_f32_e32 v11, v12, v12
	v_cmp_lt_i32_e32 vcc, v3, v4
	v_add_f32_e32 v10, v11, v10
	v_add_f32_e32 v2, v5, v2
	v_cndmask_b32_e32 v3, v157, v3, vcc
	v_add_f32_e32 v2, v10, v2
	v_lshlrev_b32_e32 v3, 2, v3
	ds_bpermute_b32 v3, v3, v2
	s_waitcnt lgkmcnt(0)
	v_add_f32_e32 v2, v2, v3
	v_xor_b32_e32 v3, 32, v157
	v_cmp_lt_i32_e32 vcc, v3, v4
	s_nop 1
	v_cndmask_b32_e32 v3, v157, v3, vcc
	v_lshlrev_b32_e32 v3, 2, v3
	ds_bpermute_b32 v3, v3, v2
	s_and_saveexec_b64 s[4:5], s[2:3]
	s_cbranch_execz .LBB0_245
	v_ashrrev_i32_e32 v19, 31, v18
	v_lshl_add_u64 v[4:5], v[18:19], 2, s[12:13]
	s_waitcnt lgkmcnt(0)
	v_add_f32_e32 v2, v2, v3
	global_atomic_add_f32 v[4:5], v2, off

; __device__ __forceinline__ unsigned pkh(float lo, float hi) { f32x2 v = {lo, hi}; h16x2 h = __builtin_convertvector(v, h16x2); return __builtin_bit_cast(unsigned, h); }
; __device__ __forceinline__ unsigned pk8(float a, float b, float c, float d) { int w = __builtin_amdgcn_cvt_pk_fp8_f32(a, b, 0, false); w = __builtin_amdgcn_cvt_pk_fp8_f32(c, d, w, true); return (unsigned)w; }
;     __device__ __forceinline__ void operator()(f32x4 (&acc)[2][2][4][2], const Unit& u, const Order& S, int wr, int wc, int fr_, int fq_, LAS unsigned char*, int) const {
;     ...
;                 const int row = row0 + ai * HALF + m * 16; const size_t off = (size_t)row * DM + col0;
;                 float sq = 0.f;
; #pragma unroll
;                 for (int bj = 0; bj < 2; ++bj) {
;                     const h16x8 bs = *(const h16x8*)(h16 + off + bj * HALF);
;                     f32x4 o0 = acc[ai][bj][m][0] * pre, o1 = acc[ai][bj][m][1] * pre;
; #pragma unroll
;                     for (int e = 0; e < 4; ++e) { o0[e] += (float)bs[e]; o1[e] += (float)bs[4 + e]; }
;                     if (out32) { if (!dry) { __builtin_nontemporal_store(o0, (f32x4*)(out32 + off + bj * HALF)); __builtin_nontemporal_store(o1, (f32x4*)(out32 + off + bj * HALF + 4)); } }
;                     else if (!dry) {
;                         sq += (o0[0] * o0[0] + o0[1] * o0[1]) + (o0[2] * o0[2] + o0[3] * o0[3]) + (o1[0] * o1[0] + o1[1] * o1[1]) + (o1[2] * o1[2] + o1[3] * o1[3]);
;                         u32x4 w; w.x = pkh(o0[0], o0[1]); w.y = pkh(o0[2], o0[3]); w.z = pkh(o1[0], o1[1]); w.w = pkh(o1[2], o1[3]);
;                         *(u32x4*)(h16 + off + bj * HALF) = w;
;                         if (h8) { u32x2 q; q.x = pk8(o0[0] * F8_SA, o0[1] * F8_SA, o0[2] * F8_SA, o0[3] * F8_SA); q.y = pk8(o1[0] * F8_SA, o1[1] * F8_SA, o1[2] * F8_SA, o1[3] * F8_SA); *(u32x2*)(h8 + off + bj * HALF) = q; } }
;                 }
;                 if (!out32 && !dry) { sq += __shfl_xor(sq, 16); sq += __shfl_xor(sq, 32); if (fq == 0) atomicAdd(ss_out + row, sq); }
.LBB0_403:
	s_lshl_b32 s3, s45, 8
	v_mov_b32_e32 v146, v150
	v_mov_b32_e32 v168, v1
	s_add_i32 s3, s3, s38
	s_lshl_b32 s2, s2, 8
	v_add_u32_e32 v148, s3, v146
	s_or_b32 s2, s2, s39
	v_ashrrev_i32_e32 v149, 31, v148
	v_lshl_add_u32 v146, v168, 3, s2
	v_lshlrev_b64 v[156:157], 11, v[148:149]
	v_ashrrev_i32_e32 v147, 31, v146
	v_lshl_add_u64 v[156:157], s[90:91], 0, v[156:157]
	v_lshl_add_u64 v[166:167], v[146:147], 1, v[156:157]
	global_load_dwordx4 v[158:161], v[166:167], off
	global_load_dwordx4 v[162:165], v[166:167], off offset:256
	v_and_b32_e32 v157, 64, v155
	v_xor_b32_e32 v156, 16, v155
	v_add_u32_e32 v157, 64, v157
	v_xor_b32_e32 v169, 32, v155
	v_cmp_lt_i32_e64 s[2:3], v156, v157
	v_cmp_eq_u32_e32 vcc, 0, v168
	s_waitcnt vmcnt(0)
	v_cvt_f32_f16_e32 v168, v158
	v_cndmask_b32_e64 v156, v155, v156, s[2:3]
	v_cmp_lt_i32_e64 s[2:3], v169, v157
	v_cvt_f32_f16_e32 v172, v162
	v_cvt_f32_f16_sdwa v173, v162 dst_sel:DWORD dst_unused:UNUSED_PAD src0_sel:WORD_1
	v_cndmask_b32_e64 v157, v155, v169, s[2:3]
	v_cvt_f32_f16_sdwa v169, v158 dst_sel:DWORD dst_unused:UNUSED_PAD src0_sel:WORD_1
	v_cvt_f32_f16_e32 v158, v159
	v_cvt_f32_f16_sdwa v159, v159 dst_sel:DWORD dst_unused:UNUSED_PAD src0_sel:WORD_1
	v_cvt_f32_f16_e32 v162, v163
	v_cvt_f32_f16_sdwa v163, v163 dst_sel:DWORD dst_unused:UNUSED_PAD src0_sel:WORD_1
	v_cvt_f32_f16_e32 v170, v160
	v_cvt_f32_f16_sdwa v171, v160 dst_sel:DWORD dst_unused:UNUSED_PAD src0_sel:WORD_1
	v_cvt_f32_f16_e32 v160, v161
	v_cvt_f32_f16_sdwa v161, v161 dst_sel:DWORD dst_unused:UNUSED_PAD src0_sel:WORD_1
	v_cvt_f32_f16_e32 v174, v164
	v_cvt_f32_f16_sdwa v175, v164 dst_sel:DWORD dst_unused:UNUSED_PAD src0_sel:WORD_1
	v_cvt_f32_f16_e32 v164, v165
	v_cvt_f32_f16_sdwa v165, v165 dst_sel:DWORD dst_unused:UNUSED_PAD src0_sel:WORD_1
	v_pk_add_f32 v[126:127], v[126:127], v[168:169]
	v_pk_add_f32 v[128:129], v[128:129], v[158:159]
	v_pk_add_f32 v[118:119], v[118:119], v[172:173]
	v_pk_add_f32 v[120:121], v[120:121], v[162:163]
	v_pk_add_f32 v[122:123], v[122:123], v[170:171]
	v_pk_add_f32 v[124:125], v[124:125], v[160:161]
	v_pk_add_f32 v[158:159], v[114:115], v[174:175]
	v_pk_add_f32 v[160:161], v[116:117], v[164:165]
	v_pk_mul_f32 v[116:117], v[126:127], v[126:127]
	v_pk_mul_f32 v[162:163], v[128:129], v[128:129]
	v_cvt_pk_f16_f32 v114, v126, v127
	v_cvt_pk_f16_f32 v115, v128, v129
	v_pk_mul_f32 v[126:127], v[118:119], v[118:119]
	v_pk_mul_f32 v[128:129], v[120:121], v[120:121]
	v_pk_mul_f32 v[164:165], v[122:123], v[122:123]
	v_pk_mul_f32 v[170:171], v[158:159], v[158:159]
	v_add_f32_e32 v128, v128, v129
	v_add_f32_e32 v126, v126, v127
	v_add_f32_e32 v162, v162, v163
	v_add_f32_e32 v116, v116, v117
	v_pk_mul_f32 v[168:169], v[124:125], v[124:125]
	v_pk_mul_f32 v[172:173], v[160:161], v[160:161]
	v_add_f32_e32 v127, v170, v171
	v_add_f32_e32 v117, v164, v165
	v_add_f32_e32 v126, v126, v128
	v_add_f32_e32 v116, v116, v162
	v_add_f32_e32 v129, v172, v173
	v_add_f32_e32 v163, v168, v169
	v_add_f32_e32 v126, v127, v126
	v_add_f32_e32 v116, v117, v116
	v_add_f32_e32 v117, v129, v126
	v_add_f32_e32 v116, v163, v116
	v_lshlrev_b32_e32 v156, 2, v156
	v_add_f32_e32 v126, v116, v117
	ds_bpermute_b32 v127, v156, v126
	v_cvt_pk_f16_f32 v116, v122, v123
	v_cvt_pk_f16_f32 v117, v124, v125
	global_store_dwordx4 v[166:167], v[114:117], off sc1
	v_cvt_pk_f16_f32 v118, v118, v119
	v_cvt_pk_f16_f32 v119, v120, v121
	s_waitcnt lgkmcnt(0)
	v_add_f32_e32 v114, v126, v127
	v_lshlrev_b32_e32 v116, 2, v157
	ds_bpermute_b32 v115, v116, v114
	v_cvt_pk_f16_f32 v120, v158, v159
	v_cvt_pk_f16_f32 v121, v160, v161
	global_store_dwordx4 v[166:167], v[118:121], off offset:256 sc1
	s_and_saveexec_b64 s[2:3], vcc
	s_cbranch_execz .LBB0_405
	v_lshl_add_u64 v[118:119], v[148:149], 2, s[18:19]
	s_waitcnt lgkmcnt(0)
	v_add_f32_e32 v114, v114, v115
	global_atomic_add_f32 v[118:119], v114, off
.LBB0_405:
	s_or_b64 exec, exec, s[2:3]
	v_add_u32_e32 v114, 16, v148
	s_waitcnt lgkmcnt(0)
	v_ashrrev_i32_e32 v115, 31, v114
	v_lshlrev_b64 v[118:119], 11, v[114:115]
	v_lshl_add_u64 v[118:119], s[90:91], 0, v[118:119]
	v_lshl_add_u64 v[126:127], v[146:147], 1, v[118:119]
	global_load_dwordx4 v[118:121], v[126:127], off
	global_load_dwordx4 v[122:125], v[126:127], off offset:256
	s_waitcnt vmcnt(1)
	v_cvt_f32_f16_e32 v128, v118
	v_cvt_f32_f16_sdwa v129, v118 dst_sel:DWORD dst_unused:UNUSED_PAD src0_sel:WORD_1
	v_cvt_f32_f16_e32 v118, v119
	v_cvt_f32_f16_sdwa v119, v119 dst_sel:DWORD dst_unused:UNUSED_PAD src0_sel:WORD_1
	s_waitcnt vmcnt(0)
	v_cvt_f32_f16_e32 v160, v122
	v_cvt_f32_f16_sdwa v161, v122 dst_sel:DWORD dst_unused:UNUSED_PAD src0_sel:WORD_1
	v_cvt_f32_f16_e32 v122, v123
	v_cvt_f32_f16_sdwa v123, v123 dst_sel:DWORD dst_unused:UNUSED_PAD src0_sel:WORD_1
	v_cvt_f32_f16_e32 v158, v120
	v_cvt_f32_f16_sdwa v159, v120 dst_sel:DWORD dst_unused:UNUSED_PAD src0_sel:WORD_1
	v_cvt_f32_f16_e32 v120, v121
	v_cvt_f32_f16_sdwa v121, v121 dst_sel:DWORD dst_unused:UNUSED_PAD src0_sel:WORD_1
	v_cvt_f32_f16_e32 v162, v124
	v_cvt_f32_f16_sdwa v163, v124 dst_sel:DWORD dst_unused:UNUSED_PAD src0_sel:WORD_1
	v_cvt_f32_f16_e32 v124, v125
	v_cvt_f32_f16_sdwa v125, v125 dst_sel:DWORD dst_unused:UNUSED_PAD src0_sel:WORD_1
	v_pk_add_f32 v[110:111], v[110:111], v[128:129]
	v_pk_add_f32 v[112:113], v[112:113], v[118:119]
	v_pk_add_f32 v[102:103], v[102:103], v[160:161]
	v_pk_add_f32 v[104:105], v[104:105], v[122:123]
	v_pk_add_f32 v[106:107], v[106:107], v[158:159]
	v_pk_add_f32 v[108:109], v[108:109], v[120:121]
	v_pk_add_f32 v[118:119], v[98:99], v[162:163]
	v_pk_add_f32 v[120:121], v[100:101], v[124:125]
	v_pk_mul_f32 v[100:101], v[110:111], v[110:111]
	v_pk_mul_f32 v[122:123], v[112:113], v[112:113]
	v_cvt_pk_f16_f32 v98, v110, v111
	v_cvt_pk_f16_f32 v99, v112, v113
	v_pk_mul_f32 v[110:111], v[102:103], v[102:103]
	v_pk_mul_f32 v[112:113], v[104:105], v[104:105]
	v_pk_mul_f32 v[124:125], v[106:107], v[106:107]
	v_pk_mul_f32 v[158:159], v[118:119], v[118:119]
	v_add_f32_e32 v112, v112, v113
	v_add_f32_e32 v110, v110, v111
	v_add_f32_e32 v117, v122, v123
	v_add_f32_e32 v100, v100, v101
	v_pk_mul_f32 v[128:129], v[108:109], v[108:109]
	v_pk_mul_f32 v[160:161], v[120:121], v[120:121]
	v_add_f32_e32 v111, v158, v159
	v_add_f32_e32 v101, v124, v125
	v_add_f32_e32 v110, v110, v112
	v_add_f32_e32 v100, v100, v117
	v_add_f32_e32 v113, v160, v161
	v_add_f32_e32 v122, v128, v129
	v_add_f32_e32 v110, v111, v110
	v_add_f32_e32 v100, v101, v100
	v_add_f32_e32 v101, v113, v110
	v_add_f32_e32 v100, v122, v100
	v_add_f32_e32 v110, v100, v101
	ds_bpermute_b32 v111, v156, v110
	v_cvt_pk_f16_f32 v100, v106, v107
	v_cvt_pk_f16_f32 v101, v108, v109
	global_store_dwordx4 v[126:127], v[98:101], off sc1
	s_waitcnt lgkmcnt(0)
	s_nop 0
	v_add_f32_e32 v98, v110, v111
	ds_bpermute_b32 v99, v116, v98
	v_cvt_pk_f16_f32 v100, v102, v103
	v_cvt_pk_f16_f32 v101, v104, v105
	v_cvt_pk_f16_f32 v102, v118, v119
	v_cvt_pk_f16_f32 v103, v120, v121
	global_store_dwordx4 v[126:127], v[100:103], off offset:256 sc1
	s_and_saveexec_b64 s[2:3], vcc
	s_cbranch_execz .LBB0_407
; __device__ __forceinline__ unsigned pkh(float lo, float hi) { f32x2 v = {lo, hi}; h16x2 h = __builtin_convertvector(v, h16x2); return __builtin_bit_cast(unsigned, h); }
; __device__ __forceinline__ unsigned pk8(float a, float b, float c, float d) { int w = __builtin_amdgcn_cvt_pk_fp8_f32(a, b, 0, false); w = __builtin_amdgcn_cvt_pk_fp8_f32(c, d, w, true); return (unsigned)w; }
;     __device__ __forceinline__ void operator()(f32x4 (&acc)[2][2][4][2], const Unit& u, const Order& S, int wr, int wc, int fr_, int fq_, LAS unsigned char*, int) const {
;     ...
;                 const int row = row0 + ai * HALF + m * 16; const size_t off = (size_t)row * DM + col0;
;                 float sq = 0.f;
; #pragma unroll
;                 for (int bj = 0; bj < 2; ++bj) {
;                     const h16x8 bs = *(const h16x8*)(h16 + off + bj * HALF);
;                     f32x4 o0 = acc[ai][bj][m][0] * pre, o1 = acc[ai][bj][m][1] * pre;
; #pragma unroll
;                     for (int e = 0; e < 4; ++e) { o0[e] += (float)bs[e]; o1[e] += (float)bs[4 + e]; }
;                     if (out32) { if (!dry) { __builtin_nontemporal_store(o0, (f32x4*)(out32 + off + bj * HALF)); __builtin_nontemporal_store(o1, (f32x4*)(out32 + off + bj * HALF + 4)); } }
;                     else if (!dry) {
;                         sq += (o0[0] * o0[0] + o0[1] * o0[1]) + (o0[2] * o0[2] + o0[3] * o0[3]) + (o1[0] * o1[0] + o1[1] * o1[1]) + (o1[2] * o1[2] + o1[3] * o1[3]);
;                         u32x4 w; w.x = pkh(o0[0], o0[1]); w.y = pkh(o0[2], o0[3]); w.z = pkh(o1[0], o1[1]); w.w = pkh(o1[2], o1[3]);
;                         *(u32x4*)(h16 + off + bj * HALF) = w;
;                         if (h8) { u32x2 q; q.x = pk8(o0[0] * F8_SA, o0[1] * F8_SA, o0[2] * F8_SA, o0[3] * F8_SA); q.y = pk8(o1[0] * F8_SA, o1[1] * F8_SA, o1[2] * F8_SA, o1[3] * F8_SA); *(u32x2*)(h8 + off + bj * HALF) = q; } }
;                 }
;                 if (!out32 && !dry) { sq += __shfl_xor(sq, 16); sq += __shfl_xor(sq, 32); if (fq == 0) atomicAdd(ss_out + row, sq); }
	v_lshl_add_u64 v[100:101], v[114:115], 2, s[18:19]
	s_waitcnt lgkmcnt(0)
	v_add_f32_e32 v98, v98, v99
	global_atomic_add_f32 v[100:101], v98, off
.LBB0_407:
	s_or_b64 exec, exec, s[2:3]
	v_add_u32_e32 v98, 32, v148
	s_waitcnt lgkmcnt(0)
	v_ashrrev_i32_e32 v99, 31, v98
	v_lshlrev_b64 v[100:101], 11, v[98:99]
	v_lshl_add_u64 v[100:101], s[90:91], 0, v[100:101]
	v_lshl_add_u64 v[108:109], v[146:147], 1, v[100:101]
	global_load_dwordx4 v[100:103], v[108:109], off
	global_load_dwordx4 v[104:107], v[108:109], off offset:256
	s_waitcnt vmcnt(1)
	v_cvt_f32_f16_e32 v110, v100
	v_cvt_f32_f16_sdwa v111, v100 dst_sel:DWORD dst_unused:UNUSED_PAD src0_sel:WORD_1
	v_cvt_f32_f16_e32 v100, v101
	v_cvt_f32_f16_sdwa v101, v101 dst_sel:DWORD dst_unused:UNUSED_PAD src0_sel:WORD_1
	s_waitcnt vmcnt(0)
	v_cvt_f32_f16_e32 v114, v104
	v_cvt_f32_f16_sdwa v115, v104 dst_sel:DWORD dst_unused:UNUSED_PAD src0_sel:WORD_1
	v_cvt_f32_f16_e32 v104, v105
	v_cvt_f32_f16_sdwa v105, v105 dst_sel:DWORD dst_unused:UNUSED_PAD src0_sel:WORD_1
	v_cvt_f32_f16_e32 v112, v102
	v_cvt_f32_f16_sdwa v113, v102 dst_sel:DWORD dst_unused:UNUSED_PAD src0_sel:WORD_1
	v_cvt_f32_f16_e32 v102, v103
	v_cvt_f32_f16_sdwa v103, v103 dst_sel:DWORD dst_unused:UNUSED_PAD src0_sel:WORD_1
	v_cvt_f32_f16_e32 v118, v106
	v_cvt_f32_f16_sdwa v119, v106 dst_sel:DWORD dst_unused:UNUSED_PAD src0_sel:WORD_1
	v_cvt_f32_f16_e32 v106, v107
	v_cvt_f32_f16_sdwa v107, v107 dst_sel:DWORD dst_unused:UNUSED_PAD src0_sel:WORD_1
	v_pk_add_f32 v[94:95], v[94:95], v[110:111]
	v_pk_add_f32 v[96:97], v[96:97], v[100:101]
	v_pk_add_f32 v[86:87], v[86:87], v[114:115]
	v_pk_add_f32 v[88:89], v[88:89], v[104:105]
	v_pk_add_f32 v[90:91], v[90:91], v[112:113]
	v_pk_add_f32 v[92:93], v[92:93], v[102:103]
	v_pk_add_f32 v[100:101], v[82:83], v[118:119]
	v_pk_add_f32 v[102:103], v[84:85], v[106:107]
	v_pk_mul_f32 v[84:85], v[94:95], v[94:95]
	v_pk_mul_f32 v[104:105], v[96:97], v[96:97]
	v_cvt_pk_f16_f32 v82, v94, v95
	v_cvt_pk_f16_f32 v83, v96, v97
	v_pk_mul_f32 v[94:95], v[86:87], v[86:87]
	v_pk_mul_f32 v[96:97], v[88:89], v[88:89]
	v_pk_mul_f32 v[106:107], v[90:91], v[90:91]
	v_pk_mul_f32 v[112:113], v[100:101], v[100:101]
	v_add_f32_e32 v96, v96, v97
	v_add_f32_e32 v94, v94, v95
	v_add_f32_e32 v104, v104, v105
	v_add_f32_e32 v84, v84, v85
	v_pk_mul_f32 v[110:111], v[92:93], v[92:93]
	v_pk_mul_f32 v[114:115], v[102:103], v[102:103]
	v_add_f32_e32 v95, v112, v113
	v_add_f32_e32 v85, v106, v107
	v_add_f32_e32 v94, v94, v96
	v_add_f32_e32 v84, v84, v104
	v_add_f32_e32 v97, v114, v115
	v_add_f32_e32 v105, v110, v111
	v_add_f32_e32 v94, v95, v94
	v_add_f32_e32 v84, v85, v84
	v_add_f32_e32 v85, v97, v94
	v_add_f32_e32 v84, v105, v84
	v_add_f32_e32 v94, v84, v85
	ds_bpermute_b32 v95, v156, v94
	v_cvt_pk_f16_f32 v84, v90, v91
	v_cvt_pk_f16_f32 v85, v92, v93
	global_store_dwordx4 v[108:109], v[82:85], off sc1
	s_waitcnt lgkmcnt(0)
	s_nop 0
	v_add_f32_e32 v82, v94, v95
	ds_bpermute_b32 v83, v116, v82
	v_cvt_pk_f16_f32 v84, v86, v87
	v_cvt_pk_f16_f32 v85, v88, v89
	v_cvt_pk_f16_f32 v86, v100, v101
	v_cvt_pk_f16_f32 v87, v102, v103
	global_store_dwordx4 v[108:109], v[84:87], off offset:256 sc1
	s_and_saveexec_b64 s[2:3], vcc
	s_cbranch_execz .LBB0_409
	v_lshl_add_u64 v[84:85], v[98:99], 2, s[18:19]
	s_waitcnt lgkmcnt(0)
	v_add_f32_e32 v82, v82, v83
	global_atomic_add_f32 v[84:85], v82, off
.LBB0_409:
	s_or_b64 exec, exec, s[2:3]
	v_add_u32_e32 v82, 48, v148
	s_waitcnt lgkmcnt(0)
	v_ashrrev_i32_e32 v83, 31, v82
	v_lshlrev_b64 v[84:85], 11, v[82:83]
	v_lshl_add_u64 v[84:85], s[90:91], 0, v[84:85]
	v_lshl_add_u64 v[92:93], v[146:147], 1, v[84:85]
	global_load_dwordx4 v[84:87], v[92:93], off
	global_load_dwordx4 v[88:91], v[92:93], off offset:256
	s_waitcnt vmcnt(1)
	v_cvt_f32_f16_e32 v94, v84
	v_cvt_f32_f16_sdwa v95, v84 dst_sel:DWORD dst_unused:UNUSED_PAD src0_sel:WORD_1
	v_cvt_f32_f16_e32 v84, v85
	v_cvt_f32_f16_sdwa v85, v85 dst_sel:DWORD dst_unused:UNUSED_PAD src0_sel:WORD_1
	s_waitcnt vmcnt(0)
	v_cvt_f32_f16_e32 v98, v88
	v_cvt_f32_f16_sdwa v99, v88 dst_sel:DWORD dst_unused:UNUSED_PAD src0_sel:WORD_1
	v_cvt_f32_f16_e32 v88, v89
	v_cvt_f32_f16_sdwa v89, v89 dst_sel:DWORD dst_unused:UNUSED_PAD src0_sel:WORD_1
	v_cvt_f32_f16_e32 v96, v86
	v_cvt_f32_f16_sdwa v97, v86 dst_sel:DWORD dst_unused:UNUSED_PAD src0_sel:WORD_1
	v_cvt_f32_f16_e32 v86, v87
	v_cvt_f32_f16_sdwa v87, v87 dst_sel:DWORD dst_unused:UNUSED_PAD src0_sel:WORD_1
	v_cvt_f32_f16_e32 v100, v90
	v_cvt_f32_f16_sdwa v101, v90 dst_sel:DWORD dst_unused:UNUSED_PAD src0_sel:WORD_1
	v_cvt_f32_f16_e32 v90, v91
	v_cvt_f32_f16_sdwa v91, v91 dst_sel:DWORD dst_unused:UNUSED_PAD src0_sel:WORD_1
	v_pk_add_f32 v[78:79], v[78:79], v[94:95]
	v_pk_add_f32 v[80:81], v[80:81], v[84:85]
	v_pk_add_f32 v[70:71], v[70:71], v[98:99]
	v_pk_add_f32 v[72:73], v[72:73], v[88:89]
	v_pk_add_f32 v[74:75], v[74:75], v[96:97]
	v_pk_add_f32 v[76:77], v[76:77], v[86:87]
	v_pk_add_f32 v[84:85], v[66:67], v[100:101]
	v_pk_add_f32 v[86:87], v[68:69], v[90:91]
	v_pk_mul_f32 v[68:69], v[78:79], v[78:79]
	v_pk_mul_f32 v[88:89], v[80:81], v[80:81]
	v_cvt_pk_f16_f32 v66, v78, v79
	v_cvt_pk_f16_f32 v67, v80, v81
	v_pk_mul_f32 v[78:79], v[70:71], v[70:71]
	v_pk_mul_f32 v[80:81], v[72:73], v[72:73]
	v_pk_mul_f32 v[90:91], v[74:75], v[74:75]
	v_pk_mul_f32 v[96:97], v[84:85], v[84:85]
	v_add_f32_e32 v80, v80, v81
	v_add_f32_e32 v78, v78, v79
	v_add_f32_e32 v88, v88, v89
	v_add_f32_e32 v68, v68, v69
	v_pk_mul_f32 v[94:95], v[76:77], v[76:77]
	v_pk_mul_f32 v[98:99], v[86:87], v[86:87]
	v_add_f32_e32 v79, v96, v97
	v_add_f32_e32 v69, v90, v91
	v_add_f32_e32 v78, v78, v80
	v_add_f32_e32 v68, v68, v88
	v_add_f32_e32 v81, v98, v99
	v_add_f32_e32 v89, v94, v95
	v_add_f32_e32 v78, v79, v78
	v_add_f32_e32 v68, v69, v68
	v_add_f32_e32 v69, v81, v78
	v_add_f32_e32 v68, v89, v68
	v_add_f32_e32 v78, v68, v69
	ds_bpermute_b32 v79, v156, v78
	v_cvt_pk_f16_f32 v68, v74, v75
	v_cvt_pk_f16_f32 v69, v76, v77
	global_store_dwordx4 v[92:93], v[66:69], off sc1
	s_waitcnt lgkmcnt(0)
	s_nop 0
	v_add_f32_e32 v66, v78, v79
	ds_bpermute_b32 v67, v116, v66
	v_cvt_pk_f16_f32 v68, v70, v71
	v_cvt_pk_f16_f32 v69, v72, v73
	v_cvt_pk_f16_f32 v70, v84, v85
	v_cvt_pk_f16_f32 v71, v86, v87
	global_store_dwordx4 v[92:93], v[68:71], off offset:256 sc1
	s_and_saveexec_b64 s[2:3], vcc
	s_cbranch_execz .LBB0_411
	v_lshl_add_u64 v[68:69], v[82:83], 2, s[18:19]
	s_waitcnt lgkmcnt(0)
	v_add_f32_e32 v66, v66, v67
	global_atomic_add_f32 v[68:69], v66, off
; __device__ __forceinline__ unsigned pkh(float lo, float hi) { f32x2 v = {lo, hi}; h16x2 h = __builtin_convertvector(v, h16x2); return __builtin_bit_cast(unsigned, h); }
; __device__ __forceinline__ unsigned pk8(float a, float b, float c, float d) { int w = __builtin_amdgcn_cvt_pk_fp8_f32(a, b, 0, false); w = __builtin_amdgcn_cvt_pk_fp8_f32(c, d, w, true); return (unsigned)w; }
;     __device__ __forceinline__ void operator()(f32x4 (&acc)[2][2][4][2], const Unit& u, const Order& S, int wr, int wc, int fr_, int fq_, LAS unsigned char*, int) const {
;     ...
;                 const int row = row0 + ai * HALF + m * 16; const size_t off = (size_t)row * DM + col0;
;                 float sq = 0.f;
; #pragma unroll
;                 for (int bj = 0; bj < 2; ++bj) {
;                     const h16x8 bs = *(const h16x8*)(h16 + off + bj * HALF);
;                     f32x4 o0 = acc[ai][bj][m][0] * pre, o1 = acc[ai][bj][m][1] * pre;
; #pragma unroll
;                     for (int e = 0; e < 4; ++e) { o0[e] += (float)bs[e]; o1[e] += (float)bs[4 + e]; }
;                     if (out32) { if (!dry) { __builtin_nontemporal_store(o0, (f32x4*)(out32 + off + bj * HALF)); __builtin_nontemporal_store(o1, (f32x4*)(out32 + off + bj * HALF + 4)); } }
;                     else if (!dry) {
;                         sq += (o0[0] * o0[0] + o0[1] * o0[1]) + (o0[2] * o0[2] + o0[3] * o0[3]) + (o1[0] * o1[0] + o1[1] * o1[1]) + (o1[2] * o1[2] + o1[3] * o1[3]);
;                         u32x4 w; w.x = pkh(o0[0], o0[1]); w.y = pkh(o0[2], o0[3]); w.z = pkh(o1[0], o1[1]); w.w = pkh(o1[2], o1[3]);
;                         *(u32x4*)(h16 + off + bj * HALF) = w;
;                         if (h8) { u32x2 q; q.x = pk8(o0[0] * F8_SA, o0[1] * F8_SA, o0[2] * F8_SA, o0[3] * F8_SA); q.y = pk8(o1[0] * F8_SA, o1[1] * F8_SA, o1[2] * F8_SA, o1[3] * F8_SA); *(u32x2*)(h8 + off + bj * HALF) = q; } }
;                 }
;                 if (!out32 && !dry) { sq += __shfl_xor(sq, 16); sq += __shfl_xor(sq, 32); if (fq == 0) atomicAdd(ss_out + row, sq); }
.LBB0_411:
	s_or_b64 exec, exec, s[2:3]
	v_add_u32_e32 v66, 0x80, v148
	s_waitcnt lgkmcnt(0)
	v_ashrrev_i32_e32 v67, 31, v66
	v_lshlrev_b64 v[68:69], 11, v[66:67]
	v_lshl_add_u64 v[68:69], s[90:91], 0, v[68:69]
	v_lshl_add_u64 v[76:77], v[146:147], 1, v[68:69]
	global_load_dwordx4 v[68:71], v[76:77], off
	global_load_dwordx4 v[72:75], v[76:77], off offset:256
	s_waitcnt vmcnt(1)
	v_cvt_f32_f16_e32 v78, v68
	v_cvt_f32_f16_sdwa v79, v68 dst_sel:DWORD dst_unused:UNUSED_PAD src0_sel:WORD_1
	v_cvt_f32_f16_e32 v68, v69
	v_cvt_f32_f16_sdwa v69, v69 dst_sel:DWORD dst_unused:UNUSED_PAD src0_sel:WORD_1
	s_waitcnt vmcnt(0)
	v_cvt_f32_f16_e32 v82, v72
	v_cvt_f32_f16_sdwa v83, v72 dst_sel:DWORD dst_unused:UNUSED_PAD src0_sel:WORD_1
	v_cvt_f32_f16_e32 v72, v73
	v_cvt_f32_f16_sdwa v73, v73 dst_sel:DWORD dst_unused:UNUSED_PAD src0_sel:WORD_1
	v_cvt_f32_f16_e32 v80, v70
	v_cvt_f32_f16_sdwa v81, v70 dst_sel:DWORD dst_unused:UNUSED_PAD src0_sel:WORD_1
	v_cvt_f32_f16_e32 v70, v71
	v_cvt_f32_f16_sdwa v71, v71 dst_sel:DWORD dst_unused:UNUSED_PAD src0_sel:WORD_1
	v_cvt_f32_f16_e32 v84, v74
	v_cvt_f32_f16_sdwa v85, v74 dst_sel:DWORD dst_unused:UNUSED_PAD src0_sel:WORD_1
	v_cvt_f32_f16_e32 v74, v75
	v_cvt_f32_f16_sdwa v75, v75 dst_sel:DWORD dst_unused:UNUSED_PAD src0_sel:WORD_1
	v_pk_add_f32 v[62:63], v[62:63], v[78:79]
	v_pk_add_f32 v[64:65], v[64:65], v[68:69]
	v_pk_add_f32 v[54:55], v[54:55], v[82:83]
	v_pk_add_f32 v[56:57], v[56:57], v[72:73]
	v_pk_add_f32 v[58:59], v[58:59], v[80:81]
	v_pk_add_f32 v[60:61], v[60:61], v[70:71]
	v_pk_add_f32 v[68:69], v[50:51], v[84:85]
	v_pk_add_f32 v[70:71], v[52:53], v[74:75]
	v_pk_mul_f32 v[52:53], v[62:63], v[62:63]
	v_pk_mul_f32 v[72:73], v[64:65], v[64:65]
	v_cvt_pk_f16_f32 v50, v62, v63
	v_cvt_pk_f16_f32 v51, v64, v65
	v_pk_mul_f32 v[62:63], v[54:55], v[54:55]
	v_pk_mul_f32 v[64:65], v[56:57], v[56:57]
	v_pk_mul_f32 v[74:75], v[58:59], v[58:59]
	v_pk_mul_f32 v[80:81], v[68:69], v[68:69]
	v_add_f32_e32 v64, v64, v65
	v_add_f32_e32 v62, v62, v63
	v_add_f32_e32 v72, v72, v73
	v_add_f32_e32 v52, v52, v53
	v_pk_mul_f32 v[78:79], v[60:61], v[60:61]
	v_pk_mul_f32 v[82:83], v[70:71], v[70:71]
	v_add_f32_e32 v63, v80, v81
	v_add_f32_e32 v53, v74, v75
	v_add_f32_e32 v62, v62, v64
	v_add_f32_e32 v52, v52, v72
	v_add_f32_e32 v65, v82, v83
	v_add_f32_e32 v73, v78, v79
	v_add_f32_e32 v62, v63, v62
	v_add_f32_e32 v52, v53, v52
	v_add_f32_e32 v53, v65, v62
	v_add_f32_e32 v52, v73, v52
	v_add_f32_e32 v62, v52, v53
	ds_bpermute_b32 v63, v156, v62
	v_cvt_pk_f16_f32 v52, v58, v59
	v_cvt_pk_f16_f32 v53, v60, v61
	global_store_dwordx4 v[76:77], v[50:53], off sc1
	s_waitcnt lgkmcnt(0)
	s_nop 0
	v_add_f32_e32 v50, v62, v63
	ds_bpermute_b32 v51, v116, v50
	v_cvt_pk_f16_f32 v52, v54, v55
	v_cvt_pk_f16_f32 v53, v56, v57
	v_cvt_pk_f16_f32 v54, v68, v69
	v_cvt_pk_f16_f32 v55, v70, v71
	global_store_dwordx4 v[76:77], v[52:55], off offset:256 sc1
	s_and_saveexec_b64 s[2:3], vcc
	s_cbranch_execz .LBB0_413
	v_lshl_add_u64 v[52:53], v[66:67], 2, s[18:19]
	s_waitcnt lgkmcnt(0)
	v_add_f32_e32 v50, v50, v51
	global_atomic_add_f32 v[52:53], v50, off
.LBB0_413:
	s_or_b64 exec, exec, s[2:3]
	v_add_u32_e32 v50, 0x90, v148
	s_waitcnt lgkmcnt(0)
	v_ashrrev_i32_e32 v51, 31, v50
	v_lshlrev_b64 v[52:53], 11, v[50:51]
	v_lshl_add_u64 v[52:53], s[90:91], 0, v[52:53]
	v_lshl_add_u64 v[60:61], v[146:147], 1, v[52:53]
	global_load_dwordx4 v[52:55], v[60:61], off
	global_load_dwordx4 v[56:59], v[60:61], off offset:256
	s_waitcnt vmcnt(1)
	v_cvt_f32_f16_e32 v62, v52
	v_cvt_f32_f16_sdwa v63, v52 dst_sel:DWORD dst_unused:UNUSED_PAD src0_sel:WORD_1
	v_cvt_f32_f16_e32 v52, v53
	v_cvt_f32_f16_sdwa v53, v53 dst_sel:DWORD dst_unused:UNUSED_PAD src0_sel:WORD_1
	s_waitcnt vmcnt(0)
	v_cvt_f32_f16_e32 v66, v56
	v_cvt_f32_f16_sdwa v67, v56 dst_sel:DWORD dst_unused:UNUSED_PAD src0_sel:WORD_1
	v_cvt_f32_f16_e32 v56, v57
	v_cvt_f32_f16_sdwa v57, v57 dst_sel:DWORD dst_unused:UNUSED_PAD src0_sel:WORD_1
	v_cvt_f32_f16_e32 v64, v54
	v_cvt_f32_f16_sdwa v65, v54 dst_sel:DWORD dst_unused:UNUSED_PAD src0_sel:WORD_1
	v_cvt_f32_f16_e32 v54, v55
	v_cvt_f32_f16_sdwa v55, v55 dst_sel:DWORD dst_unused:UNUSED_PAD src0_sel:WORD_1
	v_cvt_f32_f16_e32 v68, v58
	v_cvt_f32_f16_sdwa v69, v58 dst_sel:DWORD dst_unused:UNUSED_PAD src0_sel:WORD_1
	v_cvt_f32_f16_e32 v58, v59
	v_cvt_f32_f16_sdwa v59, v59 dst_sel:DWORD dst_unused:UNUSED_PAD src0_sel:WORD_1
	v_pk_add_f32 v[46:47], v[46:47], v[62:63]
	v_pk_add_f32 v[48:49], v[48:49], v[52:53]
	v_pk_add_f32 v[38:39], v[38:39], v[66:67]
	v_pk_add_f32 v[40:41], v[40:41], v[56:57]
	v_pk_add_f32 v[42:43], v[42:43], v[64:65]
	v_pk_add_f32 v[44:45], v[44:45], v[54:55]
	v_pk_add_f32 v[52:53], v[34:35], v[68:69]
	v_pk_add_f32 v[54:55], v[36:37], v[58:59]
	v_pk_mul_f32 v[36:37], v[46:47], v[46:47]
	v_pk_mul_f32 v[56:57], v[48:49], v[48:49]
	v_cvt_pk_f16_f32 v34, v46, v47
	v_cvt_pk_f16_f32 v35, v48, v49
	v_pk_mul_f32 v[46:47], v[38:39], v[38:39]
	v_pk_mul_f32 v[48:49], v[40:41], v[40:41]
	v_pk_mul_f32 v[58:59], v[42:43], v[42:43]
	v_pk_mul_f32 v[64:65], v[52:53], v[52:53]
	v_add_f32_e32 v48, v48, v49
	v_add_f32_e32 v46, v46, v47
	v_add_f32_e32 v56, v56, v57
	v_add_f32_e32 v36, v36, v37
	v_pk_mul_f32 v[62:63], v[44:45], v[44:45]
	v_pk_mul_f32 v[66:67], v[54:55], v[54:55]
	v_add_f32_e32 v47, v64, v65
	v_add_f32_e32 v37, v58, v59
	v_add_f32_e32 v46, v46, v48
	v_add_f32_e32 v36, v36, v56
	v_add_f32_e32 v49, v66, v67
	v_add_f32_e32 v57, v62, v63
	v_add_f32_e32 v46, v47, v46
	v_add_f32_e32 v36, v37, v36
	v_add_f32_e32 v37, v49, v46
	v_add_f32_e32 v36, v57, v36
	v_add_f32_e32 v46, v36, v37
	ds_bpermute_b32 v47, v156, v46
	v_cvt_pk_f16_f32 v36, v42, v43
	v_cvt_pk_f16_f32 v37, v44, v45
	global_store_dwordx4 v[60:61], v[34:37], off sc1
	s_waitcnt lgkmcnt(0)
	s_nop 0
	v_add_f32_e32 v34, v46, v47
	ds_bpermute_b32 v35, v116, v34
	v_cvt_pk_f16_f32 v36, v38, v39
	v_cvt_pk_f16_f32 v37, v40, v41
	v_cvt_pk_f16_f32 v38, v52, v53
	v_cvt_pk_f16_f32 v39, v54, v55
	global_store_dwordx4 v[60:61], v[36:39], off offset:256 sc1
	s_and_saveexec_b64 s[2:3], vcc
	s_cbranch_execz .LBB0_415
	v_lshl_add_u64 v[36:37], v[50:51], 2, s[18:19]
	s_waitcnt lgkmcnt(0)
	v_add_f32_e32 v34, v34, v35
	global_atomic_add_f32 v[36:37], v34, off
; __device__ __forceinline__ unsigned pkh(float lo, float hi) { f32x2 v = {lo, hi}; h16x2 h = __builtin_convertvector(v, h16x2); return __builtin_bit_cast(unsigned, h); }
; __device__ __forceinline__ unsigned pk8(float a, float b, float c, float d) { int w = __builtin_amdgcn_cvt_pk_fp8_f32(a, b, 0, false); w = __builtin_amdgcn_cvt_pk_fp8_f32(c, d, w, true); return (unsigned)w; }
;     __device__ __forceinline__ void operator()(f32x4 (&acc)[2][2][4][2], const Unit& u, const Order& S, int wr, int wc, int fr_, int fq_, LAS unsigned char*, int) const {
;     ...
;                 const int row = row0 + ai * HALF + m * 16; const size_t off = (size_t)row * DM + col0;
;                 float sq = 0.f;
; #pragma unroll
;                 for (int bj = 0; bj < 2; ++bj) {
;                     const h16x8 bs = *(const h16x8*)(h16 + off + bj * HALF);
;                     f32x4 o0 = acc[ai][bj][m][0] * pre, o1 = acc[ai][bj][m][1] * pre;
; #pragma unroll
;                     for (int e = 0; e < 4; ++e) { o0[e] += (float)bs[e]; o1[e] += (float)bs[4 + e]; }
;                     if (out32) { if (!dry) { __builtin_nontemporal_store(o0, (f32x4*)(out32 + off + bj * HALF)); __builtin_nontemporal_store(o1, (f32x4*)(out32 + off + bj * HALF + 4)); } }
;                     else if (!dry) {
;                         sq += (o0[0] * o0[0] + o0[1] * o0[1]) + (o0[2] * o0[2] + o0[3] * o0[3]) + (o1[0] * o1[0] + o1[1] * o1[1]) + (o1[2] * o1[2] + o1[3] * o1[3]);
;                         u32x4 w; w.x = pkh(o0[0], o0[1]); w.y = pkh(o0[2], o0[3]); w.z = pkh(o1[0], o1[1]); w.w = pkh(o1[2], o1[3]);
;                         *(u32x4*)(h16 + off + bj * HALF) = w;
;                         if (h8) { u32x2 q; q.x = pk8(o0[0] * F8_SA, o0[1] * F8_SA, o0[2] * F8_SA, o0[3] * F8_SA); q.y = pk8(o1[0] * F8_SA, o1[1] * F8_SA, o1[2] * F8_SA, o1[3] * F8_SA); *(u32x2*)(h8 + off + bj * HALF) = q; } }
;                 }
;                 if (!out32 && !dry) { sq += __shfl_xor(sq, 16); sq += __shfl_xor(sq, 32); if (fq == 0) atomicAdd(ss_out + row, sq); }
.LBB0_415:
	s_or_b64 exec, exec, s[2:3]
	v_add_u32_e32 v34, 0xa0, v148
	s_waitcnt lgkmcnt(0)
	v_ashrrev_i32_e32 v35, 31, v34
	v_lshlrev_b64 v[36:37], 11, v[34:35]
	v_lshl_add_u64 v[36:37], s[90:91], 0, v[36:37]
	v_lshl_add_u64 v[44:45], v[146:147], 1, v[36:37]
	global_load_dwordx4 v[36:39], v[44:45], off
	global_load_dwordx4 v[40:43], v[44:45], off offset:256
	s_waitcnt vmcnt(1)
	v_cvt_f32_f16_e32 v46, v36
	v_cvt_f32_f16_sdwa v47, v36 dst_sel:DWORD dst_unused:UNUSED_PAD src0_sel:WORD_1
	v_cvt_f32_f16_e32 v36, v37
	v_cvt_f32_f16_sdwa v37, v37 dst_sel:DWORD dst_unused:UNUSED_PAD src0_sel:WORD_1
	s_waitcnt vmcnt(0)
	v_cvt_f32_f16_e32 v50, v40
	v_cvt_f32_f16_sdwa v51, v40 dst_sel:DWORD dst_unused:UNUSED_PAD src0_sel:WORD_1
	v_cvt_f32_f16_e32 v40, v41
	v_cvt_f32_f16_sdwa v41, v41 dst_sel:DWORD dst_unused:UNUSED_PAD src0_sel:WORD_1
	v_cvt_f32_f16_e32 v48, v38
	v_cvt_f32_f16_sdwa v49, v38 dst_sel:DWORD dst_unused:UNUSED_PAD src0_sel:WORD_1
	v_cvt_f32_f16_e32 v38, v39
	v_cvt_f32_f16_sdwa v39, v39 dst_sel:DWORD dst_unused:UNUSED_PAD src0_sel:WORD_1
	v_cvt_f32_f16_e32 v52, v42
	v_cvt_f32_f16_sdwa v53, v42 dst_sel:DWORD dst_unused:UNUSED_PAD src0_sel:WORD_1
	v_cvt_f32_f16_e32 v42, v43
	v_cvt_f32_f16_sdwa v43, v43 dst_sel:DWORD dst_unused:UNUSED_PAD src0_sel:WORD_1
	v_pk_add_f32 v[30:31], v[30:31], v[46:47]
	v_pk_add_f32 v[32:33], v[32:33], v[36:37]
	v_pk_add_f32 v[22:23], v[22:23], v[50:51]
	v_pk_add_f32 v[24:25], v[24:25], v[40:41]
	v_pk_add_f32 v[26:27], v[26:27], v[48:49]
	v_pk_add_f32 v[28:29], v[28:29], v[38:39]
	v_pk_add_f32 v[36:37], v[18:19], v[52:53]
	v_pk_add_f32 v[38:39], v[20:21], v[42:43]
	v_pk_mul_f32 v[20:21], v[30:31], v[30:31]
	v_pk_mul_f32 v[40:41], v[32:33], v[32:33]
	v_cvt_pk_f16_f32 v18, v30, v31
	v_cvt_pk_f16_f32 v19, v32, v33
	v_pk_mul_f32 v[30:31], v[22:23], v[22:23]
	v_pk_mul_f32 v[32:33], v[24:25], v[24:25]
	v_pk_mul_f32 v[42:43], v[26:27], v[26:27]
	v_pk_mul_f32 v[48:49], v[36:37], v[36:37]
	v_add_f32_e32 v32, v32, v33
	v_add_f32_e32 v30, v30, v31
	v_add_f32_e32 v40, v40, v41
	v_add_f32_e32 v20, v20, v21
	v_pk_mul_f32 v[46:47], v[28:29], v[28:29]
	v_pk_mul_f32 v[50:51], v[38:39], v[38:39]
	v_add_f32_e32 v31, v48, v49
	v_add_f32_e32 v21, v42, v43
	v_add_f32_e32 v30, v30, v32
	v_add_f32_e32 v20, v20, v40
	v_add_f32_e32 v33, v50, v51
	v_add_f32_e32 v41, v46, v47
	v_add_f32_e32 v30, v31, v30
	v_add_f32_e32 v20, v21, v20
	v_add_f32_e32 v21, v33, v30
	v_add_f32_e32 v20, v41, v20
	v_add_f32_e32 v30, v20, v21
	ds_bpermute_b32 v31, v156, v30
	v_cvt_pk_f16_f32 v20, v26, v27
	v_cvt_pk_f16_f32 v21, v28, v29
	global_store_dwordx4 v[44:45], v[18:21], off sc1
	s_waitcnt lgkmcnt(0)
	s_nop 0
	v_add_f32_e32 v18, v30, v31
	ds_bpermute_b32 v19, v116, v18
	v_cvt_pk_f16_f32 v20, v22, v23
	v_cvt_pk_f16_f32 v21, v24, v25
	v_cvt_pk_f16_f32 v22, v36, v37
	v_cvt_pk_f16_f32 v23, v38, v39
	global_store_dwordx4 v[44:45], v[20:23], off offset:256 sc1
	s_and_saveexec_b64 s[2:3], vcc
	s_cbranch_execz .LBB0_417
	v_lshl_add_u64 v[20:21], v[34:35], 2, s[18:19]
	s_waitcnt lgkmcnt(0)
	v_add_f32_e32 v18, v18, v19
	global_atomic_add_f32 v[20:21], v18, off
.LBB0_417:
	s_or_b64 exec, exec, s[2:3]
	v_add_u32_e32 v18, 0xb0, v148
	s_waitcnt lgkmcnt(0)
	v_ashrrev_i32_e32 v19, 31, v18
	v_lshlrev_b64 v[20:21], 11, v[18:19]
	v_lshl_add_u64 v[20:21], s[90:91], 0, v[20:21]
	v_lshl_add_u64 v[28:29], v[146:147], 1, v[20:21]
	global_load_dwordx4 v[20:23], v[28:29], off
	global_load_dwordx4 v[24:27], v[28:29], off offset:256
	s_waitcnt vmcnt(1)
	v_cvt_f32_f16_e32 v30, v20
	v_cvt_f32_f16_sdwa v31, v20 dst_sel:DWORD dst_unused:UNUSED_PAD src0_sel:WORD_1
	v_cvt_f32_f16_e32 v20, v21
	v_cvt_f32_f16_sdwa v21, v21 dst_sel:DWORD dst_unused:UNUSED_PAD src0_sel:WORD_1
	s_waitcnt vmcnt(0)
	v_cvt_f32_f16_e32 v34, v24
	v_cvt_f32_f16_sdwa v35, v24 dst_sel:DWORD dst_unused:UNUSED_PAD src0_sel:WORD_1
	v_cvt_f32_f16_e32 v24, v25
	v_cvt_f32_f16_sdwa v25, v25 dst_sel:DWORD dst_unused:UNUSED_PAD src0_sel:WORD_1
	v_cvt_f32_f16_e32 v32, v22
	v_cvt_f32_f16_sdwa v33, v22 dst_sel:DWORD dst_unused:UNUSED_PAD src0_sel:WORD_1
	v_cvt_f32_f16_e32 v22, v23
	v_cvt_f32_f16_sdwa v23, v23 dst_sel:DWORD dst_unused:UNUSED_PAD src0_sel:WORD_1
	v_cvt_f32_f16_e32 v36, v26
	v_cvt_f32_f16_sdwa v37, v26 dst_sel:DWORD dst_unused:UNUSED_PAD src0_sel:WORD_1
	v_cvt_f32_f16_e32 v26, v27
	v_cvt_f32_f16_sdwa v27, v27 dst_sel:DWORD dst_unused:UNUSED_PAD src0_sel:WORD_1
	v_pk_add_f32 v[14:15], v[14:15], v[30:31]
	v_pk_add_f32 v[16:17], v[16:17], v[20:21]
	v_pk_add_f32 v[6:7], v[6:7], v[34:35]
	v_pk_add_f32 v[8:9], v[8:9], v[24:25]
	v_pk_add_f32 v[10:11], v[10:11], v[32:33]
	v_pk_add_f32 v[12:13], v[12:13], v[22:23]
	v_pk_add_f32 v[20:21], v[2:3], v[36:37]
	v_pk_add_f32 v[22:23], v[4:5], v[26:27]
	v_pk_mul_f32 v[4:5], v[14:15], v[14:15]
	v_pk_mul_f32 v[24:25], v[16:17], v[16:17]
	v_cvt_pk_f16_f32 v2, v14, v15
	v_cvt_pk_f16_f32 v3, v16, v17
	v_pk_mul_f32 v[14:15], v[6:7], v[6:7]
	v_pk_mul_f32 v[16:17], v[8:9], v[8:9]
	v_pk_mul_f32 v[26:27], v[10:11], v[10:11]
	v_pk_mul_f32 v[32:33], v[20:21], v[20:21]
	v_add_f32_e32 v16, v16, v17
	v_add_f32_e32 v14, v14, v15
	v_add_f32_e32 v24, v24, v25
	v_add_f32_e32 v4, v4, v5
	v_pk_mul_f32 v[30:31], v[12:13], v[12:13]
	v_pk_mul_f32 v[34:35], v[22:23], v[22:23]
	v_add_f32_e32 v15, v32, v33
	v_add_f32_e32 v5, v26, v27
	v_add_f32_e32 v14, v14, v16
	v_add_f32_e32 v4, v4, v24
	v_add_f32_e32 v17, v34, v35
	v_add_f32_e32 v25, v30, v31
	v_add_f32_e32 v14, v15, v14
	v_add_f32_e32 v4, v5, v4
	v_add_f32_e32 v5, v17, v14
	v_add_f32_e32 v4, v25, v4
	v_add_f32_e32 v14, v4, v5
	ds_bpermute_b32 v15, v156, v14
	v_cvt_pk_f16_f32 v4, v10, v11
	v_cvt_pk_f16_f32 v5, v12, v13
	global_store_dwordx4 v[28:29], v[2:5], off sc1
	s_waitcnt lgkmcnt(0)
	s_nop 0
	v_add_f32_e32 v2, v14, v15
	ds_bpermute_b32 v3, v116, v2
	v_cvt_pk_f16_f32 v4, v6, v7
	v_cvt_pk_f16_f32 v5, v8, v9
	v_cvt_pk_f16_f32 v6, v20, v21
	v_cvt_pk_f16_f32 v7, v22, v23
	global_store_dwordx4 v[28:29], v[4:7], off offset:256 sc1
	s_and_saveexec_b64 s[2:3], vcc
	s_cbranch_execz .LBB0_419
	v_lshl_add_u64 v[4:5], v[18:19], 2, s[18:19]
	s_waitcnt lgkmcnt(0)
	v_add_f32_e32 v2, v2, v3
	global_atomic_add_f32 v[4:5], v2, off

; __device__ __forceinline__ unsigned pkh(float lo, float hi) { f32x2 v = {lo, hi}; h16x2 h = __builtin_convertvector(v, h16x2); return __builtin_bit_cast(unsigned, h); }
; __device__ __forceinline__ unsigned pk8(float a, float b, float c, float d) { int w = __builtin_amdgcn_cvt_pk_fp8_f32(a, b, 0, false); w = __builtin_amdgcn_cvt_pk_fp8_f32(c, d, w, true); return (unsigned)w; }
;     __device__ __forceinline__ void operator()(f32x4 (&acc)[2][2][4][2], const Unit& u, const Order& S, int wr, int wc, int fr_, int fq_, LAS unsigned char*, int) const {
;     ...
;                 const int row = row0 + ai * HALF + m * 16; const size_t off = (size_t)row * DM + col0;
;                 float sq = 0.f;
; #pragma unroll
;                 for (int bj = 0; bj < 2; ++bj) {
;                     const h16x8 bs = *(const h16x8*)(h16 + off + bj * HALF);
;                     f32x4 o0 = acc[ai][bj][m][0] * pre, o1 = acc[ai][bj][m][1] * pre;
; #pragma unroll
;                     for (int e = 0; e < 4; ++e) { o0[e] += (float)bs[e]; o1[e] += (float)bs[4 + e]; }
;                     if (out32) { if (!dry) { __builtin_nontemporal_store(o0, (f32x4*)(out32 + off + bj * HALF)); __builtin_nontemporal_store(o1, (f32x4*)(out32 + off + bj * HALF + 4)); } }
;                     else if (!dry) {
;                         sq += (o0[0] * o0[0] + o0[1] * o0[1]) + (o0[2] * o0[2] + o0[3] * o0[3]) + (o1[0] * o1[0] + o1[1] * o1[1]) + (o1[2] * o1[2] + o1[3] * o1[3]);
;                         u32x4 w; w.x = pkh(o0[0], o0[1]); w.y = pkh(o0[2], o0[3]); w.z = pkh(o1[0], o1[1]); w.w = pkh(o1[2], o1[3]);
;                         *(u32x4*)(h16 + off + bj * HALF) = w;
;                         if (h8) { u32x2 q; q.x = pk8(o0[0] * F8_SA, o0[1] * F8_SA, o0[2] * F8_SA, o0[3] * F8_SA); q.y = pk8(o1[0] * F8_SA, o1[1] * F8_SA, o1[2] * F8_SA, o1[3] * F8_SA); *(u32x2*)(h8 + off + bj * HALF) = q; } }
;                 }
;                 if (!out32 && !dry) { sq += __shfl_xor(sq, 16); sq += __shfl_xor(sq, 32); if (fq == 0) atomicAdd(ss_out + row, sq); }
.LBB0_670:
	s_lshl_b32 s2, s45, 8
	v_mov_b32_e32 v146, v150
	v_mov_b32_e32 v170, v1
	s_add_i32 s2, s2, s36
	v_mov_b32_e32 v164, 0
	v_add_u32_e32 v148, s2, v146
	s_lshl_b32 s2, s44, 8
	s_or_b32 s2, s2, s37
	v_lshl_add_u32 v146, v170, 3, s2
	v_ashrrev_i32_e32 v149, 31, v148
	v_ashrrev_i32_e32 v147, 31, v146
	v_lshlrev_b64 v[156:157], 10, v[148:149]
	v_lshl_add_u64 v[160:161], v[156:157], 0, v[146:147]
	v_lshl_add_u64 v[162:163], v[160:161], 1, s[90:91]
	global_load_dwordx4 v[156:159], v[162:163], off
	v_mov_b32_e32 v165, 0
	v_lshl_add_u64 v[160:161], s[10:11], 0, v[160:161]
	v_cmp_eq_u32_e32 vcc, 0, v170
	s_waitcnt vmcnt(0)
	v_cvt_f32_f16_e32 v166, v156
	v_cvt_f32_f16_sdwa v167, v156 dst_sel:DWORD dst_unused:UNUSED_PAD src0_sel:WORD_1
	v_cvt_f32_f16_e32 v168, v158
	v_cvt_f32_f16_sdwa v169, v158 dst_sel:DWORD dst_unused:UNUSED_PAD src0_sel:WORD_1
	v_cvt_f32_f16_e32 v156, v157
	v_cvt_f32_f16_sdwa v157, v157 dst_sel:DWORD dst_unused:UNUSED_PAD src0_sel:WORD_1
	v_cvt_f32_f16_e32 v158, v159
	v_cvt_f32_f16_sdwa v159, v159 dst_sel:DWORD dst_unused:UNUSED_PAD src0_sel:WORD_1
	v_pk_add_f32 v[166:167], v[126:127], v[166:167]
	v_pk_add_f32 v[168:169], v[122:123], v[168:169]
	v_pk_add_f32 v[128:129], v[128:129], v[156:157]
	v_pk_add_f32 v[156:157], v[124:125], v[158:159]
	v_mul_f32_e32 v124, 0x41000000, v166
	v_mul_f32_e32 v125, 0x41000000, v167
	v_mul_f32_e32 v158, 0x41000000, v168
	v_mul_f32_e32 v159, 0x41000000, v169
	v_cvt_pk_fp8_f32 v164, v124, v125
	v_cvt_pk_fp8_f32 v165, v158, v159
	v_mul_f32_e32 v126, 0x41000000, v128
	v_mul_f32_e32 v127, 0x41000000, v129
	v_mul_f32_e32 v124, 0x41000000, v156
	v_mul_f32_e32 v125, 0x41000000, v157
	v_cvt_pk_fp8_f32 v164, v126, v127 op_sel:[0,0,1]
	v_cvt_pk_fp8_f32 v165, v124, v125 op_sel:[0,0,1]
	v_cvt_pk_f16_f32 v122, v166, v167
	v_cvt_pk_f16_f32 v123, v128, v129
	v_cvt_pk_f16_f32 v124, v168, v169
	v_cvt_pk_f16_f32 v125, v156, v157
	global_store_dwordx4 v[162:163], v[122:125], off sc1
	global_store_dwordx2 v[160:161], v[164:165], off
	global_load_dwordx4 v[124:127], v[162:163], off offset:256
	v_and_b32_e32 v123, 64, v155
	v_xor_b32_e32 v122, 16, v155
	v_add_u32_e32 v123, 64, v123
	v_xor_b32_e32 v164, 32, v155
	v_cmp_lt_i32_e64 s[2:3], v122, v123
	v_pk_mul_f32 v[128:129], v[128:129], v[128:129]
	v_pk_mul_f32 v[156:157], v[156:157], v[156:157]
	v_cndmask_b32_e64 v122, v155, v122, s[2:3]
	v_cmp_lt_i32_e64 s[2:3], v164, v123
	v_add_f32_e32 v128, v128, v129
	v_add_f32_e32 v156, v156, v157
	v_cndmask_b32_e64 v123, v155, v164, s[2:3]
	v_pk_mul_f32 v[164:165], v[166:167], v[166:167]
	v_pk_mul_f32 v[166:167], v[168:169], v[168:169]
	v_add_f32_e32 v129, v164, v165
	v_add_f32_e32 v164, v166, v167
	v_add_f32_e32 v128, v129, v128
	v_add_f32_e32 v128, v164, v128
	v_add_f32_e32 v166, v156, v128
	v_lshlrev_b32_e32 v122, 2, v122
	v_mov_b32_e32 v158, 0
	v_mov_b32_e32 v159, 0
	s_waitcnt vmcnt(0)
	v_cvt_f32_f16_e32 v128, v124
	v_cvt_f32_f16_sdwa v129, v124 dst_sel:DWORD dst_unused:UNUSED_PAD src0_sel:WORD_1
	v_cvt_f32_f16_e32 v156, v126
	v_cvt_f32_f16_sdwa v157, v126 dst_sel:DWORD dst_unused:UNUSED_PAD src0_sel:WORD_1
	v_cvt_f32_f16_e32 v124, v125
	v_cvt_f32_f16_sdwa v125, v125 dst_sel:DWORD dst_unused:UNUSED_PAD src0_sel:WORD_1
	v_cvt_f32_f16_e32 v126, v127
	v_cvt_f32_f16_sdwa v127, v127 dst_sel:DWORD dst_unused:UNUSED_PAD src0_sel:WORD_1
	v_pk_add_f32 v[128:129], v[118:119], v[128:129]
	v_pk_add_f32 v[156:157], v[114:115], v[156:157]
	v_pk_add_f32 v[114:115], v[120:121], v[124:125]
	v_pk_add_f32 v[124:125], v[116:117], v[126:127]
	v_pk_mul_f32 v[116:117], v[128:129], v[128:129]
	v_pk_mul_f32 v[120:121], v[114:115], v[114:115]
	v_pk_mul_f32 v[126:127], v[156:157], v[156:157]
	v_add_f32_e32 v120, v120, v121
	v_add_f32_e32 v116, v116, v117
	v_pk_mul_f32 v[164:165], v[124:125], v[124:125]
	v_add_f32_e32 v117, v126, v127
	v_add_f32_e32 v116, v116, v120
	v_add_f32_e32 v121, v164, v165
	v_add_f32_e32 v116, v117, v116
	v_add_f32_e32 v116, v121, v116
	v_add_f32_e32 v116, v166, v116
	v_cvt_pk_f16_f32 v118, v128, v129
	v_mul_f32_e32 v128, 0x41000000, v128
	v_mul_f32_e32 v129, 0x41000000, v129
	ds_bpermute_b32 v117, v122, v116
	v_cvt_pk_fp8_f32 v158, v128, v129
	v_mul_f32_e32 v167, 0x41000000, v156
	v_mul_f32_e32 v168, 0x41000000, v157
	v_cvt_pk_f16_f32 v119, v114, v115
	v_mul_f32_e32 v114, 0x41000000, v114
	v_mul_f32_e32 v115, 0x41000000, v115
	v_cvt_pk_fp8_f32 v159, v167, v168
	v_cvt_pk_fp8_f32 v158, v114, v115 op_sel:[0,0,1]
	s_waitcnt lgkmcnt(0)
	v_add_f32_e32 v114, v116, v117
	v_lshlrev_b32_e32 v116, 2, v123
	ds_bpermute_b32 v115, v116, v114
	v_mul_f32_e32 v120, 0x41000000, v124
	v_mul_f32_e32 v121, 0x41000000, v125
	v_cvt_pk_fp8_f32 v159, v120, v121 op_sel:[0,0,1]
	v_cvt_pk_f16_f32 v120, v156, v157
	v_cvt_pk_f16_f32 v121, v124, v125
	global_store_dwordx4 v[162:163], v[118:121], off offset:256 sc1
	global_store_dwordx2 v[160:161], v[158:159], off offset:128
	s_and_saveexec_b64 s[2:3], vcc
	s_cbranch_execz .LBB0_672
	v_lshl_add_u64 v[118:119], v[148:149], 2, s[4:5]
	s_waitcnt lgkmcnt(0)
	v_add_f32_e32 v114, v114, v115
	global_atomic_add_f32 v[118:119], v114, off
; __device__ __forceinline__ unsigned pkh(float lo, float hi) { f32x2 v = {lo, hi}; h16x2 h = __builtin_convertvector(v, h16x2); return __builtin_bit_cast(unsigned, h); }
; __device__ __forceinline__ unsigned pk8(float a, float b, float c, float d) { int w = __builtin_amdgcn_cvt_pk_fp8_f32(a, b, 0, false); w = __builtin_amdgcn_cvt_pk_fp8_f32(c, d, w, true); return (unsigned)w; }
;     __device__ __forceinline__ void operator()(f32x4 (&acc)[2][2][4][2], const Unit& u, const Order& S, int wr, int wc, int fr_, int fq_, LAS unsigned char*, int) const {
;     ...
;                 const int row = row0 + ai * HALF + m * 16; const size_t off = (size_t)row * DM + col0;
;                 float sq = 0.f;
; #pragma unroll
;                 for (int bj = 0; bj < 2; ++bj) {
;                     const h16x8 bs = *(const h16x8*)(h16 + off + bj * HALF);
;                     f32x4 o0 = acc[ai][bj][m][0] * pre, o1 = acc[ai][bj][m][1] * pre;
; #pragma unroll
;                     for (int e = 0; e < 4; ++e) { o0[e] += (float)bs[e]; o1[e] += (float)bs[4 + e]; }
;                     if (out32) { if (!dry) { __builtin_nontemporal_store(o0, (f32x4*)(out32 + off + bj * HALF)); __builtin_nontemporal_store(o1, (f32x4*)(out32 + off + bj * HALF + 4)); } }
;                     else if (!dry) {
;                         sq += (o0[0] * o0[0] + o0[1] * o0[1]) + (o0[2] * o0[2] + o0[3] * o0[3]) + (o1[0] * o1[0] + o1[1] * o1[1]) + (o1[2] * o1[2] + o1[3] * o1[3]);
;                         u32x4 w; w.x = pkh(o0[0], o0[1]); w.y = pkh(o0[2], o0[3]); w.z = pkh(o1[0], o1[1]); w.w = pkh(o1[2], o1[3]);
;                         *(u32x4*)(h16 + off + bj * HALF) = w;
;                         if (h8) { u32x2 q; q.x = pk8(o0[0] * F8_SA, o0[1] * F8_SA, o0[2] * F8_SA, o0[3] * F8_SA); q.y = pk8(o1[0] * F8_SA, o1[1] * F8_SA, o1[2] * F8_SA, o1[3] * F8_SA); *(u32x2*)(h8 + off + bj * HALF) = q; } }
;                 }
;                 if (!out32 && !dry) { sq += __shfl_xor(sq, 16); sq += __shfl_xor(sq, 32); if (fq == 0) atomicAdd(ss_out + row, sq); }
.LBB0_672:
	s_or_b64 exec, exec, s[2:3]
	v_add_u32_e32 v114, 16, v148
	s_waitcnt lgkmcnt(0)
	v_ashrrev_i32_e32 v115, 31, v114
	v_lshlrev_b64 v[118:119], 10, v[114:115]
	v_lshl_add_u64 v[124:125], v[118:119], 0, v[146:147]
	v_lshl_add_u64 v[126:127], v[124:125], 1, s[90:91]
	global_load_dwordx4 v[118:121], v[126:127], off
	v_mov_b32_e32 v128, 0
	v_mov_b32_e32 v129, 0
	v_lshl_add_u64 v[124:125], s[10:11], 0, v[124:125]
	s_waitcnt vmcnt(0)
	v_cvt_f32_f16_e32 v156, v118
	v_cvt_f32_f16_sdwa v157, v118 dst_sel:DWORD dst_unused:UNUSED_PAD src0_sel:WORD_1
	v_cvt_f32_f16_e32 v158, v120
	v_cvt_f32_f16_sdwa v159, v120 dst_sel:DWORD dst_unused:UNUSED_PAD src0_sel:WORD_1
	v_cvt_f32_f16_e32 v118, v119
	v_cvt_f32_f16_sdwa v119, v119 dst_sel:DWORD dst_unused:UNUSED_PAD src0_sel:WORD_1
	v_cvt_f32_f16_e32 v120, v121
	v_cvt_f32_f16_sdwa v121, v121 dst_sel:DWORD dst_unused:UNUSED_PAD src0_sel:WORD_1
	v_pk_add_f32 v[110:111], v[110:111], v[156:157]
	v_pk_add_f32 v[156:157], v[106:107], v[158:159]
	v_pk_add_f32 v[112:113], v[112:113], v[118:119]
	v_pk_add_f32 v[118:119], v[108:109], v[120:121]
	v_mul_f32_e32 v108, 0x41000000, v110
	v_mul_f32_e32 v109, 0x41000000, v111
	v_mul_f32_e32 v121, 0x41000000, v156
	v_mul_f32_e32 v123, 0x41000000, v157
	v_cvt_pk_fp8_f32 v128, v108, v109
	v_cvt_pk_fp8_f32 v129, v121, v123
	v_mul_f32_e32 v117, 0x41000000, v112
	v_mul_f32_e32 v120, 0x41000000, v113
	v_mul_f32_e32 v108, 0x41000000, v118
	v_mul_f32_e32 v109, 0x41000000, v119
	v_cvt_pk_fp8_f32 v128, v117, v120 op_sel:[0,0,1]
	v_cvt_pk_fp8_f32 v129, v108, v109 op_sel:[0,0,1]
	v_cvt_pk_f16_f32 v106, v110, v111
	v_cvt_pk_f16_f32 v107, v112, v113
	v_cvt_pk_f16_f32 v108, v156, v157
	v_cvt_pk_f16_f32 v109, v118, v119
	global_store_dwordx4 v[126:127], v[106:109], off sc1
	global_store_dwordx2 v[124:125], v[128:129], off
	global_load_dwordx4 v[106:109], v[126:127], off offset:256
	v_pk_mul_f32 v[110:111], v[110:111], v[110:111]
	v_pk_mul_f32 v[112:113], v[112:113], v[112:113]
	v_pk_mul_f32 v[128:129], v[156:157], v[156:157]
	v_add_f32_e32 v112, v112, v113
	v_add_f32_e32 v110, v110, v111
	v_pk_mul_f32 v[118:119], v[118:119], v[118:119]
	v_add_f32_e32 v111, v128, v129
	v_add_f32_e32 v110, v110, v112
	v_add_f32_e32 v113, v118, v119
	v_add_f32_e32 v110, v111, v110
	v_add_f32_e32 v117, v113, v110
	v_mov_b32_e32 v120, 0
	v_mov_b32_e32 v121, 0
	s_waitcnt vmcnt(0)
	v_cvt_f32_f16_e32 v110, v106
	v_cvt_f32_f16_sdwa v111, v106 dst_sel:DWORD dst_unused:UNUSED_PAD src0_sel:WORD_1
	v_cvt_f32_f16_e32 v112, v108
	v_cvt_f32_f16_sdwa v113, v108 dst_sel:DWORD dst_unused:UNUSED_PAD src0_sel:WORD_1
	v_cvt_f32_f16_e32 v106, v107
	v_cvt_f32_f16_sdwa v107, v107 dst_sel:DWORD dst_unused:UNUSED_PAD src0_sel:WORD_1
	v_cvt_f32_f16_e32 v108, v109
	v_cvt_f32_f16_sdwa v109, v109 dst_sel:DWORD dst_unused:UNUSED_PAD src0_sel:WORD_1
	v_pk_add_f32 v[102:103], v[102:103], v[110:111]
	v_pk_add_f32 v[110:111], v[98:99], v[112:113]
	v_pk_add_f32 v[98:99], v[104:105], v[106:107]
	v_pk_add_f32 v[104:105], v[100:101], v[108:109]
	v_pk_mul_f32 v[106:107], v[102:103], v[102:103]
	v_pk_mul_f32 v[108:109], v[98:99], v[98:99]
	v_pk_mul_f32 v[112:113], v[110:111], v[110:111]
	v_cvt_pk_f16_f32 v100, v102, v103
	v_mul_f32_e32 v102, 0x41000000, v102
	v_mul_f32_e32 v103, 0x41000000, v103
	v_add_f32_e32 v108, v108, v109
	v_add_f32_e32 v106, v106, v107
	v_pk_mul_f32 v[118:119], v[104:105], v[104:105]
	v_add_f32_e32 v107, v112, v113
	v_cvt_pk_fp8_f32 v120, v102, v103
	v_add_f32_e32 v102, v106, v108
	v_add_f32_e32 v109, v118, v119
	v_add_f32_e32 v102, v107, v102
	v_add_f32_e32 v102, v109, v102
	v_add_f32_e32 v102, v117, v102
	v_mul_f32_e32 v123, 0x41000000, v110
	v_mul_f32_e32 v128, 0x41000000, v111
	ds_bpermute_b32 v103, v122, v102
	v_cvt_pk_fp8_f32 v121, v123, v128
	v_cvt_pk_f16_f32 v101, v98, v99
	v_mul_f32_e32 v98, 0x41000000, v98
	v_mul_f32_e32 v99, 0x41000000, v99
	v_cvt_pk_fp8_f32 v120, v98, v99 op_sel:[0,0,1]
	v_mul_f32_e32 v98, 0x41000000, v104
	v_mul_f32_e32 v99, 0x41000000, v105
	v_cvt_pk_fp8_f32 v121, v98, v99 op_sel:[0,0,1]
	s_waitcnt lgkmcnt(0)
	v_add_f32_e32 v98, v102, v103
	ds_bpermute_b32 v99, v116, v98
	v_cvt_pk_f16_f32 v102, v110, v111
	v_cvt_pk_f16_f32 v103, v104, v105
	global_store_dwordx4 v[126:127], v[100:103], off offset:256 sc1
	global_store_dwordx2 v[124:125], v[120:121], off offset:128
	s_and_saveexec_b64 s[2:3], vcc
	s_cbranch_execz .LBB0_674
	v_lshl_add_u64 v[100:101], v[114:115], 2, s[4:5]
	s_waitcnt lgkmcnt(0)
	v_add_f32_e32 v98, v98, v99
	global_atomic_add_f32 v[100:101], v98, off
; __device__ __forceinline__ unsigned pkh(float lo, float hi) { f32x2 v = {lo, hi}; h16x2 h = __builtin_convertvector(v, h16x2); return __builtin_bit_cast(unsigned, h); }
; __device__ __forceinline__ unsigned pk8(float a, float b, float c, float d) { int w = __builtin_amdgcn_cvt_pk_fp8_f32(a, b, 0, false); w = __builtin_amdgcn_cvt_pk_fp8_f32(c, d, w, true); return (unsigned)w; }
;     __device__ __forceinline__ void operator()(f32x4 (&acc)[2][2][4][2], const Unit& u, const Order& S, int wr, int wc, int fr_, int fq_, LAS unsigned char*, int) const {
;     ...
;                 const int row = row0 + ai * HALF + m * 16; const size_t off = (size_t)row * DM + col0;
;                 float sq = 0.f;
; #pragma unroll
;                 for (int bj = 0; bj < 2; ++bj) {
;                     const h16x8 bs = *(const h16x8*)(h16 + off + bj * HALF);
;                     f32x4 o0 = acc[ai][bj][m][0] * pre, o1 = acc[ai][bj][m][1] * pre;
; #pragma unroll
;                     for (int e = 0; e < 4; ++e) { o0[e] += (float)bs[e]; o1[e] += (float)bs[4 + e]; }
;                     if (out32) { if (!dry) { __builtin_nontemporal_store(o0, (f32x4*)(out32 + off + bj * HALF)); __builtin_nontemporal_store(o1, (f32x4*)(out32 + off + bj * HALF + 4)); } }
;                     else if (!dry) {
;                         sq += (o0[0] * o0[0] + o0[1] * o0[1]) + (o0[2] * o0[2] + o0[3] * o0[3]) + (o1[0] * o1[0] + o1[1] * o1[1]) + (o1[2] * o1[2] + o1[3] * o1[3]);
;                         u32x4 w; w.x = pkh(o0[0], o0[1]); w.y = pkh(o0[2], o0[3]); w.z = pkh(o1[0], o1[1]); w.w = pkh(o1[2], o1[3]);
;                         *(u32x4*)(h16 + off + bj * HALF) = w;
;                         if (h8) { u32x2 q; q.x = pk8(o0[0] * F8_SA, o0[1] * F8_SA, o0[2] * F8_SA, o0[3] * F8_SA); q.y = pk8(o1[0] * F8_SA, o1[1] * F8_SA, o1[2] * F8_SA, o1[3] * F8_SA); *(u32x2*)(h8 + off + bj * HALF) = q; } }
;                 }
;                 if (!out32 && !dry) { sq += __shfl_xor(sq, 16); sq += __shfl_xor(sq, 32); if (fq == 0) atomicAdd(ss_out + row, sq); }
.LBB0_674:
	s_or_b64 exec, exec, s[2:3]
	v_add_u32_e32 v98, 32, v148
	s_waitcnt lgkmcnt(0)
	v_ashrrev_i32_e32 v99, 31, v98
	v_lshlrev_b64 v[100:101], 10, v[98:99]
	v_lshl_add_u64 v[104:105], v[100:101], 0, v[146:147]
	v_lshl_add_u64 v[106:107], v[104:105], 1, s[90:91]
	global_load_dwordx4 v[100:103], v[106:107], off
	v_mov_b32_e32 v108, 0
	v_mov_b32_e32 v109, 0
	v_lshl_add_u64 v[104:105], s[10:11], 0, v[104:105]
	s_waitcnt vmcnt(0)
	v_cvt_f32_f16_e32 v110, v100
	v_cvt_f32_f16_sdwa v111, v100 dst_sel:DWORD dst_unused:UNUSED_PAD src0_sel:WORD_1
	v_cvt_f32_f16_e32 v112, v102
	v_cvt_f32_f16_sdwa v113, v102 dst_sel:DWORD dst_unused:UNUSED_PAD src0_sel:WORD_1
	v_cvt_f32_f16_e32 v100, v101
	v_cvt_f32_f16_sdwa v101, v101 dst_sel:DWORD dst_unused:UNUSED_PAD src0_sel:WORD_1
	v_cvt_f32_f16_e32 v102, v103
	v_cvt_f32_f16_sdwa v103, v103 dst_sel:DWORD dst_unused:UNUSED_PAD src0_sel:WORD_1
	v_pk_add_f32 v[94:95], v[94:95], v[110:111]
	v_pk_add_f32 v[110:111], v[90:91], v[112:113]
	v_pk_add_f32 v[96:97], v[96:97], v[100:101]
	v_pk_add_f32 v[100:101], v[92:93], v[102:103]
	v_mul_f32_e32 v92, 0x41000000, v94
	v_mul_f32_e32 v93, 0x41000000, v95
	v_mul_f32_e32 v112, 0x41000000, v110
	v_mul_f32_e32 v113, 0x41000000, v111
	v_cvt_pk_fp8_f32 v108, v92, v93
	v_cvt_pk_fp8_f32 v109, v112, v113
	v_mul_f32_e32 v102, 0x41000000, v96
	v_mul_f32_e32 v103, 0x41000000, v97
	v_mul_f32_e32 v92, 0x41000000, v100
	v_mul_f32_e32 v93, 0x41000000, v101
	v_cvt_pk_fp8_f32 v108, v102, v103 op_sel:[0,0,1]
	v_cvt_pk_fp8_f32 v109, v92, v93 op_sel:[0,0,1]
	v_cvt_pk_f16_f32 v90, v94, v95
	v_cvt_pk_f16_f32 v91, v96, v97
	v_cvt_pk_f16_f32 v92, v110, v111
	v_cvt_pk_f16_f32 v93, v100, v101
	global_store_dwordx4 v[106:107], v[90:93], off sc1
	global_store_dwordx2 v[104:105], v[108:109], off
	global_load_dwordx4 v[90:93], v[106:107], off offset:256
	v_pk_mul_f32 v[94:95], v[94:95], v[94:95]
	v_pk_mul_f32 v[96:97], v[96:97], v[96:97]
	v_pk_mul_f32 v[108:109], v[110:111], v[110:111]
	v_add_f32_e32 v96, v96, v97
	v_add_f32_e32 v94, v94, v95
	v_pk_mul_f32 v[100:101], v[100:101], v[100:101]
	v_add_f32_e32 v95, v108, v109
	v_add_f32_e32 v94, v94, v96
	v_add_f32_e32 v97, v100, v101
	v_add_f32_e32 v94, v95, v94
	v_add_f32_e32 v108, v97, v94
	v_mov_b32_e32 v102, 0
	v_mov_b32_e32 v103, 0
	s_waitcnt vmcnt(0)
	v_cvt_f32_f16_e32 v94, v90
	v_cvt_f32_f16_sdwa v95, v90 dst_sel:DWORD dst_unused:UNUSED_PAD src0_sel:WORD_1
	v_cvt_f32_f16_e32 v96, v92
	v_cvt_f32_f16_sdwa v97, v92 dst_sel:DWORD dst_unused:UNUSED_PAD src0_sel:WORD_1
	v_cvt_f32_f16_e32 v90, v91
	v_cvt_f32_f16_sdwa v91, v91 dst_sel:DWORD dst_unused:UNUSED_PAD src0_sel:WORD_1
	v_cvt_f32_f16_e32 v92, v93
	v_cvt_f32_f16_sdwa v93, v93 dst_sel:DWORD dst_unused:UNUSED_PAD src0_sel:WORD_1
	v_pk_add_f32 v[86:87], v[86:87], v[94:95]
	v_pk_add_f32 v[94:95], v[82:83], v[96:97]
	v_pk_add_f32 v[82:83], v[88:89], v[90:91]
	v_pk_add_f32 v[88:89], v[84:85], v[92:93]
	v_pk_mul_f32 v[90:91], v[86:87], v[86:87]
	v_pk_mul_f32 v[92:93], v[82:83], v[82:83]
	v_pk_mul_f32 v[96:97], v[94:95], v[94:95]
	v_cvt_pk_f16_f32 v84, v86, v87
	v_mul_f32_e32 v86, 0x41000000, v86
	v_mul_f32_e32 v87, 0x41000000, v87
	v_add_f32_e32 v92, v92, v93
	v_add_f32_e32 v90, v90, v91
	v_pk_mul_f32 v[100:101], v[88:89], v[88:89]
	v_add_f32_e32 v91, v96, v97
	v_cvt_pk_fp8_f32 v102, v86, v87
	v_add_f32_e32 v86, v90, v92
	v_add_f32_e32 v93, v100, v101
	v_add_f32_e32 v86, v91, v86
	v_add_f32_e32 v86, v93, v86
	v_add_f32_e32 v86, v108, v86
	v_mul_f32_e32 v109, 0x41000000, v94
	v_mul_f32_e32 v110, 0x41000000, v95
	ds_bpermute_b32 v87, v122, v86
	v_cvt_pk_fp8_f32 v103, v109, v110
	v_cvt_pk_f16_f32 v85, v82, v83
	v_mul_f32_e32 v82, 0x41000000, v82
	v_mul_f32_e32 v83, 0x41000000, v83
	v_cvt_pk_fp8_f32 v102, v82, v83 op_sel:[0,0,1]
	v_mul_f32_e32 v82, 0x41000000, v88
	v_mul_f32_e32 v83, 0x41000000, v89
	v_cvt_pk_fp8_f32 v103, v82, v83 op_sel:[0,0,1]
	s_waitcnt lgkmcnt(0)
	v_add_f32_e32 v82, v86, v87
	ds_bpermute_b32 v83, v116, v82
	v_cvt_pk_f16_f32 v86, v94, v95
	v_cvt_pk_f16_f32 v87, v88, v89
	global_store_dwordx4 v[106:107], v[84:87], off offset:256 sc1
	global_store_dwordx2 v[104:105], v[102:103], off offset:128
	s_and_saveexec_b64 s[2:3], vcc
	s_cbranch_execz .LBB0_676
	v_lshl_add_u64 v[84:85], v[98:99], 2, s[4:5]
	s_waitcnt lgkmcnt(0)
	v_add_f32_e32 v82, v82, v83
	global_atomic_add_f32 v[84:85], v82, off
; __device__ __forceinline__ unsigned pkh(float lo, float hi) { f32x2 v = {lo, hi}; h16x2 h = __builtin_convertvector(v, h16x2); return __builtin_bit_cast(unsigned, h); }
; __device__ __forceinline__ unsigned pk8(float a, float b, float c, float d) { int w = __builtin_amdgcn_cvt_pk_fp8_f32(a, b, 0, false); w = __builtin_amdgcn_cvt_pk_fp8_f32(c, d, w, true); return (unsigned)w; }
;     __device__ __forceinline__ void operator()(f32x4 (&acc)[2][2][4][2], const Unit& u, const Order& S, int wr, int wc, int fr_, int fq_, LAS unsigned char*, int) const {
;     ...
;         for (int ai = 0; ai < 2; ++ai)
; #pragma unroll
;             for (int m = 0; m < 4; ++m) {
;                 const int row = row0 + ai * HALF + m * 16; const size_t off = (size_t)row * DM + col0;
;                 float sq = 0.f;
; #pragma unroll
;                 for (int bj = 0; bj < 2; ++bj) {
;                     const h16x8 bs = *(const h16x8*)(h16 + off + bj * HALF);
;                     f32x4 o0 = acc[ai][bj][m][0] * pre, o1 = acc[ai][bj][m][1] * pre;
; #pragma unroll
;                     for (int e = 0; e < 4; ++e) { o0[e] += (float)bs[e]; o1[e] += (float)bs[4 + e]; }
;                     if (out32) { if (!dry) { __builtin_nontemporal_store(o0, (f32x4*)(out32 + off + bj * HALF)); __builtin_nontemporal_store(o1, (f32x4*)(out32 + off + bj * HALF + 4)); } }
;                     else if (!dry) {
;                         sq += (o0[0] * o0[0] + o0[1] * o0[1]) + (o0[2] * o0[2] + o0[3] * o0[3]) + (o1[0] * o1[0] + o1[1] * o1[1]) + (o1[2] * o1[2] + o1[3] * o1[3]);
;                         u32x4 w; w.x = pkh(o0[0], o0[1]); w.y = pkh(o0[2], o0[3]); w.z = pkh(o1[0], o1[1]); w.w = pkh(o1[2], o1[3]);
;                         *(u32x4*)(h16 + off + bj * HALF) = w;
;                         if (h8) { u32x2 q; q.x = pk8(o0[0] * F8_SA, o0[1] * F8_SA, o0[2] * F8_SA, o0[3] * F8_SA); q.y = pk8(o1[0] * F8_SA, o1[1] * F8_SA, o1[2] * F8_SA, o1[3] * F8_SA); *(u32x2*)(h8 + off + bj * HALF) = q; } }
;                 }
;                 if (!out32 && !dry) { sq += __shfl_xor(sq, 16); sq += __shfl_xor(sq, 32); if (fq == 0) atomicAdd(ss_out + row, sq); }
.LBB0_676:
	s_or_b64 exec, exec, s[2:3]
	v_add_u32_e32 v82, 48, v148
	s_waitcnt lgkmcnt(0)
	v_ashrrev_i32_e32 v83, 31, v82
	v_lshlrev_b64 v[84:85], 10, v[82:83]
	v_lshl_add_u64 v[88:89], v[84:85], 0, v[146:147]
	v_lshl_add_u64 v[90:91], v[88:89], 1, s[90:91]
	global_load_dwordx4 v[84:87], v[90:91], off
	v_mov_b32_e32 v92, 0
	v_mov_b32_e32 v93, 0
	v_lshl_add_u64 v[88:89], s[10:11], 0, v[88:89]
	s_waitcnt vmcnt(0)
	v_cvt_f32_f16_e32 v94, v84
	v_cvt_f32_f16_sdwa v95, v84 dst_sel:DWORD dst_unused:UNUSED_PAD src0_sel:WORD_1
	v_cvt_f32_f16_e32 v96, v86
	v_cvt_f32_f16_sdwa v97, v86 dst_sel:DWORD dst_unused:UNUSED_PAD src0_sel:WORD_1
	v_cvt_f32_f16_e32 v84, v85
	v_cvt_f32_f16_sdwa v85, v85 dst_sel:DWORD dst_unused:UNUSED_PAD src0_sel:WORD_1
	v_cvt_f32_f16_e32 v86, v87
	v_cvt_f32_f16_sdwa v87, v87 dst_sel:DWORD dst_unused:UNUSED_PAD src0_sel:WORD_1
	v_pk_add_f32 v[78:79], v[78:79], v[94:95]
	v_pk_add_f32 v[94:95], v[74:75], v[96:97]
	v_pk_add_f32 v[80:81], v[80:81], v[84:85]
	v_pk_add_f32 v[84:85], v[76:77], v[86:87]
	v_mul_f32_e32 v76, 0x41000000, v78
	v_mul_f32_e32 v77, 0x41000000, v79
	v_mul_f32_e32 v96, 0x41000000, v94
	v_mul_f32_e32 v97, 0x41000000, v95
	v_cvt_pk_fp8_f32 v92, v76, v77
	v_cvt_pk_fp8_f32 v93, v96, v97
	v_mul_f32_e32 v86, 0x41000000, v80
	v_mul_f32_e32 v87, 0x41000000, v81
	v_mul_f32_e32 v76, 0x41000000, v84
	v_mul_f32_e32 v77, 0x41000000, v85
	v_cvt_pk_fp8_f32 v92, v86, v87 op_sel:[0,0,1]
	v_cvt_pk_fp8_f32 v93, v76, v77 op_sel:[0,0,1]
	v_cvt_pk_f16_f32 v74, v78, v79
	v_cvt_pk_f16_f32 v75, v80, v81
	v_cvt_pk_f16_f32 v76, v94, v95
	v_cvt_pk_f16_f32 v77, v84, v85
	global_store_dwordx4 v[90:91], v[74:77], off sc1
	global_store_dwordx2 v[88:89], v[92:93], off
	global_load_dwordx4 v[74:77], v[90:91], off offset:256
	v_pk_mul_f32 v[78:79], v[78:79], v[78:79]
	v_pk_mul_f32 v[80:81], v[80:81], v[80:81]
	v_pk_mul_f32 v[92:93], v[94:95], v[94:95]
	v_add_f32_e32 v80, v80, v81
	v_add_f32_e32 v78, v78, v79
	v_pk_mul_f32 v[84:85], v[84:85], v[84:85]
	v_add_f32_e32 v79, v92, v93
	v_add_f32_e32 v78, v78, v80
	v_add_f32_e32 v81, v84, v85
	v_add_f32_e32 v78, v79, v78
	v_add_f32_e32 v92, v81, v78
	v_mov_b32_e32 v86, 0
	v_mov_b32_e32 v87, 0
	s_waitcnt vmcnt(0)
	v_cvt_f32_f16_e32 v78, v74
	v_cvt_f32_f16_sdwa v79, v74 dst_sel:DWORD dst_unused:UNUSED_PAD src0_sel:WORD_1
	v_cvt_f32_f16_e32 v80, v76
	v_cvt_f32_f16_sdwa v81, v76 dst_sel:DWORD dst_unused:UNUSED_PAD src0_sel:WORD_1
	v_cvt_f32_f16_e32 v74, v75
	v_cvt_f32_f16_sdwa v75, v75 dst_sel:DWORD dst_unused:UNUSED_PAD src0_sel:WORD_1
	v_cvt_f32_f16_e32 v76, v77
	v_cvt_f32_f16_sdwa v77, v77 dst_sel:DWORD dst_unused:UNUSED_PAD src0_sel:WORD_1
	v_pk_add_f32 v[70:71], v[70:71], v[78:79]
	v_pk_add_f32 v[78:79], v[66:67], v[80:81]
	v_pk_add_f32 v[66:67], v[72:73], v[74:75]
	v_pk_add_f32 v[72:73], v[68:69], v[76:77]
	v_pk_mul_f32 v[74:75], v[70:71], v[70:71]
	v_pk_mul_f32 v[76:77], v[66:67], v[66:67]
	v_pk_mul_f32 v[80:81], v[78:79], v[78:79]
	v_cvt_pk_f16_f32 v68, v70, v71
	v_mul_f32_e32 v70, 0x41000000, v70
	v_mul_f32_e32 v71, 0x41000000, v71
	v_add_f32_e32 v76, v76, v77
	v_add_f32_e32 v74, v74, v75
	v_pk_mul_f32 v[84:85], v[72:73], v[72:73]
	v_add_f32_e32 v75, v80, v81
	v_cvt_pk_fp8_f32 v86, v70, v71
	v_add_f32_e32 v70, v74, v76
	v_add_f32_e32 v77, v84, v85
	v_add_f32_e32 v70, v75, v70
	v_add_f32_e32 v70, v77, v70
	v_add_f32_e32 v70, v92, v70
	v_mul_f32_e32 v93, 0x41000000, v78
	v_mul_f32_e32 v94, 0x41000000, v79
	ds_bpermute_b32 v71, v122, v70
	v_cvt_pk_fp8_f32 v87, v93, v94
	v_cvt_pk_f16_f32 v69, v66, v67
	v_mul_f32_e32 v66, 0x41000000, v66
	v_mul_f32_e32 v67, 0x41000000, v67
	v_cvt_pk_fp8_f32 v86, v66, v67 op_sel:[0,0,1]
	v_mul_f32_e32 v66, 0x41000000, v72
	v_mul_f32_e32 v67, 0x41000000, v73
	v_cvt_pk_fp8_f32 v87, v66, v67 op_sel:[0,0,1]
	s_waitcnt lgkmcnt(0)
	v_add_f32_e32 v66, v70, v71
	ds_bpermute_b32 v67, v116, v66
	v_cvt_pk_f16_f32 v70, v78, v79
	v_cvt_pk_f16_f32 v71, v72, v73
	global_store_dwordx4 v[90:91], v[68:71], off offset:256 sc1
	global_store_dwordx2 v[88:89], v[86:87], off offset:128
	s_and_saveexec_b64 s[2:3], vcc
	s_cbranch_execz .LBB0_678
	v_lshl_add_u64 v[68:69], v[82:83], 2, s[4:5]
	s_waitcnt lgkmcnt(0)
	v_add_f32_e32 v66, v66, v67
	global_atomic_add_f32 v[68:69], v66, off
.LBB0_678:
	s_or_b64 exec, exec, s[2:3]
	v_add_u32_e32 v66, 0x80, v148
	s_waitcnt lgkmcnt(0)
	v_ashrrev_i32_e32 v67, 31, v66
	v_lshlrev_b64 v[68:69], 10, v[66:67]
	v_lshl_add_u64 v[72:73], v[68:69], 0, v[146:147]
	v_lshl_add_u64 v[74:75], v[72:73], 1, s[90:91]
	global_load_dwordx4 v[68:71], v[74:75], off
	v_mov_b32_e32 v76, 0
	v_mov_b32_e32 v77, 0
	v_lshl_add_u64 v[72:73], s[10:11], 0, v[72:73]
	s_waitcnt vmcnt(0)
	v_cvt_f32_f16_e32 v78, v68
	v_cvt_f32_f16_sdwa v79, v68 dst_sel:DWORD dst_unused:UNUSED_PAD src0_sel:WORD_1
	v_cvt_f32_f16_e32 v80, v70
	v_cvt_f32_f16_sdwa v81, v70 dst_sel:DWORD dst_unused:UNUSED_PAD src0_sel:WORD_1
	v_cvt_f32_f16_e32 v68, v69
	v_cvt_f32_f16_sdwa v69, v69 dst_sel:DWORD dst_unused:UNUSED_PAD src0_sel:WORD_1
	v_cvt_f32_f16_e32 v70, v71
	v_cvt_f32_f16_sdwa v71, v71 dst_sel:DWORD dst_unused:UNUSED_PAD src0_sel:WORD_1
	v_pk_add_f32 v[62:63], v[62:63], v[78:79]
	v_pk_add_f32 v[78:79], v[58:59], v[80:81]
	v_pk_add_f32 v[64:65], v[64:65], v[68:69]
	v_pk_add_f32 v[68:69], v[60:61], v[70:71]
	v_mul_f32_e32 v60, 0x41000000, v62
	v_mul_f32_e32 v61, 0x41000000, v63
	v_mul_f32_e32 v80, 0x41000000, v78
	v_mul_f32_e32 v81, 0x41000000, v79
	v_cvt_pk_fp8_f32 v76, v60, v61
	v_cvt_pk_fp8_f32 v77, v80, v81
	v_mul_f32_e32 v70, 0x41000000, v64
	v_mul_f32_e32 v71, 0x41000000, v65
	v_mul_f32_e32 v60, 0x41000000, v68
	v_mul_f32_e32 v61, 0x41000000, v69
	v_cvt_pk_fp8_f32 v76, v70, v71 op_sel:[0,0,1]
	v_cvt_pk_fp8_f32 v77, v60, v61 op_sel:[0,0,1]
	v_cvt_pk_f16_f32 v58, v62, v63
	v_cvt_pk_f16_f32 v59, v64, v65
	v_cvt_pk_f16_f32 v60, v78, v79
	v_cvt_pk_f16_f32 v61, v68, v69
	global_store_dwordx4 v[74:75], v[58:61], off sc1
	global_store_dwordx2 v[72:73], v[76:77], off
	global_load_dwordx4 v[58:61], v[74:75], off offset:256
	v_pk_mul_f32 v[62:63], v[62:63], v[62:63]
	v_pk_mul_f32 v[64:65], v[64:65], v[64:65]
	v_pk_mul_f32 v[76:77], v[78:79], v[78:79]
	v_add_f32_e32 v64, v64, v65
	v_add_f32_e32 v62, v62, v63
	v_pk_mul_f32 v[68:69], v[68:69], v[68:69]
	v_add_f32_e32 v63, v76, v77
	v_add_f32_e32 v62, v62, v64
	v_add_f32_e32 v65, v68, v69
	v_add_f32_e32 v62, v63, v62
	v_add_f32_e32 v76, v65, v62
	v_mov_b32_e32 v70, 0
	v_mov_b32_e32 v71, 0
	s_waitcnt vmcnt(0)
; __device__ __forceinline__ unsigned pkh(float lo, float hi) { f32x2 v = {lo, hi}; h16x2 h = __builtin_convertvector(v, h16x2); return __builtin_bit_cast(unsigned, h); }
; __device__ __forceinline__ unsigned pk8(float a, float b, float c, float d) { int w = __builtin_amdgcn_cvt_pk_fp8_f32(a, b, 0, false); w = __builtin_amdgcn_cvt_pk_fp8_f32(c, d, w, true); return (unsigned)w; }
;     __device__ __forceinline__ void operator()(f32x4 (&acc)[2][2][4][2], const Unit& u, const Order& S, int wr, int wc, int fr_, int fq_, LAS unsigned char*, int) const {
;     ...
;         for (int ai = 0; ai < 2; ++ai)
; #pragma unroll
;             for (int m = 0; m < 4; ++m) {
;                 const int row = row0 + ai * HALF + m * 16; const size_t off = (size_t)row * DM + col0;
;                 float sq = 0.f;
; #pragma unroll
;                 for (int bj = 0; bj < 2; ++bj) {
;                     const h16x8 bs = *(const h16x8*)(h16 + off + bj * HALF);
;                     f32x4 o0 = acc[ai][bj][m][0] * pre, o1 = acc[ai][bj][m][1] * pre;
; #pragma unroll
;                     for (int e = 0; e < 4; ++e) { o0[e] += (float)bs[e]; o1[e] += (float)bs[4 + e]; }
;                     if (out32) { if (!dry) { __builtin_nontemporal_store(o0, (f32x4*)(out32 + off + bj * HALF)); __builtin_nontemporal_store(o1, (f32x4*)(out32 + off + bj * HALF + 4)); } }
;                     else if (!dry) {
;                         sq += (o0[0] * o0[0] + o0[1] * o0[1]) + (o0[2] * o0[2] + o0[3] * o0[3]) + (o1[0] * o1[0] + o1[1] * o1[1]) + (o1[2] * o1[2] + o1[3] * o1[3]);
;                         u32x4 w; w.x = pkh(o0[0], o0[1]); w.y = pkh(o0[2], o0[3]); w.z = pkh(o1[0], o1[1]); w.w = pkh(o1[2], o1[3]);
;                         *(u32x4*)(h16 + off + bj * HALF) = w;
;                         if (h8) { u32x2 q; q.x = pk8(o0[0] * F8_SA, o0[1] * F8_SA, o0[2] * F8_SA, o0[3] * F8_SA); q.y = pk8(o1[0] * F8_SA, o1[1] * F8_SA, o1[2] * F8_SA, o1[3] * F8_SA); *(u32x2*)(h8 + off + bj * HALF) = q; } }
;                 }
;                 if (!out32 && !dry) { sq += __shfl_xor(sq, 16); sq += __shfl_xor(sq, 32); if (fq == 0) atomicAdd(ss_out + row, sq); }
	v_cvt_f32_f16_e32 v62, v58
	v_cvt_f32_f16_sdwa v63, v58 dst_sel:DWORD dst_unused:UNUSED_PAD src0_sel:WORD_1
	v_cvt_f32_f16_e32 v64, v60
	v_cvt_f32_f16_sdwa v65, v60 dst_sel:DWORD dst_unused:UNUSED_PAD src0_sel:WORD_1
	v_cvt_f32_f16_e32 v58, v59
	v_cvt_f32_f16_sdwa v59, v59 dst_sel:DWORD dst_unused:UNUSED_PAD src0_sel:WORD_1
	v_cvt_f32_f16_e32 v60, v61
	v_cvt_f32_f16_sdwa v61, v61 dst_sel:DWORD dst_unused:UNUSED_PAD src0_sel:WORD_1
	v_pk_add_f32 v[54:55], v[54:55], v[62:63]
	v_pk_add_f32 v[62:63], v[50:51], v[64:65]
	v_pk_add_f32 v[50:51], v[56:57], v[58:59]
	v_pk_add_f32 v[56:57], v[52:53], v[60:61]
	v_pk_mul_f32 v[58:59], v[54:55], v[54:55]
	v_pk_mul_f32 v[60:61], v[50:51], v[50:51]
	v_pk_mul_f32 v[64:65], v[62:63], v[62:63]
	v_cvt_pk_f16_f32 v52, v54, v55
	v_mul_f32_e32 v54, 0x41000000, v54
	v_mul_f32_e32 v55, 0x41000000, v55
	v_add_f32_e32 v60, v60, v61
	v_add_f32_e32 v58, v58, v59
	v_pk_mul_f32 v[68:69], v[56:57], v[56:57]
	v_add_f32_e32 v59, v64, v65
	v_cvt_pk_fp8_f32 v70, v54, v55
	v_add_f32_e32 v54, v58, v60
	v_add_f32_e32 v61, v68, v69
	v_add_f32_e32 v54, v59, v54
	v_add_f32_e32 v54, v61, v54
	v_add_f32_e32 v54, v76, v54
	v_mul_f32_e32 v77, 0x41000000, v62
	v_mul_f32_e32 v78, 0x41000000, v63
	ds_bpermute_b32 v55, v122, v54
	v_cvt_pk_fp8_f32 v71, v77, v78
	v_cvt_pk_f16_f32 v53, v50, v51
	v_mul_f32_e32 v50, 0x41000000, v50
	v_mul_f32_e32 v51, 0x41000000, v51
	v_cvt_pk_fp8_f32 v70, v50, v51 op_sel:[0,0,1]
	v_mul_f32_e32 v50, 0x41000000, v56
	v_mul_f32_e32 v51, 0x41000000, v57
	v_cvt_pk_fp8_f32 v71, v50, v51 op_sel:[0,0,1]
	s_waitcnt lgkmcnt(0)
	v_add_f32_e32 v50, v54, v55
	ds_bpermute_b32 v51, v116, v50
	v_cvt_pk_f16_f32 v54, v62, v63
	v_cvt_pk_f16_f32 v55, v56, v57
	global_store_dwordx4 v[74:75], v[52:55], off offset:256 sc1
	global_store_dwordx2 v[72:73], v[70:71], off offset:128
	s_and_saveexec_b64 s[2:3], vcc
	s_cbranch_execz .LBB0_680
	v_lshl_add_u64 v[52:53], v[66:67], 2, s[4:5]
	s_waitcnt lgkmcnt(0)
	v_add_f32_e32 v50, v50, v51
	global_atomic_add_f32 v[52:53], v50, off
.LBB0_680:
	s_or_b64 exec, exec, s[2:3]
	v_add_u32_e32 v50, 0x90, v148
	s_waitcnt lgkmcnt(0)
	v_ashrrev_i32_e32 v51, 31, v50
	v_lshlrev_b64 v[52:53], 10, v[50:51]
	v_lshl_add_u64 v[56:57], v[52:53], 0, v[146:147]
	v_lshl_add_u64 v[58:59], v[56:57], 1, s[90:91]
	global_load_dwordx4 v[52:55], v[58:59], off
	v_mov_b32_e32 v60, 0
	v_mov_b32_e32 v61, 0
	v_lshl_add_u64 v[56:57], s[10:11], 0, v[56:57]
	s_waitcnt vmcnt(0)
	v_cvt_f32_f16_e32 v62, v52
	v_cvt_f32_f16_sdwa v63, v52 dst_sel:DWORD dst_unused:UNUSED_PAD src0_sel:WORD_1
	v_cvt_f32_f16_e32 v64, v54
	v_cvt_f32_f16_sdwa v65, v54 dst_sel:DWORD dst_unused:UNUSED_PAD src0_sel:WORD_1
	v_cvt_f32_f16_e32 v52, v53
	v_cvt_f32_f16_sdwa v53, v53 dst_sel:DWORD dst_unused:UNUSED_PAD src0_sel:WORD_1
	v_cvt_f32_f16_e32 v54, v55
	v_cvt_f32_f16_sdwa v55, v55 dst_sel:DWORD dst_unused:UNUSED_PAD src0_sel:WORD_1
	v_pk_add_f32 v[46:47], v[46:47], v[62:63]
	v_pk_add_f32 v[62:63], v[42:43], v[64:65]
	v_pk_add_f32 v[48:49], v[48:49], v[52:53]
	v_pk_add_f32 v[52:53], v[44:45], v[54:55]
	v_mul_f32_e32 v44, 0x41000000, v46
	v_mul_f32_e32 v45, 0x41000000, v47
	v_mul_f32_e32 v64, 0x41000000, v62
	v_mul_f32_e32 v65, 0x41000000, v63
	v_cvt_pk_fp8_f32 v60, v44, v45
	v_cvt_pk_fp8_f32 v61, v64, v65
	v_mul_f32_e32 v54, 0x41000000, v48
	v_mul_f32_e32 v55, 0x41000000, v49
	v_mul_f32_e32 v44, 0x41000000, v52
	v_mul_f32_e32 v45, 0x41000000, v53
	v_cvt_pk_fp8_f32 v60, v54, v55 op_sel:[0,0,1]
	v_cvt_pk_fp8_f32 v61, v44, v45 op_sel:[0,0,1]
	v_cvt_pk_f16_f32 v42, v46, v47
	v_cvt_pk_f16_f32 v43, v48, v49
	v_cvt_pk_f16_f32 v44, v62, v63
	v_cvt_pk_f16_f32 v45, v52, v53
	global_store_dwordx4 v[58:59], v[42:45], off sc1
	global_store_dwordx2 v[56:57], v[60:61], off
	global_load_dwordx4 v[42:45], v[58:59], off offset:256
	v_pk_mul_f32 v[46:47], v[46:47], v[46:47]
	v_pk_mul_f32 v[48:49], v[48:49], v[48:49]
	v_pk_mul_f32 v[60:61], v[62:63], v[62:63]
	v_add_f32_e32 v48, v48, v49
	v_add_f32_e32 v46, v46, v47
	v_pk_mul_f32 v[52:53], v[52:53], v[52:53]
	v_add_f32_e32 v47, v60, v61
	v_add_f32_e32 v46, v46, v48
	v_add_f32_e32 v49, v52, v53
	v_add_f32_e32 v46, v47, v46
	v_add_f32_e32 v60, v49, v46
	v_mov_b32_e32 v54, 0
	v_mov_b32_e32 v55, 0
	s_waitcnt vmcnt(0)
	v_cvt_f32_f16_e32 v46, v42
	v_cvt_f32_f16_sdwa v47, v42 dst_sel:DWORD dst_unused:UNUSED_PAD src0_sel:WORD_1
	v_cvt_f32_f16_e32 v48, v44
	v_cvt_f32_f16_sdwa v49, v44 dst_sel:DWORD dst_unused:UNUSED_PAD src0_sel:WORD_1
	v_cvt_f32_f16_e32 v42, v43
	v_cvt_f32_f16_sdwa v43, v43 dst_sel:DWORD dst_unused:UNUSED_PAD src0_sel:WORD_1
	v_cvt_f32_f16_e32 v44, v45
	v_cvt_f32_f16_sdwa v45, v45 dst_sel:DWORD dst_unused:UNUSED_PAD src0_sel:WORD_1
	v_pk_add_f32 v[38:39], v[38:39], v[46:47]
	v_pk_add_f32 v[46:47], v[34:35], v[48:49]
	v_pk_add_f32 v[34:35], v[40:41], v[42:43]
	v_pk_add_f32 v[40:41], v[36:37], v[44:45]
	v_pk_mul_f32 v[42:43], v[38:39], v[38:39]
	v_pk_mul_f32 v[44:45], v[34:35], v[34:35]
	v_pk_mul_f32 v[48:49], v[46:47], v[46:47]
	v_cvt_pk_f16_f32 v36, v38, v39
	v_mul_f32_e32 v38, 0x41000000, v38
	v_mul_f32_e32 v39, 0x41000000, v39
	v_add_f32_e32 v44, v44, v45
	v_add_f32_e32 v42, v42, v43
	v_pk_mul_f32 v[52:53], v[40:41], v[40:41]
	v_add_f32_e32 v43, v48, v49
	v_cvt_pk_fp8_f32 v54, v38, v39
	v_add_f32_e32 v38, v42, v44
	v_add_f32_e32 v45, v52, v53
	v_add_f32_e32 v38, v43, v38
	v_add_f32_e32 v38, v45, v38
	v_add_f32_e32 v38, v60, v38
	v_mul_f32_e32 v61, 0x41000000, v46
	v_mul_f32_e32 v62, 0x41000000, v47
	ds_bpermute_b32 v39, v122, v38
	v_cvt_pk_fp8_f32 v55, v61, v62
	v_cvt_pk_f16_f32 v37, v34, v35
	v_mul_f32_e32 v34, 0x41000000, v34
	v_mul_f32_e32 v35, 0x41000000, v35
	v_cvt_pk_fp8_f32 v54, v34, v35 op_sel:[0,0,1]
	v_mul_f32_e32 v34, 0x41000000, v40
	v_mul_f32_e32 v35, 0x41000000, v41
	v_cvt_pk_fp8_f32 v55, v34, v35 op_sel:[0,0,1]
	s_waitcnt lgkmcnt(0)
	v_add_f32_e32 v34, v38, v39
	ds_bpermute_b32 v35, v116, v34
	v_cvt_pk_f16_f32 v38, v46, v47
	v_cvt_pk_f16_f32 v39, v40, v41
	global_store_dwordx4 v[58:59], v[36:39], off offset:256 sc1
	global_store_dwordx2 v[56:57], v[54:55], off offset:128
	s_and_saveexec_b64 s[2:3], vcc
	s_cbranch_execz .LBB0_682
	v_lshl_add_u64 v[36:37], v[50:51], 2, s[4:5]
	s_waitcnt lgkmcnt(0)
	v_add_f32_e32 v34, v34, v35
	global_atomic_add_f32 v[36:37], v34, off
; __device__ __forceinline__ unsigned pkh(float lo, float hi) { f32x2 v = {lo, hi}; h16x2 h = __builtin_convertvector(v, h16x2); return __builtin_bit_cast(unsigned, h); }
; __device__ __forceinline__ unsigned pk8(float a, float b, float c, float d) { int w = __builtin_amdgcn_cvt_pk_fp8_f32(a, b, 0, false); w = __builtin_amdgcn_cvt_pk_fp8_f32(c, d, w, true); return (unsigned)w; }
;     __device__ __forceinline__ void operator()(f32x4 (&acc)[2][2][4][2], const Unit& u, const Order& S, int wr, int wc, int fr_, int fq_, LAS unsigned char*, int) const {
;     ...
;         for (int ai = 0; ai < 2; ++ai)
; #pragma unroll
;             for (int m = 0; m < 4; ++m) {
;                 const int row = row0 + ai * HALF + m * 16; const size_t off = (size_t)row * DM + col0;
;                 float sq = 0.f;
; #pragma unroll
;                 for (int bj = 0; bj < 2; ++bj) {
;                     const h16x8 bs = *(const h16x8*)(h16 + off + bj * HALF);
;                     f32x4 o0 = acc[ai][bj][m][0] * pre, o1 = acc[ai][bj][m][1] * pre;
; #pragma unroll
;                     for (int e = 0; e < 4; ++e) { o0[e] += (float)bs[e]; o1[e] += (float)bs[4 + e]; }
;                     if (out32) { if (!dry) { __builtin_nontemporal_store(o0, (f32x4*)(out32 + off + bj * HALF)); __builtin_nontemporal_store(o1, (f32x4*)(out32 + off + bj * HALF + 4)); } }
;                     else if (!dry) {
;                         sq += (o0[0] * o0[0] + o0[1] * o0[1]) + (o0[2] * o0[2] + o0[3] * o0[3]) + (o1[0] * o1[0] + o1[1] * o1[1]) + (o1[2] * o1[2] + o1[3] * o1[3]);
;                         u32x4 w; w.x = pkh(o0[0], o0[1]); w.y = pkh(o0[2], o0[3]); w.z = pkh(o1[0], o1[1]); w.w = pkh(o1[2], o1[3]);
;                         *(u32x4*)(h16 + off + bj * HALF) = w;
;                         if (h8) { u32x2 q; q.x = pk8(o0[0] * F8_SA, o0[1] * F8_SA, o0[2] * F8_SA, o0[3] * F8_SA); q.y = pk8(o1[0] * F8_SA, o1[1] * F8_SA, o1[2] * F8_SA, o1[3] * F8_SA); *(u32x2*)(h8 + off + bj * HALF) = q; } }
;                 }
;                 if (!out32 && !dry) { sq += __shfl_xor(sq, 16); sq += __shfl_xor(sq, 32); if (fq == 0) atomicAdd(ss_out + row, sq); }
.LBB0_682:
	s_or_b64 exec, exec, s[2:3]
	v_add_u32_e32 v34, 0xa0, v148
	s_waitcnt lgkmcnt(0)
	v_ashrrev_i32_e32 v35, 31, v34
	v_lshlrev_b64 v[36:37], 10, v[34:35]
	v_lshl_add_u64 v[40:41], v[36:37], 0, v[146:147]
	v_lshl_add_u64 v[42:43], v[40:41], 1, s[90:91]
	global_load_dwordx4 v[36:39], v[42:43], off
	v_mov_b32_e32 v44, 0
	v_mov_b32_e32 v45, 0
	v_lshl_add_u64 v[40:41], s[10:11], 0, v[40:41]
	s_waitcnt vmcnt(0)
	v_cvt_f32_f16_e32 v46, v36
	v_cvt_f32_f16_sdwa v47, v36 dst_sel:DWORD dst_unused:UNUSED_PAD src0_sel:WORD_1
	v_cvt_f32_f16_e32 v48, v38
	v_cvt_f32_f16_sdwa v49, v38 dst_sel:DWORD dst_unused:UNUSED_PAD src0_sel:WORD_1
	v_cvt_f32_f16_e32 v36, v37
	v_cvt_f32_f16_sdwa v37, v37 dst_sel:DWORD dst_unused:UNUSED_PAD src0_sel:WORD_1
	v_cvt_f32_f16_e32 v38, v39
	v_cvt_f32_f16_sdwa v39, v39 dst_sel:DWORD dst_unused:UNUSED_PAD src0_sel:WORD_1
	v_pk_add_f32 v[30:31], v[30:31], v[46:47]
	v_pk_add_f32 v[46:47], v[26:27], v[48:49]
	v_pk_add_f32 v[32:33], v[32:33], v[36:37]
	v_pk_add_f32 v[36:37], v[28:29], v[38:39]
	v_mul_f32_e32 v28, 0x41000000, v30
	v_mul_f32_e32 v29, 0x41000000, v31
	v_mul_f32_e32 v48, 0x41000000, v46
	v_mul_f32_e32 v49, 0x41000000, v47
	v_cvt_pk_fp8_f32 v44, v28, v29
	v_cvt_pk_fp8_f32 v45, v48, v49
	v_mul_f32_e32 v38, 0x41000000, v32
	v_mul_f32_e32 v39, 0x41000000, v33
	v_mul_f32_e32 v28, 0x41000000, v36
	v_mul_f32_e32 v29, 0x41000000, v37
	v_cvt_pk_fp8_f32 v44, v38, v39 op_sel:[0,0,1]
	v_cvt_pk_fp8_f32 v45, v28, v29 op_sel:[0,0,1]
	v_cvt_pk_f16_f32 v26, v30, v31
	v_cvt_pk_f16_f32 v27, v32, v33
	v_cvt_pk_f16_f32 v28, v46, v47
	v_cvt_pk_f16_f32 v29, v36, v37
	global_store_dwordx4 v[42:43], v[26:29], off sc1
	global_store_dwordx2 v[40:41], v[44:45], off
	global_load_dwordx4 v[26:29], v[42:43], off offset:256
	v_pk_mul_f32 v[30:31], v[30:31], v[30:31]
	v_pk_mul_f32 v[32:33], v[32:33], v[32:33]
	v_pk_mul_f32 v[44:45], v[46:47], v[46:47]
	v_add_f32_e32 v32, v32, v33
	v_add_f32_e32 v30, v30, v31
	v_pk_mul_f32 v[36:37], v[36:37], v[36:37]
	v_add_f32_e32 v31, v44, v45
	v_add_f32_e32 v30, v30, v32
	v_add_f32_e32 v33, v36, v37
	v_add_f32_e32 v30, v31, v30
	v_add_f32_e32 v44, v33, v30
	v_mov_b32_e32 v38, 0
	v_mov_b32_e32 v39, 0
	s_waitcnt vmcnt(0)
	v_cvt_f32_f16_e32 v30, v26
	v_cvt_f32_f16_sdwa v31, v26 dst_sel:DWORD dst_unused:UNUSED_PAD src0_sel:WORD_1
	v_cvt_f32_f16_e32 v32, v28
	v_cvt_f32_f16_sdwa v33, v28 dst_sel:DWORD dst_unused:UNUSED_PAD src0_sel:WORD_1
	v_cvt_f32_f16_e32 v26, v27
	v_cvt_f32_f16_sdwa v27, v27 dst_sel:DWORD dst_unused:UNUSED_PAD src0_sel:WORD_1
	v_cvt_f32_f16_e32 v28, v29
	v_cvt_f32_f16_sdwa v29, v29 dst_sel:DWORD dst_unused:UNUSED_PAD src0_sel:WORD_1
	v_pk_add_f32 v[22:23], v[22:23], v[30:31]
	v_pk_add_f32 v[30:31], v[18:19], v[32:33]
	v_pk_add_f32 v[18:19], v[24:25], v[26:27]
	v_pk_add_f32 v[24:25], v[20:21], v[28:29]
	v_pk_mul_f32 v[26:27], v[22:23], v[22:23]
	v_pk_mul_f32 v[28:29], v[18:19], v[18:19]
	v_pk_mul_f32 v[32:33], v[30:31], v[30:31]
	v_cvt_pk_f16_f32 v20, v22, v23
	v_mul_f32_e32 v22, 0x41000000, v22
	v_mul_f32_e32 v23, 0x41000000, v23
	v_add_f32_e32 v28, v28, v29
	v_add_f32_e32 v26, v26, v27
	v_pk_mul_f32 v[36:37], v[24:25], v[24:25]
	v_add_f32_e32 v27, v32, v33
	v_cvt_pk_fp8_f32 v38, v22, v23
	v_add_f32_e32 v22, v26, v28
	v_add_f32_e32 v29, v36, v37
	v_add_f32_e32 v22, v27, v22
	v_add_f32_e32 v22, v29, v22
	v_add_f32_e32 v22, v44, v22
	v_mul_f32_e32 v45, 0x41000000, v30
	v_mul_f32_e32 v46, 0x41000000, v31
	ds_bpermute_b32 v23, v122, v22
	v_cvt_pk_fp8_f32 v39, v45, v46
	v_cvt_pk_f16_f32 v21, v18, v19
	v_mul_f32_e32 v18, 0x41000000, v18
	v_mul_f32_e32 v19, 0x41000000, v19
	v_cvt_pk_fp8_f32 v38, v18, v19 op_sel:[0,0,1]
	v_mul_f32_e32 v18, 0x41000000, v24
	v_mul_f32_e32 v19, 0x41000000, v25
	v_cvt_pk_fp8_f32 v39, v18, v19 op_sel:[0,0,1]
	s_waitcnt lgkmcnt(0)
	v_add_f32_e32 v18, v22, v23
	ds_bpermute_b32 v19, v116, v18
	v_cvt_pk_f16_f32 v22, v30, v31
	v_cvt_pk_f16_f32 v23, v24, v25
	global_store_dwordx4 v[42:43], v[20:23], off offset:256 sc1
	global_store_dwordx2 v[40:41], v[38:39], off offset:128
	s_and_saveexec_b64 s[2:3], vcc
	s_cbranch_execz .LBB0_684
	v_lshl_add_u64 v[20:21], v[34:35], 2, s[4:5]
	s_waitcnt lgkmcnt(0)
	v_add_f32_e32 v18, v18, v19
	global_atomic_add_f32 v[20:21], v18, off
; __device__ __forceinline__ unsigned pkh(float lo, float hi) { f32x2 v = {lo, hi}; h16x2 h = __builtin_convertvector(v, h16x2); return __builtin_bit_cast(unsigned, h); }
; __device__ __forceinline__ unsigned pk8(float a, float b, float c, float d) { int w = __builtin_amdgcn_cvt_pk_fp8_f32(a, b, 0, false); w = __builtin_amdgcn_cvt_pk_fp8_f32(c, d, w, true); return (unsigned)w; }
;     __device__ __forceinline__ void operator()(f32x4 (&acc)[2][2][4][2], const Unit& u, const Order& S, int wr, int wc, int fr_, int fq_, LAS unsigned char*, int) const {
;     ...
;         for (int ai = 0; ai < 2; ++ai)
; #pragma unroll
;             for (int m = 0; m < 4; ++m) {
;                 const int row = row0 + ai * HALF + m * 16; const size_t off = (size_t)row * DM + col0;
;                 float sq = 0.f;
; #pragma unroll
;                 for (int bj = 0; bj < 2; ++bj) {
;                     const h16x8 bs = *(const h16x8*)(h16 + off + bj * HALF);
;                     f32x4 o0 = acc[ai][bj][m][0] * pre, o1 = acc[ai][bj][m][1] * pre;
; #pragma unroll
;                     for (int e = 0; e < 4; ++e) { o0[e] += (float)bs[e]; o1[e] += (float)bs[4 + e]; }
;                     if (out32) { if (!dry) { __builtin_nontemporal_store(o0, (f32x4*)(out32 + off + bj * HALF)); __builtin_nontemporal_store(o1, (f32x4*)(out32 + off + bj * HALF + 4)); } }
;                     else if (!dry) {
;                         sq += (o0[0] * o0[0] + o0[1] * o0[1]) + (o0[2] * o0[2] + o0[3] * o0[3]) + (o1[0] * o1[0] + o1[1] * o1[1]) + (o1[2] * o1[2] + o1[3] * o1[3]);
;                         u32x4 w; w.x = pkh(o0[0], o0[1]); w.y = pkh(o0[2], o0[3]); w.z = pkh(o1[0], o1[1]); w.w = pkh(o1[2], o1[3]);
;                         *(u32x4*)(h16 + off + bj * HALF) = w;
;                         if (h8) { u32x2 q; q.x = pk8(o0[0] * F8_SA, o0[1] * F8_SA, o0[2] * F8_SA, o0[3] * F8_SA); q.y = pk8(o1[0] * F8_SA, o1[1] * F8_SA, o1[2] * F8_SA, o1[3] * F8_SA); *(u32x2*)(h8 + off + bj * HALF) = q; } }
;                 }
;                 if (!out32 && !dry) { sq += __shfl_xor(sq, 16); sq += __shfl_xor(sq, 32); if (fq == 0) atomicAdd(ss_out + row, sq); }
.LBB0_684:
	s_or_b64 exec, exec, s[2:3]
	v_add_u32_e32 v18, 0xb0, v148
	s_waitcnt lgkmcnt(0)
	v_ashrrev_i32_e32 v19, 31, v18
	v_lshlrev_b64 v[20:21], 10, v[18:19]
	v_lshl_add_u64 v[24:25], v[20:21], 0, v[146:147]
	v_lshl_add_u64 v[26:27], v[24:25], 1, s[90:91]
	global_load_dwordx4 v[20:23], v[26:27], off
	v_mov_b32_e32 v28, 0
	v_mov_b32_e32 v29, 0
	v_lshl_add_u64 v[24:25], s[10:11], 0, v[24:25]
	s_waitcnt vmcnt(0)
	v_cvt_f32_f16_e32 v30, v20
	v_cvt_f32_f16_sdwa v31, v20 dst_sel:DWORD dst_unused:UNUSED_PAD src0_sel:WORD_1
	v_cvt_f32_f16_e32 v32, v22
	v_cvt_f32_f16_sdwa v33, v22 dst_sel:DWORD dst_unused:UNUSED_PAD src0_sel:WORD_1
	v_cvt_f32_f16_e32 v20, v21
	v_cvt_f32_f16_sdwa v21, v21 dst_sel:DWORD dst_unused:UNUSED_PAD src0_sel:WORD_1
	v_cvt_f32_f16_e32 v22, v23
	v_cvt_f32_f16_sdwa v23, v23 dst_sel:DWORD dst_unused:UNUSED_PAD src0_sel:WORD_1
	v_pk_add_f32 v[14:15], v[14:15], v[30:31]
	v_pk_add_f32 v[30:31], v[10:11], v[32:33]
	v_pk_add_f32 v[16:17], v[16:17], v[20:21]
	v_pk_add_f32 v[20:21], v[12:13], v[22:23]
	v_mul_f32_e32 v12, 0x41000000, v14
	v_mul_f32_e32 v13, 0x41000000, v15
	v_mul_f32_e32 v32, 0x41000000, v30
	v_mul_f32_e32 v33, 0x41000000, v31
	v_cvt_pk_fp8_f32 v28, v12, v13
	v_cvt_pk_fp8_f32 v29, v32, v33
	v_mul_f32_e32 v22, 0x41000000, v16
	v_mul_f32_e32 v23, 0x41000000, v17
	v_mul_f32_e32 v12, 0x41000000, v20
	v_mul_f32_e32 v13, 0x41000000, v21
	v_cvt_pk_fp8_f32 v28, v22, v23 op_sel:[0,0,1]
	v_cvt_pk_fp8_f32 v29, v12, v13 op_sel:[0,0,1]
	v_cvt_pk_f16_f32 v10, v14, v15
	v_cvt_pk_f16_f32 v11, v16, v17
	v_cvt_pk_f16_f32 v12, v30, v31
	v_cvt_pk_f16_f32 v13, v20, v21
	global_store_dwordx4 v[26:27], v[10:13], off sc1
	global_store_dwordx2 v[24:25], v[28:29], off
	global_load_dwordx4 v[10:13], v[26:27], off offset:256
	v_pk_mul_f32 v[14:15], v[14:15], v[14:15]
	v_pk_mul_f32 v[16:17], v[16:17], v[16:17]
	v_pk_mul_f32 v[28:29], v[30:31], v[30:31]
	v_add_f32_e32 v16, v16, v17
	v_add_f32_e32 v14, v14, v15
	v_pk_mul_f32 v[20:21], v[20:21], v[20:21]
	v_add_f32_e32 v15, v28, v29
	v_add_f32_e32 v14, v14, v16
	v_add_f32_e32 v17, v20, v21
	v_add_f32_e32 v14, v15, v14
	v_add_f32_e32 v28, v17, v14
	v_mov_b32_e32 v22, 0
	v_mov_b32_e32 v23, 0
	s_waitcnt vmcnt(0)
	v_cvt_f32_f16_e32 v14, v10
	v_cvt_f32_f16_sdwa v15, v10 dst_sel:DWORD dst_unused:UNUSED_PAD src0_sel:WORD_1
	v_cvt_f32_f16_e32 v16, v12
	v_cvt_f32_f16_sdwa v17, v12 dst_sel:DWORD dst_unused:UNUSED_PAD src0_sel:WORD_1
	v_cvt_f32_f16_e32 v10, v11
	v_cvt_f32_f16_sdwa v11, v11 dst_sel:DWORD dst_unused:UNUSED_PAD src0_sel:WORD_1
	v_cvt_f32_f16_e32 v12, v13
	v_cvt_f32_f16_sdwa v13, v13 dst_sel:DWORD dst_unused:UNUSED_PAD src0_sel:WORD_1
	v_pk_add_f32 v[6:7], v[6:7], v[14:15]
	v_pk_add_f32 v[14:15], v[2:3], v[16:17]
	v_pk_add_f32 v[2:3], v[8:9], v[10:11]
	v_pk_add_f32 v[8:9], v[4:5], v[12:13]
	v_pk_mul_f32 v[10:11], v[6:7], v[6:7]
	v_pk_mul_f32 v[12:13], v[2:3], v[2:3]
	v_pk_mul_f32 v[16:17], v[14:15], v[14:15]
	v_cvt_pk_f16_f32 v4, v6, v7
	v_mul_f32_e32 v6, 0x41000000, v6
	v_mul_f32_e32 v7, 0x41000000, v7
	v_add_f32_e32 v12, v12, v13
	v_add_f32_e32 v10, v10, v11
	v_pk_mul_f32 v[20:21], v[8:9], v[8:9]
	v_add_f32_e32 v11, v16, v17
	v_cvt_pk_fp8_f32 v22, v6, v7
	v_add_f32_e32 v6, v10, v12
	v_add_f32_e32 v13, v20, v21
	v_add_f32_e32 v6, v11, v6
	v_add_f32_e32 v6, v13, v6
	v_add_f32_e32 v6, v28, v6
	v_mul_f32_e32 v29, 0x41000000, v14
	v_mul_f32_e32 v30, 0x41000000, v15
	ds_bpermute_b32 v7, v122, v6
	v_cvt_pk_fp8_f32 v23, v29, v30
	v_cvt_pk_f16_f32 v5, v2, v3
	v_mul_f32_e32 v2, 0x41000000, v2
	v_mul_f32_e32 v3, 0x41000000, v3
	v_cvt_pk_fp8_f32 v22, v2, v3 op_sel:[0,0,1]
	v_mul_f32_e32 v2, 0x41000000, v8
	v_mul_f32_e32 v3, 0x41000000, v9
	v_cvt_pk_fp8_f32 v23, v2, v3 op_sel:[0,0,1]
	s_waitcnt lgkmcnt(0)
	v_add_f32_e32 v2, v6, v7
	ds_bpermute_b32 v3, v116, v2
	v_cvt_pk_f16_f32 v6, v14, v15
	v_cvt_pk_f16_f32 v7, v8, v9
	global_store_dwordx4 v[26:27], v[4:7], off offset:256 sc1
	global_store_dwordx2 v[24:25], v[22:23], off offset:128
	s_and_saveexec_b64 s[2:3], vcc
	s_cbranch_execz .LBB0_686
	v_lshl_add_u64 v[4:5], v[18:19], 2, s[4:5]
	s_waitcnt lgkmcnt(0)
	v_add_f32_e32 v2, v2, v3
	global_atomic_add_f32 v[4:5], v2, off

; __device__ __forceinline__ unsigned pkh(float lo, float hi) { f32x2 v = {lo, hi}; h16x2 h = __builtin_convertvector(v, h16x2); return __builtin_bit_cast(unsigned, h); }
;     __device__ __forceinline__ void operator()(f32x4 (&acc)[2][2][4][2], const Unit& u, const Order& S, int wr, int wc, int fr_, int fq_, LAS unsigned char*, int) const {
;     ...
;         for (int ai = 0; ai < 2; ++ai)
; #pragma unroll
;             for (int m = 0; m < 4; ++m) {
;                 const int row = row0 + ai * HALF + m * 16;
;                 const float sc = __builtin_amdgcn_rsqf(ss_in[row] * (1.0f / DM) + EPS) * pre;
;                 f32x4 v[2][2]; float sq = 0.f;
; #pragma unroll
;                 for (int bj = 0; bj < 2; ++bj)
; #pragma unroll
;                     for (int n = 0; n < 2; ++n) { v[bj][n] = acc[ai][bj][m][n] * sc; const f32x4 t = v[bj][n]; sq += (t[0] * t[0] + t[1] * t[1]) + (t[2] * t[2] + t[3] * t[3]); }
;                 float rn = 1.f;
;                 if (nrm) { sq += __shfl_xor(sq, 16); sq += __shfl_xor(sq, 32); rn = __builtin_amdgcn_rsqf(sq * (1.0f / HD) + EPS); }
; #pragma unroll
;                 for (int bj = 0; bj < 2; ++bj) {
;                     const f32x4 a = v[bj][0] * rn * gv[bj][0], b = v[bj][1] * rn * gv[bj][1];
;                     ks[bj][0] += a; ks[bj][1] += b;
;                     u32x4 w; w.x = pkh(a[0], a[1]); w.y = pkh(a[2], a[3]); w.z = pkh(b[0], b[1]); w.w = pkh(b[2], b[3]);
;                     *(u32x4*)(P + (size_t)row * NB + colh + 32 * bj + 8 * fq) = w;
;                 }
.LBB0_763:
	s_lshl_b32 s17, s22, 8
	v_pk_mul_f32 v[146:147], v[160:161], v[152:153] op_sel_hi:[1,0]
	v_pk_mul_f32 v[148:149], v[158:159], v[152:153] op_sel_hi:[1,0]
	v_pk_mul_f32 v[30:31], v[30:31], v[152:153] op_sel_hi:[1,0]
	v_pk_mul_f32 v[32:33], v[32:33], v[152:153] op_sel_hi:[1,0]
	s_or_b32 s26, s17, s46
	v_pk_mul_f32 v[150:151], v[6:7], v[148:149]
	v_pk_mul_f32 v[148:149], v[8:9], v[146:147]
	v_pk_mul_f32 v[146:147], v[2:3], v[32:33]
	v_pk_mul_f32 v[32:33], v[4:5], v[30:31]
	v_mov_b64_e32 v[30:31], s[58:59]
	s_ashr_i32 s27, s26, 31
	v_mad_i64_i32 v[30:31], s[28:29], v178, s51, v[30:31]
	v_lshl_add_u64 v[30:31], s[26:27], 1, v[30:31]
	v_pk_mul_f32 v[22:23], v[22:23], v[152:153] op_sel_hi:[1,0]
	v_pk_mul_f32 v[28:29], v[28:29], v[152:153] op_sel_hi:[1,0]
	v_pk_mul_f32 v[18:19], v[18:19], v[152:153] op_sel_hi:[1,0]
	v_pk_mul_f32 v[20:21], v[20:21], v[152:153] op_sel_hi:[1,0]
	v_cvt_pk_f16_f32 v154, v150, v151
	v_cvt_pk_f16_f32 v155, v148, v149
	v_cvt_pk_f16_f32 v156, v146, v147
	v_cvt_pk_f16_f32 v157, v32, v33
	v_lshl_add_u64 v[30:31], v[24:25], 1, v[30:31]
	v_pk_mul_f32 v[28:29], v[14:15], v[28:29]
	v_pk_mul_f32 v[22:23], v[16:17], v[22:23]
	v_pk_mul_f32 v[20:21], v[10:11], v[20:21]
	v_pk_mul_f32 v[18:19], v[12:13], v[18:19]
	global_store_dwordx4 v[30:31], v[154:157], off sc1
	v_cvt_pk_f16_f32 v152, v28, v29
	v_cvt_pk_f16_f32 v153, v22, v23
	v_cvt_pk_f16_f32 v154, v20, v21
	v_cvt_pk_f16_f32 v155, v18, v19
	global_store_dwordx4 v[30:31], v[152:155], off offset:64 sc1
	global_load_dword v27, v[180:181], off offset:64
	s_and_b64 vcc, exec, s[2:3]
	s_waitcnt vmcnt(0)
	v_fmamk_f32 v27, v27, 0x3a800000, v192
	v_rsq_f32_e32 v27, v27
	s_nop 0
	v_mul_f32_e32 v184, 0x39800000, v27
	v_pk_mul_f32 v[158:159], v[144:145], v[184:185] op_sel_hi:[1,0]
	v_pk_mul_f32 v[160:161], v[142:143], v[184:185] op_sel_hi:[1,0]
	v_pk_mul_f32 v[154:155], v[140:141], v[184:185] op_sel_hi:[1,0]
	v_pk_mul_f32 v[156:157], v[138:139], v[184:185] op_sel_hi:[1,0]
	v_pk_mul_f32 v[144:145], v[136:137], v[184:185] op_sel_hi:[1,0]
	v_pk_mul_f32 v[152:153], v[134:135], v[184:185] op_sel_hi:[1,0]
	v_pk_mul_f32 v[30:31], v[132:133], v[184:185] op_sel_hi:[1,0]
	v_pk_mul_f32 v[142:143], v[130:131], v[184:185] op_sel_hi:[1,0]
	s_cbranch_vccnz .LBB0_765
	v_pk_mul_f32 v[26:27], v[158:159], v[158:159]
	v_pk_mul_f32 v[130:131], v[160:161], v[160:161]
	s_nop 0
	v_pk_mov_b32 v[132:133], v[130:131], v[26:27] op_sel:[1,0]
	v_mov_b32_e32 v131, v27
	v_pk_add_f32 v[26:27], v[132:133], v[130:131]
	v_pk_mul_f32 v[130:131], v[154:155], v[154:155]
	v_pk_add_f32 v[26:27], v[26:27], v[26:27] op_sel_hi:[0,1]
	v_pk_mul_f32 v[132:133], v[156:157], v[156:157]
	v_mul_f32_e32 v26, v152, v152
	v_pk_mov_b32 v[134:135], v[132:133], v[130:131] op_sel:[1,0]
	v_mov_b32_e32 v133, v131
	v_pk_add_f32 v[130:131], v[134:135], v[132:133]
	v_pk_fma_f32 v[132:133], v[152:153], v[152:153], v[26:27] op_sel_hi:[1,1,0]
	v_mul_f32_e32 v26, v144, v144
	v_pk_add_f32 v[130:131], v[130:131], v[130:131] op_sel_hi:[0,1]
	v_pk_fma_f32 v[134:135], v[144:145], v[144:145], v[26:27] op_sel_hi:[1,1,0]
	v_mul_f32_e32 v132, v142, v142
	v_mul_f32_e32 v134, v143, v143
	v_mul_f32_e32 v26, v30, v30
	v_mul_f32_e32 v130, v31, v31
	v_pk_add_f32 v[132:133], v[132:133], v[134:135]
	v_pk_add_f32 v[26:27], v[26:27], v[130:131]
	v_and_b32_e32 v130, 64, v193
	v_pk_add_f32 v[26:27], v[132:133], v[26:27]
	v_add_u32_e32 v130, 64, v130
	v_add_f32_e32 v26, v26, v27
	v_xor_b32_e32 v27, 16, v193
	v_cmp_lt_i32_e32 vcc, v27, v130
	s_nop 1
	v_cndmask_b32_e32 v27, v193, v27, vcc
	v_lshlrev_b32_e32 v27, 2, v27
	ds_bpermute_b32 v27, v27, v26
	s_waitcnt lgkmcnt(0)
	v_add_f32_e32 v26, v26, v27
	v_xor_b32_e32 v27, 32, v193
	v_cmp_lt_i32_e32 vcc, v27, v130
	s_nop 1
	v_cndmask_b32_e32 v27, v193, v27, vcc
	v_lshlrev_b32_e32 v27, 2, v27
	ds_bpermute_b32 v27, v27, v26
	s_waitcnt lgkmcnt(0)
	v_add_f32_e32 v26, v26, v27
	v_fmamk_f32 v26, v26, 0x3c800000, v192
	v_rsq_f32_e32 v26, v26
.LBB0_765:
	v_add_u32_e32 v27, 16, v178
	v_pk_mul_f32 v[130:131], v[158:159], v[26:27] op_sel_hi:[1,0]
	v_pk_mul_f32 v[132:133], v[160:161], v[26:27] op_sel_hi:[1,0]
	v_pk_mul_f32 v[138:139], v[8:9], v[130:131]
	v_pk_mul_f32 v[130:131], v[154:155], v[26:27] op_sel_hi:[1,0]
	v_mov_b64_e32 v[154:155], s[58:59]
	v_pk_mul_f32 v[140:141], v[6:7], v[132:133]
	v_pk_mul_f32 v[132:133], v[156:157], v[26:27] op_sel_hi:[1,0]
	v_mad_i64_i32 v[154:155], s[28:29], v27, s51, v[154:155]
	v_pk_mul_f32 v[134:135], v[4:5], v[130:131]
	v_pk_mul_f32 v[136:137], v[2:3], v[132:133]
	v_lshl_add_u64 v[154:155], s[26:27], 1, v[154:155]
	v_cvt_pk_f16_f32 v130, v140, v141
	v_cvt_pk_f16_f32 v131, v138, v139
	v_cvt_pk_f16_f32 v132, v136, v137
	v_cvt_pk_f16_f32 v133, v134, v135
	v_lshl_add_u64 v[154:155], v[24:25], 1, v[154:155]
	global_store_dwordx4 v[154:155], v[130:133], off sc1
	v_pk_mul_f32 v[30:31], v[30:31], v[26:27] op_sel_hi:[1,0]
	v_pk_mul_f32 v[142:143], v[142:143], v[26:27] op_sel_hi:[1,0]
	v_pk_mul_f32 v[130:131], v[144:145], v[26:27] op_sel_hi:[1,0]
	v_pk_mul_f32 v[132:133], v[152:153], v[26:27] op_sel_hi:[1,0]
	v_pk_mul_f32 v[130:131], v[16:17], v[130:131]
	v_pk_mul_f32 v[132:133], v[14:15], v[132:133]
	v_pk_mul_f32 v[26:27], v[12:13], v[30:31]
	v_pk_mul_f32 v[30:31], v[10:11], v[142:143]
	v_cvt_pk_f16_f32 v142, v132, v133
	v_cvt_pk_f16_f32 v143, v130, v131
	v_cvt_pk_f16_f32 v144, v30, v31
	v_cvt_pk_f16_f32 v145, v26, v27
	global_store_dwordx4 v[154:155], v[142:145], off offset:64 sc1
	global_load_dword v142, v[180:181], off offset:128
	s_and_b64 vcc, exec, s[2:3]
	s_waitcnt vmcnt(0)
	v_fmamk_f32 v142, v142, 0x3a800000, v192
	v_rsq_f32_e32 v143, v142
	v_mov_b32_e32 v142, 1.0
	v_mul_f32_e32 v144, 0x39800000, v143
	v_pk_mul_f32 v[128:129], v[128:129], v[144:145] op_sel_hi:[1,0]
	v_pk_mul_f32 v[126:127], v[126:127], v[144:145] op_sel_hi:[1,0]
	v_pk_mul_f32 v[124:125], v[124:125], v[144:145] op_sel_hi:[1,0]
	v_pk_mul_f32 v[122:123], v[122:123], v[144:145] op_sel_hi:[1,0]
	v_pk_mul_f32 v[120:121], v[120:121], v[144:145] op_sel_hi:[1,0]
	v_pk_mul_f32 v[118:119], v[118:119], v[144:145] op_sel_hi:[1,0]
	v_pk_mul_f32 v[116:117], v[116:117], v[144:145] op_sel_hi:[1,0]
	v_pk_mul_f32 v[114:115], v[114:115], v[144:145] op_sel_hi:[1,0]
	v_mov_b32_e32 v144, 1.0
	s_cbranch_vccnz .LBB0_767
; __device__ __forceinline__ unsigned pkh(float lo, float hi) { f32x2 v = {lo, hi}; h16x2 h = __builtin_convertvector(v, h16x2); return __builtin_bit_cast(unsigned, h); }
;     __device__ __forceinline__ void operator()(f32x4 (&acc)[2][2][4][2], const Unit& u, const Order& S, int wr, int wc, int fr_, int fq_, LAS unsigned char*, int) const {
;     ...
;         for (int ai = 0; ai < 2; ++ai)
; #pragma unroll
;             for (int m = 0; m < 4; ++m) {
;                 const int row = row0 + ai * HALF + m * 16;
;                 const float sc = __builtin_amdgcn_rsqf(ss_in[row] * (1.0f / DM) + EPS) * pre;
;                 f32x4 v[2][2]; float sq = 0.f;
; #pragma unroll
;                 for (int bj = 0; bj < 2; ++bj)
; #pragma unroll
;                     for (int n = 0; n < 2; ++n) { v[bj][n] = acc[ai][bj][m][n] * sc; const f32x4 t = v[bj][n]; sq += (t[0] * t[0] + t[1] * t[1]) + (t[2] * t[2] + t[3] * t[3]); }
;                 float rn = 1.f;
;                 if (nrm) { sq += __shfl_xor(sq, 16); sq += __shfl_xor(sq, 32); rn = __builtin_amdgcn_rsqf(sq * (1.0f / HD) + EPS); }
; #pragma unroll
;                 for (int bj = 0; bj < 2; ++bj) {
;                     const f32x4 a = v[bj][0] * rn * gv[bj][0], b = v[bj][1] * rn * gv[bj][1];
;                     ks[bj][0] += a; ks[bj][1] += b;
;                     u32x4 w; w.x = pkh(a[0], a[1]); w.y = pkh(a[2], a[3]); w.z = pkh(b[0], b[1]); w.w = pkh(b[2], b[3]);
;                     *(u32x4*)(P + (size_t)row * NB + colh + 32 * bj + 8 * fq) = w;
;                 }
	v_pk_mul_f32 v[144:145], v[128:129], v[128:129]
	v_pk_mul_f32 v[152:153], v[126:127], v[126:127]
	s_nop 0
	v_pk_mov_b32 v[154:155], v[152:153], v[144:145] op_sel:[1,0]
	v_mov_b32_e32 v153, v145
	v_pk_add_f32 v[144:145], v[154:155], v[152:153]
	v_pk_mul_f32 v[152:153], v[124:125], v[124:125]
	v_pk_add_f32 v[144:145], v[144:145], v[144:145] op_sel_hi:[0,1]
	v_pk_mul_f32 v[154:155], v[122:123], v[122:123]
	v_mul_f32_e32 v144, v118, v118
	v_pk_mov_b32 v[156:157], v[154:155], v[152:153] op_sel:[1,0]
	v_mov_b32_e32 v155, v153
	v_pk_add_f32 v[152:153], v[156:157], v[154:155]
	v_pk_fma_f32 v[154:155], v[118:119], v[118:119], v[144:145] op_sel_hi:[1,1,0]
	v_mul_f32_e32 v144, v120, v120
	v_pk_add_f32 v[152:153], v[152:153], v[152:153] op_sel_hi:[0,1]
	v_pk_fma_f32 v[156:157], v[120:121], v[120:121], v[144:145] op_sel_hi:[1,1,0]
	v_mul_f32_e32 v154, v114, v114
	v_mul_f32_e32 v156, v115, v115
	v_mul_f32_e32 v144, v116, v116
	v_mul_f32_e32 v152, v117, v117
	v_pk_add_f32 v[154:155], v[154:155], v[156:157]
	v_pk_add_f32 v[144:145], v[144:145], v[152:153]
	s_nop 0
	v_pk_add_f32 v[144:145], v[154:155], v[144:145]
	s_nop 0
	v_add_f32_e32 v143, v144, v145
	v_and_b32_e32 v145, 64, v193
	v_xor_b32_e32 v144, 16, v193
	v_add_u32_e32 v145, 64, v145
	v_cmp_lt_i32_e32 vcc, v144, v145
	s_nop 1
	v_cndmask_b32_e32 v144, v193, v144, vcc
	v_lshlrev_b32_e32 v144, 2, v144
	ds_bpermute_b32 v144, v144, v143
	s_waitcnt lgkmcnt(0)
	v_add_f32_e32 v143, v143, v144
	v_xor_b32_e32 v144, 32, v193
	v_cmp_lt_i32_e32 vcc, v144, v145
	s_nop 1
	v_cndmask_b32_e32 v144, v193, v144, vcc
	v_lshlrev_b32_e32 v144, 2, v144
	ds_bpermute_b32 v144, v144, v143
	s_waitcnt lgkmcnt(0)
	v_add_f32_e32 v143, v143, v144
	v_fmamk_f32 v143, v143, 0x3c800000, v192
	v_rsq_f32_e32 v144, v143
.LBB0_767:
	v_add_u32_e32 v143, 32, v178
	v_pk_mul_f32 v[128:129], v[128:129], v[144:145] op_sel_hi:[1,0]
	v_pk_mul_f32 v[152:153], v[126:127], v[144:145] op_sel_hi:[1,0]
	v_mov_b64_e32 v[156:157], s[58:59]
	v_pk_mul_f32 v[126:127], v[8:9], v[128:129]
	v_pk_mul_f32 v[128:129], v[6:7], v[152:153]
	v_pk_mul_f32 v[124:125], v[124:125], v[144:145] op_sel_hi:[1,0]
	v_pk_mul_f32 v[152:153], v[122:123], v[144:145] op_sel_hi:[1,0]
	v_mad_i64_i32 v[156:157], s[28:29], v143, s51, v[156:157]
	v_pk_mul_f32 v[122:123], v[4:5], v[124:125]
	v_pk_mul_f32 v[124:125], v[2:3], v[152:153]
	v_lshl_add_u64 v[156:157], s[26:27], 1, v[156:157]
	v_cvt_pk_f16_f32 v152, v128, v129
	v_cvt_pk_f16_f32 v153, v126, v127
	v_cvt_pk_f16_f32 v154, v124, v125
	v_cvt_pk_f16_f32 v155, v122, v123
	v_lshl_add_u64 v[156:157], v[24:25], 1, v[156:157]
	global_store_dwordx4 v[156:157], v[152:155], off sc1
	v_pk_mul_f32 v[120:121], v[120:121], v[144:145] op_sel_hi:[1,0]
	v_pk_mul_f32 v[116:117], v[116:117], v[144:145] op_sel_hi:[1,0]
	v_pk_mul_f32 v[152:153], v[118:119], v[144:145] op_sel_hi:[1,0]
	v_pk_mul_f32 v[144:145], v[114:115], v[144:145] op_sel_hi:[1,0]
	v_pk_mul_f32 v[118:119], v[16:17], v[120:121]
	v_pk_mul_f32 v[120:121], v[14:15], v[152:153]
	v_pk_mul_f32 v[114:115], v[12:13], v[116:117]
	v_pk_mul_f32 v[116:117], v[10:11], v[144:145]
	v_cvt_pk_f16_f32 v152, v120, v121
	v_cvt_pk_f16_f32 v153, v118, v119
	v_cvt_pk_f16_f32 v154, v116, v117
	v_cvt_pk_f16_f32 v155, v114, v115
	global_store_dwordx4 v[156:157], v[152:155], off offset:64 sc1
	global_load_dword v143, v[180:181], off offset:192
	s_and_b64 vcc, exec, s[2:3]
	s_waitcnt vmcnt(0)
	v_fmamk_f32 v143, v143, 0x3a800000, v192
	v_rsq_f32_e32 v143, v143
	s_nop 0
	v_mul_f32_e32 v144, 0x39800000, v143
	v_pk_mul_f32 v[112:113], v[112:113], v[144:145] op_sel_hi:[1,0]
	v_pk_mul_f32 v[110:111], v[110:111], v[144:145] op_sel_hi:[1,0]
	v_pk_mul_f32 v[108:109], v[108:109], v[144:145] op_sel_hi:[1,0]
	v_pk_mul_f32 v[106:107], v[106:107], v[144:145] op_sel_hi:[1,0]
	v_pk_mul_f32 v[104:105], v[104:105], v[144:145] op_sel_hi:[1,0]
	v_pk_mul_f32 v[102:103], v[102:103], v[144:145] op_sel_hi:[1,0]
	v_pk_mul_f32 v[100:101], v[100:101], v[144:145] op_sel_hi:[1,0]
	v_pk_mul_f32 v[98:99], v[98:99], v[144:145] op_sel_hi:[1,0]
	s_cbranch_vccnz .LBB0_769
	v_pk_mul_f32 v[142:143], v[112:113], v[112:113]
	v_pk_mul_f32 v[144:145], v[110:111], v[110:111]
	s_nop 0
	v_pk_mov_b32 v[152:153], v[144:145], v[142:143] op_sel:[1,0]
	v_mov_b32_e32 v145, v143
	v_pk_add_f32 v[142:143], v[152:153], v[144:145]
	v_pk_mul_f32 v[144:145], v[108:109], v[108:109]
	v_pk_add_f32 v[142:143], v[142:143], v[142:143] op_sel_hi:[0,1]
	v_pk_mul_f32 v[152:153], v[106:107], v[106:107]
	v_mul_f32_e32 v142, v102, v102
	v_pk_mov_b32 v[154:155], v[152:153], v[144:145] op_sel:[1,0]
	v_mov_b32_e32 v153, v145
	v_pk_add_f32 v[144:145], v[154:155], v[152:153]
	v_pk_fma_f32 v[152:153], v[102:103], v[102:103], v[142:143] op_sel_hi:[1,1,0]
	v_mul_f32_e32 v142, v104, v104
	v_pk_add_f32 v[144:145], v[144:145], v[144:145] op_sel_hi:[0,1]
	v_pk_fma_f32 v[154:155], v[104:105], v[104:105], v[142:143] op_sel_hi:[1,1,0]
	v_mul_f32_e32 v152, v98, v98
	v_mul_f32_e32 v154, v99, v99
	v_mul_f32_e32 v142, v100, v100
	v_mul_f32_e32 v144, v101, v101
	v_pk_add_f32 v[152:153], v[152:153], v[154:155]
	v_pk_add_f32 v[142:143], v[142:143], v[144:145]
	v_and_b32_e32 v144, 64, v193
	v_pk_add_f32 v[142:143], v[152:153], v[142:143]
	v_add_u32_e32 v144, 64, v144
	v_add_f32_e32 v142, v142, v143
	v_xor_b32_e32 v143, 16, v193
	v_cmp_lt_i32_e32 vcc, v143, v144
	s_nop 1
	v_cndmask_b32_e32 v143, v193, v143, vcc
	v_lshlrev_b32_e32 v143, 2, v143
	ds_bpermute_b32 v143, v143, v142
	s_waitcnt lgkmcnt(0)
	v_add_f32_e32 v142, v142, v143
	v_xor_b32_e32 v143, 32, v193
	v_cmp_lt_i32_e32 vcc, v143, v144
	s_nop 1
	v_cndmask_b32_e32 v143, v193, v143, vcc
	v_lshlrev_b32_e32 v143, 2, v143
	ds_bpermute_b32 v143, v143, v142
	s_waitcnt lgkmcnt(0)
	v_add_f32_e32 v142, v142, v143
	v_fmamk_f32 v142, v142, 0x3c800000, v192
	v_rsq_f32_e32 v142, v142
; __device__ __forceinline__ unsigned pkh(float lo, float hi) { f32x2 v = {lo, hi}; h16x2 h = __builtin_convertvector(v, h16x2); return __builtin_bit_cast(unsigned, h); }
;     __device__ __forceinline__ void operator()(f32x4 (&acc)[2][2][4][2], const Unit& u, const Order& S, int wr, int wc, int fr_, int fq_, LAS unsigned char*, int) const {
;     ...
;         for (int ai = 0; ai < 2; ++ai)
; #pragma unroll
;             for (int m = 0; m < 4; ++m) {
;                 const int row = row0 + ai * HALF + m * 16;
;                 const float sc = __builtin_amdgcn_rsqf(ss_in[row] * (1.0f / DM) + EPS) * pre;
;                 f32x4 v[2][2]; float sq = 0.f;
; #pragma unroll
;                 for (int bj = 0; bj < 2; ++bj)
; #pragma unroll
;                     for (int n = 0; n < 2; ++n) { v[bj][n] = acc[ai][bj][m][n] * sc; const f32x4 t = v[bj][n]; sq += (t[0] * t[0] + t[1] * t[1]) + (t[2] * t[2] + t[3] * t[3]); }
;                 float rn = 1.f;
;                 if (nrm) { sq += __shfl_xor(sq, 16); sq += __shfl_xor(sq, 32); rn = __builtin_amdgcn_rsqf(sq * (1.0f / HD) + EPS); }
; #pragma unroll
;                 for (int bj = 0; bj < 2; ++bj) {
;                     const f32x4 a = v[bj][0] * rn * gv[bj][0], b = v[bj][1] * rn * gv[bj][1];
;                     ks[bj][0] += a; ks[bj][1] += b;
;                     u32x4 w; w.x = pkh(a[0], a[1]); w.y = pkh(a[2], a[3]); w.z = pkh(b[0], b[1]); w.w = pkh(b[2], b[3]);
;                     *(u32x4*)(P + (size_t)row * NB + colh + 32 * bj + 8 * fq) = w;
;                 }
.LBB0_769:
	v_add_u32_e32 v143, 48, v178
	v_pk_mul_f32 v[112:113], v[112:113], v[142:143] op_sel_hi:[1,0]
	v_pk_mul_f32 v[144:145], v[110:111], v[142:143] op_sel_hi:[1,0]
	v_pk_mul_f32 v[110:111], v[8:9], v[112:113]
	v_pk_mul_f32 v[112:113], v[6:7], v[144:145]
	v_pk_mul_f32 v[108:109], v[108:109], v[142:143] op_sel_hi:[1,0]
	v_pk_mul_f32 v[144:145], v[106:107], v[142:143] op_sel_hi:[1,0]
	v_pk_mul_f32 v[106:107], v[4:5], v[108:109]
	v_pk_mul_f32 v[108:109], v[2:3], v[144:145]
	v_mov_b64_e32 v[144:145], s[58:59]
	v_mad_i64_i32 v[144:145], s[28:29], v143, s51, v[144:145]
	v_lshl_add_u64 v[144:145], s[26:27], 1, v[144:145]
	v_lshl_add_u64 v[156:157], v[24:25], 1, v[144:145]
	v_pk_mul_f32 v[104:105], v[104:105], v[142:143] op_sel_hi:[1,0]
	v_pk_mul_f32 v[144:145], v[102:103], v[142:143] op_sel_hi:[1,0]
	v_pk_mul_f32 v[100:101], v[100:101], v[142:143] op_sel_hi:[1,0]
	v_pk_mul_f32 v[142:143], v[98:99], v[142:143] op_sel_hi:[1,0]
	v_pk_mul_f32 v[102:103], v[16:17], v[104:105]
	v_pk_mul_f32 v[104:105], v[14:15], v[144:145]
	v_pk_mul_f32 v[98:99], v[12:13], v[100:101]
	v_pk_mul_f32 v[100:101], v[10:11], v[142:143]
	v_cvt_pk_f16_f32 v152, v112, v113
	v_cvt_pk_f16_f32 v153, v110, v111
	v_cvt_pk_f16_f32 v154, v108, v109
	v_cvt_pk_f16_f32 v155, v106, v107
	v_cvt_pk_f16_f32 v142, v104, v105
	v_cvt_pk_f16_f32 v143, v102, v103
	v_cvt_pk_f16_f32 v144, v100, v101
	v_cvt_pk_f16_f32 v145, v98, v99
	global_store_dwordx4 v[156:157], v[152:155], off sc1
	global_store_dwordx4 v[156:157], v[142:145], off offset:64 sc1
	global_load_dword v142, v[180:181], off offset:512
	s_and_b64 vcc, exec, s[2:3]
	s_waitcnt vmcnt(0)
	v_fmamk_f32 v142, v142, 0x3a800000, v192
	v_rsq_f32_e32 v143, v142
	v_mov_b32_e32 v142, 1.0
	v_mul_f32_e32 v144, 0x39800000, v143
	v_pk_mul_f32 v[96:97], v[96:97], v[144:145] op_sel_hi:[1,0]
	v_pk_mul_f32 v[94:95], v[94:95], v[144:145] op_sel_hi:[1,0]
	v_pk_mul_f32 v[92:93], v[92:93], v[144:145] op_sel_hi:[1,0]
	v_pk_mul_f32 v[90:91], v[90:91], v[144:145] op_sel_hi:[1,0]
	v_pk_mul_f32 v[88:89], v[88:89], v[144:145] op_sel_hi:[1,0]
	v_pk_mul_f32 v[86:87], v[86:87], v[144:145] op_sel_hi:[1,0]
	v_pk_mul_f32 v[84:85], v[84:85], v[144:145] op_sel_hi:[1,0]
	v_pk_mul_f32 v[82:83], v[82:83], v[144:145] op_sel_hi:[1,0]
	v_mov_b32_e32 v144, 1.0
	s_cbranch_vccnz .LBB0_771
	v_pk_mul_f32 v[144:145], v[96:97], v[96:97]
	v_pk_mul_f32 v[152:153], v[94:95], v[94:95]
	s_nop 0
	v_pk_mov_b32 v[154:155], v[152:153], v[144:145] op_sel:[1,0]
	v_mov_b32_e32 v153, v145
	v_pk_add_f32 v[144:145], v[154:155], v[152:153]
	v_pk_mul_f32 v[152:153], v[92:93], v[92:93]
	v_pk_add_f32 v[144:145], v[144:145], v[144:145] op_sel_hi:[0,1]
	v_pk_mul_f32 v[154:155], v[90:91], v[90:91]
	v_mul_f32_e32 v144, v86, v86
	v_pk_mov_b32 v[156:157], v[154:155], v[152:153] op_sel:[1,0]
	v_mov_b32_e32 v155, v153
	v_pk_add_f32 v[152:153], v[156:157], v[154:155]
	v_pk_fma_f32 v[154:155], v[86:87], v[86:87], v[144:145] op_sel_hi:[1,1,0]
	v_mul_f32_e32 v144, v88, v88
	v_pk_add_f32 v[152:153], v[152:153], v[152:153] op_sel_hi:[0,1]
	v_pk_fma_f32 v[156:157], v[88:89], v[88:89], v[144:145] op_sel_hi:[1,1,0]
	v_mul_f32_e32 v154, v82, v82
	v_mul_f32_e32 v156, v83, v83
	v_mul_f32_e32 v144, v84, v84
	v_mul_f32_e32 v152, v85, v85
	v_pk_add_f32 v[154:155], v[154:155], v[156:157]
	v_pk_add_f32 v[144:145], v[144:145], v[152:153]
	s_nop 0
	v_pk_add_f32 v[144:145], v[154:155], v[144:145]
	s_nop 0
	v_add_f32_e32 v143, v144, v145
	v_and_b32_e32 v145, 64, v193
	v_xor_b32_e32 v144, 16, v193
	v_add_u32_e32 v145, 64, v145
	v_cmp_lt_i32_e32 vcc, v144, v145
	s_nop 1
	v_cndmask_b32_e32 v144, v193, v144, vcc
	v_lshlrev_b32_e32 v144, 2, v144
	ds_bpermute_b32 v144, v144, v143
	s_waitcnt lgkmcnt(0)
	v_add_f32_e32 v143, v143, v144
	v_xor_b32_e32 v144, 32, v193
	v_cmp_lt_i32_e32 vcc, v144, v145
	s_nop 1
	v_cndmask_b32_e32 v144, v193, v144, vcc
	v_lshlrev_b32_e32 v144, 2, v144
	ds_bpermute_b32 v144, v144, v143
	s_waitcnt lgkmcnt(0)
	v_add_f32_e32 v143, v143, v144
	v_fmamk_f32 v143, v143, 0x3c800000, v192
	v_rsq_f32_e32 v144, v143
.LBB0_771:
	v_add_u32_e32 v143, 0x80, v178
	v_pk_mul_f32 v[96:97], v[96:97], v[144:145] op_sel_hi:[1,0]
	v_pk_mul_f32 v[152:153], v[94:95], v[144:145] op_sel_hi:[1,0]
	v_mov_b64_e32 v[156:157], s[58:59]
	v_pk_mul_f32 v[94:95], v[8:9], v[96:97]
	v_pk_mul_f32 v[96:97], v[6:7], v[152:153]
	v_pk_mul_f32 v[92:93], v[92:93], v[144:145] op_sel_hi:[1,0]
	v_pk_mul_f32 v[152:153], v[90:91], v[144:145] op_sel_hi:[1,0]
	v_mad_i64_i32 v[156:157], s[28:29], v143, s51, v[156:157]
	v_pk_mul_f32 v[90:91], v[4:5], v[92:93]
	v_pk_mul_f32 v[92:93], v[2:3], v[152:153]
	v_lshl_add_u64 v[156:157], s[26:27], 1, v[156:157]
	v_cvt_pk_f16_f32 v152, v96, v97
	v_cvt_pk_f16_f32 v153, v94, v95
	v_cvt_pk_f16_f32 v154, v92, v93
	v_cvt_pk_f16_f32 v155, v90, v91
	v_lshl_add_u64 v[156:157], v[24:25], 1, v[156:157]
	global_store_dwordx4 v[156:157], v[152:155], off sc1
	v_pk_mul_f32 v[88:89], v[88:89], v[144:145] op_sel_hi:[1,0]
	v_pk_mul_f32 v[84:85], v[84:85], v[144:145] op_sel_hi:[1,0]
	v_pk_mul_f32 v[152:153], v[86:87], v[144:145] op_sel_hi:[1,0]
	v_pk_mul_f32 v[144:145], v[82:83], v[144:145] op_sel_hi:[1,0]
	v_pk_mul_f32 v[86:87], v[16:17], v[88:89]
	v_pk_mul_f32 v[88:89], v[14:15], v[152:153]
	v_pk_mul_f32 v[82:83], v[12:13], v[84:85]
	v_pk_mul_f32 v[84:85], v[10:11], v[144:145]
	v_cvt_pk_f16_f32 v152, v88, v89
	v_cvt_pk_f16_f32 v153, v86, v87
	v_cvt_pk_f16_f32 v154, v84, v85
	v_cvt_pk_f16_f32 v155, v82, v83
	global_store_dwordx4 v[156:157], v[152:155], off offset:64 sc1
	global_load_dword v143, v[180:181], off offset:576
	s_and_b64 vcc, exec, s[2:3]
	s_waitcnt vmcnt(0)
	v_fmamk_f32 v143, v143, 0x3a800000, v192
	v_rsq_f32_e32 v143, v143
	s_nop 0
	v_mul_f32_e32 v144, 0x39800000, v143
	v_pk_mul_f32 v[80:81], v[80:81], v[144:145] op_sel_hi:[1,0]
	v_pk_mul_f32 v[78:79], v[78:79], v[144:145] op_sel_hi:[1,0]
	v_pk_mul_f32 v[76:77], v[76:77], v[144:145] op_sel_hi:[1,0]
	v_pk_mul_f32 v[74:75], v[74:75], v[144:145] op_sel_hi:[1,0]
	v_pk_mul_f32 v[72:73], v[72:73], v[144:145] op_sel_hi:[1,0]
	v_pk_mul_f32 v[70:71], v[70:71], v[144:145] op_sel_hi:[1,0]
	v_pk_mul_f32 v[68:69], v[68:69], v[144:145] op_sel_hi:[1,0]
	v_pk_mul_f32 v[66:67], v[66:67], v[144:145] op_sel_hi:[1,0]
	s_cbranch_vccnz .LBB0_773
; __device__ __forceinline__ unsigned pkh(float lo, float hi) { f32x2 v = {lo, hi}; h16x2 h = __builtin_convertvector(v, h16x2); return __builtin_bit_cast(unsigned, h); }
;     __device__ __forceinline__ void operator()(f32x4 (&acc)[2][2][4][2], const Unit& u, const Order& S, int wr, int wc, int fr_, int fq_, LAS unsigned char*, int) const {
;     ...
;         for (int ai = 0; ai < 2; ++ai)
; #pragma unroll
;             for (int m = 0; m < 4; ++m) {
;                 const int row = row0 + ai * HALF + m * 16;
;                 const float sc = __builtin_amdgcn_rsqf(ss_in[row] * (1.0f / DM) + EPS) * pre;
;                 f32x4 v[2][2]; float sq = 0.f;
; #pragma unroll
;                 for (int bj = 0; bj < 2; ++bj)
; #pragma unroll
;                     for (int n = 0; n < 2; ++n) { v[bj][n] = acc[ai][bj][m][n] * sc; const f32x4 t = v[bj][n]; sq += (t[0] * t[0] + t[1] * t[1]) + (t[2] * t[2] + t[3] * t[3]); }
;                 float rn = 1.f;
;                 if (nrm) { sq += __shfl_xor(sq, 16); sq += __shfl_xor(sq, 32); rn = __builtin_amdgcn_rsqf(sq * (1.0f / HD) + EPS); }
; #pragma unroll
;                 for (int bj = 0; bj < 2; ++bj) {
;                     const f32x4 a = v[bj][0] * rn * gv[bj][0], b = v[bj][1] * rn * gv[bj][1];
;                     ks[bj][0] += a; ks[bj][1] += b;
;                     u32x4 w; w.x = pkh(a[0], a[1]); w.y = pkh(a[2], a[3]); w.z = pkh(b[0], b[1]); w.w = pkh(b[2], b[3]);
;                     *(u32x4*)(P + (size_t)row * NB + colh + 32 * bj + 8 * fq) = w;
;                 }
	v_pk_mul_f32 v[142:143], v[80:81], v[80:81]
	v_pk_mul_f32 v[144:145], v[78:79], v[78:79]
	s_nop 0
	v_pk_mov_b32 v[152:153], v[144:145], v[142:143] op_sel:[1,0]
	v_mov_b32_e32 v145, v143
	v_pk_add_f32 v[142:143], v[152:153], v[144:145]
	v_pk_mul_f32 v[144:145], v[76:77], v[76:77]
	v_pk_add_f32 v[142:143], v[142:143], v[142:143] op_sel_hi:[0,1]
	v_pk_mul_f32 v[152:153], v[74:75], v[74:75]
	v_mul_f32_e32 v142, v70, v70
	v_pk_mov_b32 v[154:155], v[152:153], v[144:145] op_sel:[1,0]
	v_mov_b32_e32 v153, v145
	v_pk_add_f32 v[144:145], v[154:155], v[152:153]
	v_pk_fma_f32 v[152:153], v[70:71], v[70:71], v[142:143] op_sel_hi:[1,1,0]
	v_mul_f32_e32 v142, v72, v72
	v_pk_add_f32 v[144:145], v[144:145], v[144:145] op_sel_hi:[0,1]
	v_pk_fma_f32 v[154:155], v[72:73], v[72:73], v[142:143] op_sel_hi:[1,1,0]
	v_mul_f32_e32 v152, v66, v66
	v_mul_f32_e32 v154, v67, v67
	v_mul_f32_e32 v142, v68, v68
	v_mul_f32_e32 v144, v69, v69
	v_pk_add_f32 v[152:153], v[152:153], v[154:155]
	v_pk_add_f32 v[142:143], v[142:143], v[144:145]
	v_and_b32_e32 v144, 64, v193
	v_pk_add_f32 v[142:143], v[152:153], v[142:143]
	v_add_u32_e32 v144, 64, v144
	v_add_f32_e32 v142, v142, v143
	v_xor_b32_e32 v143, 16, v193
	v_cmp_lt_i32_e32 vcc, v143, v144
	s_nop 1
	v_cndmask_b32_e32 v143, v193, v143, vcc
	v_lshlrev_b32_e32 v143, 2, v143
	ds_bpermute_b32 v143, v143, v142
	s_waitcnt lgkmcnt(0)
	v_add_f32_e32 v142, v142, v143
	v_xor_b32_e32 v143, 32, v193
	v_cmp_lt_i32_e32 vcc, v143, v144
	s_nop 1
	v_cndmask_b32_e32 v143, v193, v143, vcc
	v_lshlrev_b32_e32 v143, 2, v143
	ds_bpermute_b32 v143, v143, v142
	s_waitcnt lgkmcnt(0)
	v_add_f32_e32 v142, v142, v143
	v_fmamk_f32 v142, v142, 0x3c800000, v192
	v_rsq_f32_e32 v142, v142
.LBB0_773:
	v_add_u32_e32 v143, 0x90, v178
	v_pk_mul_f32 v[80:81], v[80:81], v[142:143] op_sel_hi:[1,0]
	v_pk_mul_f32 v[144:145], v[78:79], v[142:143] op_sel_hi:[1,0]
	v_pk_mul_f32 v[78:79], v[8:9], v[80:81]
	v_pk_mul_f32 v[80:81], v[6:7], v[144:145]
	v_pk_mul_f32 v[76:77], v[76:77], v[142:143] op_sel_hi:[1,0]
	v_pk_mul_f32 v[144:145], v[74:75], v[142:143] op_sel_hi:[1,0]
	v_pk_mul_f32 v[74:75], v[4:5], v[76:77]
	v_pk_mul_f32 v[76:77], v[2:3], v[144:145]
	v_mov_b64_e32 v[144:145], s[58:59]
	v_mad_i64_i32 v[144:145], s[28:29], v143, s51, v[144:145]
	v_lshl_add_u64 v[144:145], s[26:27], 1, v[144:145]
	v_lshl_add_u64 v[156:157], v[24:25], 1, v[144:145]
	v_pk_mul_f32 v[72:73], v[72:73], v[142:143] op_sel_hi:[1,0]
	v_pk_mul_f32 v[144:145], v[70:71], v[142:143] op_sel_hi:[1,0]
	v_pk_mul_f32 v[68:69], v[68:69], v[142:143] op_sel_hi:[1,0]
	v_pk_mul_f32 v[142:143], v[66:67], v[142:143] op_sel_hi:[1,0]
	v_pk_mul_f32 v[70:71], v[16:17], v[72:73]
	v_pk_mul_f32 v[72:73], v[14:15], v[144:145]
	v_pk_mul_f32 v[66:67], v[12:13], v[68:69]
	v_pk_mul_f32 v[68:69], v[10:11], v[142:143]
	v_cvt_pk_f16_f32 v152, v80, v81
	v_cvt_pk_f16_f32 v153, v78, v79
	v_cvt_pk_f16_f32 v154, v76, v77
	v_cvt_pk_f16_f32 v155, v74, v75
	v_cvt_pk_f16_f32 v142, v72, v73
	v_cvt_pk_f16_f32 v143, v70, v71
	v_cvt_pk_f16_f32 v144, v68, v69
	v_cvt_pk_f16_f32 v145, v66, v67
	global_store_dwordx4 v[156:157], v[152:155], off sc1
	global_store_dwordx4 v[156:157], v[142:145], off offset:64 sc1
	global_load_dword v142, v[180:181], off offset:640
	s_and_b64 vcc, exec, s[2:3]
	s_waitcnt vmcnt(0)
	v_fmamk_f32 v142, v142, 0x3a800000, v192
	v_rsq_f32_e32 v143, v142
	v_mov_b32_e32 v142, 1.0
	v_mul_f32_e32 v144, 0x39800000, v143
	v_pk_mul_f32 v[64:65], v[64:65], v[144:145] op_sel_hi:[1,0]
	v_pk_mul_f32 v[62:63], v[62:63], v[144:145] op_sel_hi:[1,0]
	v_pk_mul_f32 v[60:61], v[60:61], v[144:145] op_sel_hi:[1,0]
	v_pk_mul_f32 v[58:59], v[58:59], v[144:145] op_sel_hi:[1,0]
	v_pk_mul_f32 v[56:57], v[56:57], v[144:145] op_sel_hi:[1,0]
	v_pk_mul_f32 v[54:55], v[54:55], v[144:145] op_sel_hi:[1,0]
	v_pk_mul_f32 v[52:53], v[52:53], v[144:145] op_sel_hi:[1,0]
	v_pk_mul_f32 v[50:51], v[50:51], v[144:145] op_sel_hi:[1,0]
	v_mov_b32_e32 v144, 1.0
	s_cbranch_vccnz .LBB0_775
	v_pk_mul_f32 v[144:145], v[64:65], v[64:65]
	v_pk_mul_f32 v[152:153], v[62:63], v[62:63]
	s_nop 0
	v_pk_mov_b32 v[154:155], v[152:153], v[144:145] op_sel:[1,0]
	v_mov_b32_e32 v153, v145
	v_pk_add_f32 v[144:145], v[154:155], v[152:153]
	v_pk_mul_f32 v[152:153], v[60:61], v[60:61]
	v_pk_add_f32 v[144:145], v[144:145], v[144:145] op_sel_hi:[0,1]
	v_pk_mul_f32 v[154:155], v[58:59], v[58:59]
	v_mul_f32_e32 v144, v54, v54
	v_pk_mov_b32 v[156:157], v[154:155], v[152:153] op_sel:[1,0]
	v_mov_b32_e32 v155, v153
	v_pk_add_f32 v[152:153], v[156:157], v[154:155]
	v_pk_fma_f32 v[154:155], v[54:55], v[54:55], v[144:145] op_sel_hi:[1,1,0]
	v_mul_f32_e32 v144, v56, v56
	v_pk_add_f32 v[152:153], v[152:153], v[152:153] op_sel_hi:[0,1]
	v_pk_fma_f32 v[156:157], v[56:57], v[56:57], v[144:145] op_sel_hi:[1,1,0]
	v_mul_f32_e32 v154, v50, v50
	v_mul_f32_e32 v156, v51, v51
	v_mul_f32_e32 v144, v52, v52
	v_mul_f32_e32 v152, v53, v53
	v_pk_add_f32 v[154:155], v[154:155], v[156:157]
	v_pk_add_f32 v[144:145], v[144:145], v[152:153]
	s_nop 0
	v_pk_add_f32 v[144:145], v[154:155], v[144:145]
	s_nop 0
	v_add_f32_e32 v143, v144, v145
	v_and_b32_e32 v145, 64, v193
	v_xor_b32_e32 v144, 16, v193
	v_add_u32_e32 v145, 64, v145
	v_cmp_lt_i32_e32 vcc, v144, v145
	s_nop 1
	v_cndmask_b32_e32 v144, v193, v144, vcc
	v_lshlrev_b32_e32 v144, 2, v144
	ds_bpermute_b32 v144, v144, v143
	s_waitcnt lgkmcnt(0)
	v_add_f32_e32 v143, v143, v144
	v_xor_b32_e32 v144, 32, v193
	v_cmp_lt_i32_e32 vcc, v144, v145
	s_nop 1
	v_cndmask_b32_e32 v144, v193, v144, vcc
	v_lshlrev_b32_e32 v144, 2, v144
	ds_bpermute_b32 v144, v144, v143
	s_waitcnt lgkmcnt(0)
	v_add_f32_e32 v143, v143, v144
	v_fmamk_f32 v143, v143, 0x3c800000, v192
	v_rsq_f32_e32 v144, v143
; __device__ __forceinline__ unsigned pkh(float lo, float hi) { f32x2 v = {lo, hi}; h16x2 h = __builtin_convertvector(v, h16x2); return __builtin_bit_cast(unsigned, h); }
;     __device__ __forceinline__ void operator()(f32x4 (&acc)[2][2][4][2], const Unit& u, const Order& S, int wr, int wc, int fr_, int fq_, LAS unsigned char*, int) const {
;     ...
;         for (int ai = 0; ai < 2; ++ai)
; #pragma unroll
;             for (int m = 0; m < 4; ++m) {
;                 const int row = row0 + ai * HALF + m * 16;
;                 const float sc = __builtin_amdgcn_rsqf(ss_in[row] * (1.0f / DM) + EPS) * pre;
;                 f32x4 v[2][2]; float sq = 0.f;
; #pragma unroll
;                 for (int bj = 0; bj < 2; ++bj)
; #pragma unroll
;                     for (int n = 0; n < 2; ++n) { v[bj][n] = acc[ai][bj][m][n] * sc; const f32x4 t = v[bj][n]; sq += (t[0] * t[0] + t[1] * t[1]) + (t[2] * t[2] + t[3] * t[3]); }
;                 float rn = 1.f;
;                 if (nrm) { sq += __shfl_xor(sq, 16); sq += __shfl_xor(sq, 32); rn = __builtin_amdgcn_rsqf(sq * (1.0f / HD) + EPS); }
; #pragma unroll
;                 for (int bj = 0; bj < 2; ++bj) {
;                     const f32x4 a = v[bj][0] * rn * gv[bj][0], b = v[bj][1] * rn * gv[bj][1];
;                     ks[bj][0] += a; ks[bj][1] += b;
;                     u32x4 w; w.x = pkh(a[0], a[1]); w.y = pkh(a[2], a[3]); w.z = pkh(b[0], b[1]); w.w = pkh(b[2], b[3]);
;                     *(u32x4*)(P + (size_t)row * NB + colh + 32 * bj + 8 * fq) = w;
;                 }
.LBB0_775:
	v_add_u32_e32 v143, 0xa0, v178
	v_pk_mul_f32 v[64:65], v[64:65], v[144:145] op_sel_hi:[1,0]
	v_pk_mul_f32 v[152:153], v[62:63], v[144:145] op_sel_hi:[1,0]
	v_mov_b64_e32 v[156:157], s[58:59]
	v_pk_mul_f32 v[62:63], v[8:9], v[64:65]
	v_pk_mul_f32 v[64:65], v[6:7], v[152:153]
	v_pk_mul_f32 v[60:61], v[60:61], v[144:145] op_sel_hi:[1,0]
	v_pk_mul_f32 v[152:153], v[58:59], v[144:145] op_sel_hi:[1,0]
	v_mad_i64_i32 v[156:157], s[28:29], v143, s51, v[156:157]
	v_pk_mul_f32 v[58:59], v[4:5], v[60:61]
	v_pk_mul_f32 v[60:61], v[2:3], v[152:153]
	v_lshl_add_u64 v[156:157], s[26:27], 1, v[156:157]
	v_cvt_pk_f16_f32 v152, v64, v65
	v_cvt_pk_f16_f32 v153, v62, v63
	v_cvt_pk_f16_f32 v154, v60, v61
	v_cvt_pk_f16_f32 v155, v58, v59
	v_lshl_add_u64 v[156:157], v[24:25], 1, v[156:157]
	global_store_dwordx4 v[156:157], v[152:155], off sc1
	v_pk_mul_f32 v[56:57], v[56:57], v[144:145] op_sel_hi:[1,0]
	v_pk_mul_f32 v[52:53], v[52:53], v[144:145] op_sel_hi:[1,0]
	v_pk_mul_f32 v[152:153], v[54:55], v[144:145] op_sel_hi:[1,0]
	v_pk_mul_f32 v[144:145], v[50:51], v[144:145] op_sel_hi:[1,0]
	v_pk_mul_f32 v[54:55], v[16:17], v[56:57]
	v_pk_mul_f32 v[56:57], v[14:15], v[152:153]
	v_pk_mul_f32 v[50:51], v[12:13], v[52:53]
	v_pk_mul_f32 v[52:53], v[10:11], v[144:145]
	v_cvt_pk_f16_f32 v152, v56, v57
	v_cvt_pk_f16_f32 v153, v54, v55
	v_cvt_pk_f16_f32 v154, v52, v53
	v_cvt_pk_f16_f32 v155, v50, v51
	global_store_dwordx4 v[156:157], v[152:155], off offset:64 sc1
	global_load_dword v143, v[180:181], off offset:704
	s_and_b64 vcc, exec, s[2:3]
	s_waitcnt vmcnt(0)
	v_fmamk_f32 v143, v143, 0x3a800000, v192
	v_rsq_f32_e32 v143, v143
	s_nop 0
	v_mul_f32_e32 v156, 0x39800000, v143
	v_pk_mul_f32 v[152:153], v[48:49], v[156:157] op_sel_hi:[1,0]
	v_pk_mul_f32 v[154:155], v[46:47], v[156:157] op_sel_hi:[1,0]
	v_pk_mul_f32 v[48:49], v[44:45], v[156:157] op_sel_hi:[1,0]
	v_pk_mul_f32 v[144:145], v[42:43], v[156:157] op_sel_hi:[1,0]
	v_pk_mul_f32 v[44:45], v[40:41], v[156:157] op_sel_hi:[1,0]
	v_pk_mul_f32 v[46:47], v[38:39], v[156:157] op_sel_hi:[1,0]
	v_pk_mul_f32 v[40:41], v[36:37], v[156:157] op_sel_hi:[1,0]
	v_pk_mul_f32 v[42:43], v[34:35], v[156:157] op_sel_hi:[1,0]
	s_cbranch_vccnz .LBB0_777
	v_pk_mul_f32 v[34:35], v[152:153], v[152:153]
	v_pk_mul_f32 v[36:37], v[154:155], v[154:155]
	s_nop 0
	v_pk_mov_b32 v[38:39], v[36:37], v[34:35] op_sel:[1,0]
	v_mov_b32_e32 v37, v35
	v_pk_add_f32 v[34:35], v[38:39], v[36:37]
	v_pk_mul_f32 v[36:37], v[48:49], v[48:49]
	v_pk_add_f32 v[34:35], v[34:35], v[34:35] op_sel_hi:[0,1]
	v_pk_mul_f32 v[38:39], v[144:145], v[144:145]
	v_mul_f32_e32 v34, v46, v46
	v_pk_mov_b32 v[142:143], v[38:39], v[36:37] op_sel:[1,0]
	v_mov_b32_e32 v39, v37
	v_pk_add_f32 v[36:37], v[142:143], v[38:39]
	v_pk_fma_f32 v[38:39], v[46:47], v[46:47], v[34:35] op_sel_hi:[1,1,0]
	v_mul_f32_e32 v34, v44, v44
	v_pk_add_f32 v[36:37], v[36:37], v[36:37] op_sel_hi:[0,1]
	v_pk_fma_f32 v[142:143], v[44:45], v[44:45], v[34:35] op_sel_hi:[1,1,0]
	v_mul_f32_e32 v38, v42, v42
	v_mul_f32_e32 v142, v43, v43
	v_mul_f32_e32 v34, v40, v40
	v_mul_f32_e32 v36, v41, v41
	v_pk_add_f32 v[38:39], v[38:39], v[142:143]
	v_pk_add_f32 v[34:35], v[34:35], v[36:37]
	v_and_b32_e32 v36, 64, v193
	v_pk_add_f32 v[34:35], v[38:39], v[34:35]
	v_add_u32_e32 v36, 64, v36
	v_add_f32_e32 v34, v34, v35
	v_xor_b32_e32 v35, 16, v193
	v_cmp_lt_i32_e32 vcc, v35, v36
	s_nop 1
	v_cndmask_b32_e32 v35, v193, v35, vcc
	v_lshlrev_b32_e32 v35, 2, v35
	ds_bpermute_b32 v35, v35, v34
	s_waitcnt lgkmcnt(0)
	v_add_f32_e32 v34, v34, v35
	v_xor_b32_e32 v35, 32, v193
	v_cmp_lt_i32_e32 vcc, v35, v36
	s_nop 1
	v_cndmask_b32_e32 v35, v193, v35, vcc
	v_lshlrev_b32_e32 v35, 2, v35
	ds_bpermute_b32 v35, v35, v34
	s_waitcnt lgkmcnt(0)
	v_add_f32_e32 v34, v34, v35
	v_fmamk_f32 v34, v34, 0x3c800000, v192
	v_rsq_f32_e32 v142, v34
; __device__ __forceinline__ unsigned pkh(float lo, float hi) { f32x2 v = {lo, hi}; h16x2 h = __builtin_convertvector(v, h16x2); return __builtin_bit_cast(unsigned, h); }
;     __device__ __forceinline__ void operator()(f32x4 (&acc)[2][2][4][2], const Unit& u, const Order& S, int wr, int wc, int fr_, int fq_, LAS unsigned char*, int) const {
;     ...
;         for (int ai = 0; ai < 2; ++ai)
; #pragma unroll
;             for (int m = 0; m < 4; ++m) {
;                 const int row = row0 + ai * HALF + m * 16;
;                 const float sc = __builtin_amdgcn_rsqf(ss_in[row] * (1.0f / DM) + EPS) * pre;
;                 f32x4 v[2][2]; float sq = 0.f;
; #pragma unroll
;                 for (int bj = 0; bj < 2; ++bj)
; #pragma unroll
;                     for (int n = 0; n < 2; ++n) { v[bj][n] = acc[ai][bj][m][n] * sc; const f32x4 t = v[bj][n]; sq += (t[0] * t[0] + t[1] * t[1]) + (t[2] * t[2] + t[3] * t[3]); }
;                 float rn = 1.f;
;                 if (nrm) { sq += __shfl_xor(sq, 16); sq += __shfl_xor(sq, 32); rn = __builtin_amdgcn_rsqf(sq * (1.0f / HD) + EPS); }
; #pragma unroll
;                 for (int bj = 0; bj < 2; ++bj) {
;                     const f32x4 a = v[bj][0] * rn * gv[bj][0], b = v[bj][1] * rn * gv[bj][1];
;                     ks[bj][0] += a; ks[bj][1] += b;
;                     u32x4 w; w.x = pkh(a[0], a[1]); w.y = pkh(a[2], a[3]); w.z = pkh(b[0], b[1]); w.w = pkh(b[2], b[3]);
;                     *(u32x4*)(P + (size_t)row * NB + colh + 32 * bj + 8 * fq) = w;
;                 }
;             }
;         if (isk && !dry) {
;             const int b = u.pm / NBLK, blk = u.pm % NBLK, h = (u.pn - 3) * 4 + wc;
;             float* dst = kmean + ((size_t)(b * MOBA_H + h) * NBLK + blk) * HD;
; #pragma unroll
;             for (int bj = 0; bj < 2; ++bj)
; #pragma unroll
;                 for (int n = 0; n < 2; ++n)
; #pragma unroll
;                     for (int e = 0; e < 4; ++e) {
;                         float s = ks[bj][n][e];
;                         s += __shfl_xor(s, 1); s += __shfl_xor(s, 2); s += __shfl_xor(s, 4); s += __shfl_xor(s, 8);
;                         if (fr == 0) atomicAdd(dst + 32 * bj + 8 * fq + 4 * n + e, s);
;                     }
.LBB0_777:
	v_add_u32_e32 v143, 0xb0, v178
	v_pk_mul_f32 v[34:35], v[152:153], v[142:143] op_sel_hi:[1,0]
	v_pk_mul_f32 v[36:37], v[154:155], v[142:143] op_sel_hi:[1,0]
	v_pk_mul_f32 v[38:39], v[8:9], v[34:35]
	v_pk_mul_f32 v[8:9], v[48:49], v[142:143] op_sel_hi:[1,0]
	v_pk_mul_f32 v[6:7], v[6:7], v[36:37]
	v_pk_mul_f32 v[34:35], v[4:5], v[8:9]
	v_mov_b64_e32 v[8:9], s[58:59]
	v_pk_mul_f32 v[36:37], v[144:145], v[142:143] op_sel_hi:[1,0]
	v_mad_i64_i32 v[8:9], s[2:3], v143, s51, v[8:9]
	v_pk_mul_f32 v[36:37], v[2:3], v[36:37]
	v_lshl_add_u64 v[8:9], s[26:27], 1, v[8:9]
	v_cvt_pk_f16_f32 v2, v6, v7
	v_cvt_pk_f16_f32 v3, v38, v39
	v_cvt_pk_f16_f32 v4, v36, v37
	v_cvt_pk_f16_f32 v5, v34, v35
	v_lshl_add_u64 v[48:49], v[24:25], 1, v[8:9]
	global_store_dwordx4 v[48:49], v[2:5], off sc1
	s_andn2_b64 vcc, exec, s[24:25]
	s_nop 0
	v_pk_mul_f32 v[2:3], v[44:45], v[142:143] op_sel_hi:[1,0]
	v_pk_mul_f32 v[4:5], v[46:47], v[142:143] op_sel_hi:[1,0]
	v_pk_mul_f32 v[8:9], v[16:17], v[2:3]
	v_pk_mul_f32 v[14:15], v[14:15], v[4:5]
	v_pk_mul_f32 v[2:3], v[40:41], v[142:143] op_sel_hi:[1,0]
	v_pk_mul_f32 v[4:5], v[42:43], v[142:143] op_sel_hi:[1,0]
	v_pk_mul_f32 v[2:3], v[12:13], v[2:3]
	v_pk_mul_f32 v[4:5], v[10:11], v[4:5]
	v_cvt_pk_f16_f32 v10, v14, v15
	v_cvt_pk_f16_f32 v11, v8, v9
	v_cvt_pk_f16_f32 v12, v4, v5
	v_cvt_pk_f16_f32 v13, v2, v3
	global_store_dwordx4 v[48:49], v[10:13], off offset:64 sc1
	s_cbranch_vccnz .LBB0_811
	s_nop 0
	v_pk_add_f32 v[10:11], v[150:151], 0 op_sel_hi:[1,0]
	v_xor_b32_e32 v13, 2, v193
	v_pk_add_f32 v[10:11], v[10:11], v[140:141]
	v_xor_b32_e32 v16, 4, v193
	v_pk_add_f32 v[10:11], v[10:11], v[128:129]
	s_ashr_i32 s2, s53, 31
	v_pk_add_f32 v[10:11], v[10:11], v[112:113]
	s_lshr_b32 s2, s2, 26
	v_pk_add_f32 v[10:11], v[10:11], v[96:97]
	s_add_i32 s2, s53, s2
	v_pk_add_f32 v[10:11], v[10:11], v[80:81]
	s_ashr_i32 s3, s2, 6
	v_pk_add_f32 v[10:11], v[10:11], v[64:65]
	s_lshl_b32 s17, s22, 2
	v_pk_add_f32 v[10:11], v[10:11], v[6:7]
	v_and_b32_e32 v7, 64, v193
	v_xor_b32_e32 v6, 1, v193
	v_add_u32_e32 v7, 64, v7
	v_cmp_lt_i32_e32 vcc, v6, v7
	s_mul_i32 s3, s3, 12
	s_add_i32 s17, s47, s17
	v_cndmask_b32_e32 v6, v193, v6, vcc
	v_lshlrev_b32_e32 v12, 2, v6
	ds_bpermute_b32 v6, v12, v10
	v_cmp_lt_i32_e32 vcc, v13, v7
	v_xor_b32_e32 v17, 8, v193
	s_andn2_b32 s2, s2, 63
	v_cndmask_b32_e32 v13, v193, v13, vcc
	v_lshlrev_b32_e32 v13, 2, v13
	s_waitcnt lgkmcnt(0)
	v_add_f32_e32 v6, v10, v6
	ds_bpermute_b32 v10, v13, v6
	v_cmp_lt_i32_e32 vcc, v16, v7
	s_add_i32 s24, s17, s3
	s_sub_i32 s2, s53, s2
	v_cndmask_b32_e32 v16, v193, v16, vcc
	v_lshlrev_b32_e32 v16, 2, v16
	s_waitcnt lgkmcnt(0)
	v_add_f32_e32 v6, v6, v10
	ds_bpermute_b32 v10, v16, v6
	v_cmp_lt_i32_e32 vcc, v17, v7
	s_ashr_i32 s25, s24, 31
	s_ashr_i32 s3, s2, 31
	v_cndmask_b32_e32 v7, v193, v17, vcc
	s_lshl_b64 s[24:25], s[24:25], 14
	v_lshlrev_b32_e32 v17, 2, v7
	s_waitcnt lgkmcnt(0)
	v_add_f32_e32 v10, v6, v10
	s_add_u32 s17, s6, s24
	ds_bpermute_b32 v40, v17, v10
	s_addc_u32 s22, s7, s25
	s_lshl_b64 s[2:3], s[2:3], 8
	s_add_u32 s2, s17, s2
	s_addc_u32 s3, s22, s3
	v_cmp_eq_u32_e32 vcc, 0, v182
	v_lshl_add_u64 v[6:7], v[24:25], 2, s[2:3]
	s_and_saveexec_b64 s[2:3], vcc
	s_cbranch_execz .LBB0_780
	s_waitcnt lgkmcnt(0)
	v_add_f32_e32 v10, v10, v40
	global_atomic_add_f32 v[6:7], v10, off

; __device__ __forceinline__ unsigned pkh(float lo, float hi) { f32x2 v = {lo, hi}; h16x2 h = __builtin_convertvector(v, h16x2); return __builtin_bit_cast(unsigned, h); }
; template <class Epi, bool ALIGN_EPI, bool FP8 = false>
; __device__ __forceinline__ void gemm_phase(LAS unsigned char* lds, LAS unsigned char* xl, const Gemm g, const Order& S, const Epi& E) {
;     ...
;         if constexpr (FP8) asm volatile("s_nop 15\n\ts_nop 15" ::: "memory");
;         E(acc, cur, S, wr, wc, fr, fq, xl, ui);
;     __device__ __forceinline__ void operator()(f32x4 (&acc)[2][2][4][2], const Unit& u, const Order& S, int wr, int wc, int fr_, int fq_, LAS unsigned char*, int) const {
;     ...
;         for (int ai = 0; ai < 2; ++ai)
; #pragma unroll
;             for (int m = 0; m < 4; ++m) {
;                 const int row = row0 + ai * HALF + m * 16; const size_t off = (size_t)row * DM + col0;
;                 float sq = 0.f;
; #pragma unroll
;                 for (int bj = 0; bj < 2; ++bj) {
;                     const h16x8 bs = *(const h16x8*)(h16 + off + bj * HALF);
;                     f32x4 o0 = acc[ai][bj][m][0] * pre, o1 = acc[ai][bj][m][1] * pre;
; #pragma unroll
;                     for (int e = 0; e < 4; ++e) { o0[e] += (float)bs[e]; o1[e] += (float)bs[4 + e]; }
;                     if (out32) { if (!dry) { __builtin_nontemporal_store(o0, (f32x4*)(out32 + off + bj * HALF)); __builtin_nontemporal_store(o1, (f32x4*)(out32 + off + bj * HALF + 4)); } }
;                     else if (!dry) {
;                         sq += (o0[0] * o0[0] + o0[1] * o0[1]) + (o0[2] * o0[2] + o0[3] * o0[3]) + (o1[0] * o1[0] + o1[1] * o1[1]) + (o1[2] * o1[2] + o1[3] * o1[3]);
;                         u32x4 w; w.x = pkh(o0[0], o0[1]); w.y = pkh(o0[2], o0[3]); w.z = pkh(o1[0], o1[1]); w.w = pkh(o1[2], o1[3]);
;                         *(u32x4*)(h16 + off + bj * HALF) = w;
;                         if (h8) { u32x2 q; q.x = pk8(o0[0] * F8_SA, o0[1] * F8_SA, o0[2] * F8_SA, o0[3] * F8_SA); q.y = pk8(o1[0] * F8_SA, o1[1] * F8_SA, o1[2] * F8_SA, o1[3] * F8_SA); *(u32x2*)(h8 + off + bj * HALF) = q; } }
;                 }
;                 if (!out32 && !dry) { sq += __shfl_xor(sq, 16); sq += __shfl_xor(sq, 32); if (fq == 0) atomicAdd(ss_out + row, sq); }
.LBB0_1326:
	s_lshl_b32 s3, s46, 8
	v_mov_b32_e32 v8, v187
	v_mov_b32_e32 v2, v186
	s_add_i32 s3, s3, s39
	s_nop 15
	s_nop 15
	s_lshl_b32 s2, s2, 8
	v_add_u32_e32 v4, s3, v2
	s_or_b32 s2, s2, s40
	v_ashrrev_i32_e32 v5, 31, v4
	v_lshl_add_u32 v2, v8, 3, s2
	v_lshlrev_b64 v[6:7], 11, v[4:5]
	v_ashrrev_i32_e32 v3, 31, v2
	v_lshl_add_u64 v[6:7], s[90:91], 0, v[6:7]
	v_lshl_add_u64 v[18:19], v[2:3], 1, v[6:7]
	global_load_dwordx4 v[10:13], v[18:19], off
	global_load_dwordx4 v[14:17], v[18:19], off offset:256
	v_and_b32_e32 v7, 64, v192
	v_xor_b32_e32 v6, 16, v192
	v_add_u32_e32 v7, 64, v7
	v_cmp_lt_i32_e64 s[2:3], v6, v7
	v_xor_b32_e32 v9, 32, v192
	v_cmp_eq_u32_e32 vcc, 0, v8
	v_cndmask_b32_e64 v6, v192, v6, s[2:3]
	v_cmp_lt_i32_e64 s[2:3], v9, v7
	v_lshlrev_b32_e32 v8, 2, v6
	s_waitcnt vmcnt(0)
	v_cvt_f32_f16_e32 v6, v10
	v_cvt_f32_f16_sdwa v7, v10 dst_sel:DWORD dst_unused:UNUSED_PAD src0_sel:WORD_1
	v_cvt_f32_f16_e32 v10, v11
	v_cvt_f32_f16_sdwa v11, v11 dst_sel:DWORD dst_unused:UNUSED_PAD src0_sel:WORD_1
	v_cvt_f32_f16_e32 v22, v14
	v_cvt_f32_f16_sdwa v23, v14 dst_sel:DWORD dst_unused:UNUSED_PAD src0_sel:WORD_1
	v_cvt_f32_f16_e32 v14, v15
	v_cvt_f32_f16_sdwa v15, v15 dst_sel:DWORD dst_unused:UNUSED_PAD src0_sel:WORD_1
	v_cvt_f32_f16_e32 v20, v12
	v_cvt_f32_f16_sdwa v21, v12 dst_sel:DWORD dst_unused:UNUSED_PAD src0_sel:WORD_1
	v_cvt_f32_f16_e32 v12, v13
	v_cvt_f32_f16_sdwa v13, v13 dst_sel:DWORD dst_unused:UNUSED_PAD src0_sel:WORD_1
	v_cvt_f32_f16_e32 v24, v16
	v_cvt_f32_f16_sdwa v25, v16 dst_sel:DWORD dst_unused:UNUSED_PAD src0_sel:WORD_1
	v_cvt_f32_f16_e32 v16, v17
	v_cvt_f32_f16_sdwa v17, v17 dst_sel:DWORD dst_unused:UNUSED_PAD src0_sel:WORD_1
	v_pk_fma_f32 v[6:7], v[158:159], s[12:13], v[6:7] op_sel_hi:[1,0,1]
	v_pk_fma_f32 v[26:27], v[160:161], s[12:13], v[10:11] op_sel_hi:[1,0,1]
	v_pk_fma_f32 v[22:23], v[150:151], s[12:13], v[22:23] op_sel_hi:[1,0,1]
	v_pk_fma_f32 v[30:31], v[152:153], s[12:13], v[14:15] op_sel_hi:[1,0,1]
	v_pk_fma_f32 v[20:21], v[154:155], s[12:13], v[20:21] op_sel_hi:[1,0,1]
	v_pk_fma_f32 v[28:29], v[156:157], s[12:13], v[12:13] op_sel_hi:[1,0,1]
	v_pk_fma_f32 v[24:25], v[146:147], s[12:13], v[24:25] op_sel_hi:[1,0,1]
	v_pk_mul_f32 v[12:13], v[6:7], v[6:7]
	v_pk_mul_f32 v[14:15], v[26:27], v[26:27]
	v_cvt_pk_f16_f32 v10, v6, v7
	v_cvt_pk_f16_f32 v11, v26, v27
	v_pk_mul_f32 v[6:7], v[22:23], v[22:23]
	v_pk_mul_f32 v[26:27], v[30:31], v[30:31]
	v_pk_fma_f32 v[32:33], v[148:149], s[12:13], v[16:17] op_sel_hi:[1,0,1]
	v_pk_mul_f32 v[16:17], v[20:21], v[20:21]
	v_pk_mul_f32 v[148:149], v[24:25], v[24:25]
	v_add_f32_e32 v26, v26, v27
	v_add_f32_e32 v6, v6, v7
	v_add_f32_e32 v14, v14, v15
	v_add_f32_e32 v12, v12, v13
	v_pk_mul_f32 v[146:147], v[28:29], v[28:29]
	v_pk_mul_f32 v[150:151], v[32:33], v[32:33]
	v_add_f32_e32 v7, v148, v149
	v_add_f32_e32 v13, v16, v17
	v_add_f32_e32 v6, v6, v26
	v_add_f32_e32 v12, v12, v14
	v_add_f32_e32 v27, v150, v151
	v_add_f32_e32 v15, v146, v147
	v_add_f32_e32 v6, v7, v6
	v_add_f32_e32 v7, v13, v12
	v_add_f32_e32 v6, v27, v6
	v_add_f32_e32 v7, v15, v7
	v_add_f32_e32 v6, v7, v6
	ds_bpermute_b32 v7, v8, v6
	v_cndmask_b32_e64 v9, v192, v9, s[2:3]
	v_lshlrev_b32_e32 v9, 2, v9
	v_cvt_pk_f16_f32 v12, v20, v21
	v_cvt_pk_f16_f32 v13, v28, v29
	s_waitcnt lgkmcnt(0)
	v_add_f32_e32 v6, v6, v7
	ds_bpermute_b32 v7, v9, v6
	v_cvt_pk_f16_f32 v14, v22, v23
	v_cvt_pk_f16_f32 v15, v30, v31
	v_cvt_pk_f16_f32 v16, v24, v25
	v_cvt_pk_f16_f32 v17, v32, v33
	global_store_dwordx4 v[18:19], v[10:13], off sc1
	global_store_dwordx4 v[18:19], v[14:17], off offset:256 sc1
	s_and_saveexec_b64 s[2:3], vcc
	s_cbranch_execz .LBB0_1328
	v_lshl_add_u64 v[10:11], v[4:5], 2, s[18:19]
	s_waitcnt lgkmcnt(0)
	v_add_f32_e32 v5, v6, v7
	global_atomic_add_f32 v[10:11], v5, off
.LBB0_1328:
	s_or_b64 exec, exec, s[2:3]
	v_add_u32_e32 v6, 16, v4
	s_waitcnt lgkmcnt(0)
	v_ashrrev_i32_e32 v7, 31, v6
	v_lshlrev_b64 v[10:11], 11, v[6:7]
	v_lshl_add_u64 v[10:11], s[90:91], 0, v[10:11]
	v_lshl_add_u64 v[18:19], v[2:3], 1, v[10:11]
	global_load_dwordx4 v[10:13], v[18:19], off
	global_load_dwordx4 v[14:17], v[18:19], off offset:256
	s_waitcnt vmcnt(1)
	v_cvt_f32_f16_e32 v20, v10
	v_cvt_f32_f16_sdwa v21, v10 dst_sel:DWORD dst_unused:UNUSED_PAD src0_sel:WORD_1
	v_cvt_f32_f16_e32 v10, v11
	v_cvt_f32_f16_sdwa v11, v11 dst_sel:DWORD dst_unused:UNUSED_PAD src0_sel:WORD_1
	s_waitcnt vmcnt(0)
	v_cvt_f32_f16_e32 v24, v14
	v_cvt_f32_f16_sdwa v25, v14 dst_sel:DWORD dst_unused:UNUSED_PAD src0_sel:WORD_1
	v_cvt_f32_f16_e32 v14, v15
	v_cvt_f32_f16_sdwa v15, v15 dst_sel:DWORD dst_unused:UNUSED_PAD src0_sel:WORD_1
	v_cvt_f32_f16_e32 v22, v12
	v_cvt_f32_f16_sdwa v23, v12 dst_sel:DWORD dst_unused:UNUSED_PAD src0_sel:WORD_1
	v_cvt_f32_f16_e32 v12, v13
	v_cvt_f32_f16_sdwa v13, v13 dst_sel:DWORD dst_unused:UNUSED_PAD src0_sel:WORD_1
	v_cvt_f32_f16_e32 v26, v16
	v_cvt_f32_f16_sdwa v27, v16 dst_sel:DWORD dst_unused:UNUSED_PAD src0_sel:WORD_1
	v_cvt_f32_f16_e32 v16, v17
	v_cvt_f32_f16_sdwa v17, v17 dst_sel:DWORD dst_unused:UNUSED_PAD src0_sel:WORD_1
	v_pk_fma_f32 v[20:21], v[142:143], s[12:13], v[20:21] op_sel_hi:[1,0,1]
	v_pk_fma_f32 v[28:29], v[144:145], s[12:13], v[10:11] op_sel_hi:[1,0,1]
	v_pk_fma_f32 v[24:25], v[134:135], s[12:13], v[24:25] op_sel_hi:[1,0,1]
	v_pk_fma_f32 v[14:15], v[136:137], s[12:13], v[14:15] op_sel_hi:[1,0,1]
	v_pk_fma_f32 v[22:23], v[138:139], s[12:13], v[22:23] op_sel_hi:[1,0,1]
	v_pk_fma_f32 v[30:31], v[140:141], s[12:13], v[12:13] op_sel_hi:[1,0,1]
	v_pk_fma_f32 v[26:27], v[130:131], s[12:13], v[26:27] op_sel_hi:[1,0,1]
	v_pk_mul_f32 v[12:13], v[20:21], v[20:21]
	v_pk_mul_f32 v[32:33], v[28:29], v[28:29]
	v_cvt_pk_f16_f32 v10, v20, v21
	v_cvt_pk_f16_f32 v11, v28, v29
	v_pk_mul_f32 v[20:21], v[24:25], v[24:25]
	v_pk_mul_f32 v[28:29], v[14:15], v[14:15]
	v_pk_fma_f32 v[16:17], v[132:133], s[12:13], v[16:17] op_sel_hi:[1,0,1]
	v_pk_mul_f32 v[130:131], v[22:23], v[22:23]
	v_pk_mul_f32 v[134:135], v[26:27], v[26:27]
	v_add_f32_e32 v5, v28, v29
	v_add_f32_e32 v20, v20, v21
	v_add_f32_e32 v29, v32, v33
	v_add_f32_e32 v12, v12, v13
	v_pk_mul_f32 v[132:133], v[30:31], v[30:31]
	v_pk_mul_f32 v[136:137], v[16:17], v[16:17]
	v_add_f32_e32 v21, v134, v135
	v_add_f32_e32 v13, v130, v131
	v_add_f32_e32 v5, v20, v5
	v_add_f32_e32 v12, v12, v29
	v_add_f32_e32 v28, v136, v137
	v_add_f32_e32 v32, v132, v133
	v_add_f32_e32 v5, v21, v5
	v_add_f32_e32 v12, v13, v12
	v_add_f32_e32 v5, v28, v5
	v_add_f32_e32 v12, v32, v12
	v_add_f32_e32 v5, v12, v5
	ds_bpermute_b32 v20, v8, v5
	v_cvt_pk_f16_f32 v12, v22, v23
	v_cvt_pk_f16_f32 v13, v30, v31
	global_store_dwordx4 v[18:19], v[10:13], off sc1
	s_waitcnt lgkmcnt(0)
	v_add_f32_e32 v5, v5, v20
	ds_bpermute_b32 v10, v9, v5
	v_cvt_pk_f16_f32 v12, v24, v25
	v_cvt_pk_f16_f32 v13, v14, v15
	v_cvt_pk_f16_f32 v14, v26, v27
	v_cvt_pk_f16_f32 v15, v16, v17
	global_store_dwordx4 v[18:19], v[12:15], off offset:256 sc1
	s_and_saveexec_b64 s[2:3], vcc
	s_cbranch_execz .LBB0_1330
; __device__ __forceinline__ unsigned pkh(float lo, float hi) { f32x2 v = {lo, hi}; h16x2 h = __builtin_convertvector(v, h16x2); return __builtin_bit_cast(unsigned, h); }
; __device__ __forceinline__ unsigned pk8(float a, float b, float c, float d) { int w = __builtin_amdgcn_cvt_pk_fp8_f32(a, b, 0, false); w = __builtin_amdgcn_cvt_pk_fp8_f32(c, d, w, true); return (unsigned)w; }
;     __device__ __forceinline__ void operator()(f32x4 (&acc)[2][2][4][2], const Unit& u, const Order& S, int wr, int wc, int fr_, int fq_, LAS unsigned char*, int) const {
;     ...
;         for (int ai = 0; ai < 2; ++ai)
; #pragma unroll
;             for (int m = 0; m < 4; ++m) {
;                 const int row = row0 + ai * HALF + m * 16; const size_t off = (size_t)row * DM + col0;
;                 float sq = 0.f;
; #pragma unroll
;                 for (int bj = 0; bj < 2; ++bj) {
;                     const h16x8 bs = *(const h16x8*)(h16 + off + bj * HALF);
;                     f32x4 o0 = acc[ai][bj][m][0] * pre, o1 = acc[ai][bj][m][1] * pre;
; #pragma unroll
;                     for (int e = 0; e < 4; ++e) { o0[e] += (float)bs[e]; o1[e] += (float)bs[4 + e]; }
;                     if (out32) { if (!dry) { __builtin_nontemporal_store(o0, (f32x4*)(out32 + off + bj * HALF)); __builtin_nontemporal_store(o1, (f32x4*)(out32 + off + bj * HALF + 4)); } }
;                     else if (!dry) {
;                         sq += (o0[0] * o0[0] + o0[1] * o0[1]) + (o0[2] * o0[2] + o0[3] * o0[3]) + (o1[0] * o1[0] + o1[1] * o1[1]) + (o1[2] * o1[2] + o1[3] * o1[3]);
;                         u32x4 w; w.x = pkh(o0[0], o0[1]); w.y = pkh(o0[2], o0[3]); w.z = pkh(o1[0], o1[1]); w.w = pkh(o1[2], o1[3]);
;                         *(u32x4*)(h16 + off + bj * HALF) = w;
;                         if (h8) { u32x2 q; q.x = pk8(o0[0] * F8_SA, o0[1] * F8_SA, o0[2] * F8_SA, o0[3] * F8_SA); q.y = pk8(o1[0] * F8_SA, o1[1] * F8_SA, o1[2] * F8_SA, o1[3] * F8_SA); *(u32x2*)(h8 + off + bj * HALF) = q; } }
;                 }
;                 if (!out32 && !dry) { sq += __shfl_xor(sq, 16); sq += __shfl_xor(sq, 32); if (fq == 0) atomicAdd(ss_out + row, sq); }
	v_lshl_add_u64 v[6:7], v[6:7], 2, s[18:19]
	s_waitcnt lgkmcnt(0)
	v_add_f32_e32 v5, v5, v10
	global_atomic_add_f32 v[6:7], v5, off
.LBB0_1330:
	s_or_b64 exec, exec, s[2:3]
	v_add_u32_e32 v6, 32, v4
	v_ashrrev_i32_e32 v7, 31, v6
	s_waitcnt lgkmcnt(0)
	v_lshlrev_b64 v[10:11], 11, v[6:7]
	v_lshl_add_u64 v[10:11], s[90:91], 0, v[10:11]
	v_lshl_add_u64 v[18:19], v[2:3], 1, v[10:11]
	global_load_dwordx4 v[10:13], v[18:19], off
	global_load_dwordx4 v[14:17], v[18:19], off offset:256
	s_waitcnt vmcnt(1)
	v_cvt_f32_f16_e32 v20, v10
	v_cvt_f32_f16_sdwa v21, v10 dst_sel:DWORD dst_unused:UNUSED_PAD src0_sel:WORD_1
	v_cvt_f32_f16_e32 v10, v11
	v_cvt_f32_f16_sdwa v11, v11 dst_sel:DWORD dst_unused:UNUSED_PAD src0_sel:WORD_1
	s_waitcnt vmcnt(0)
	v_cvt_f32_f16_e32 v24, v14
	v_cvt_f32_f16_sdwa v25, v14 dst_sel:DWORD dst_unused:UNUSED_PAD src0_sel:WORD_1
	v_cvt_f32_f16_e32 v14, v15
	v_cvt_f32_f16_sdwa v15, v15 dst_sel:DWORD dst_unused:UNUSED_PAD src0_sel:WORD_1
	v_cvt_f32_f16_e32 v22, v12
	v_cvt_f32_f16_sdwa v23, v12 dst_sel:DWORD dst_unused:UNUSED_PAD src0_sel:WORD_1
	v_cvt_f32_f16_e32 v12, v13
	v_cvt_f32_f16_sdwa v13, v13 dst_sel:DWORD dst_unused:UNUSED_PAD src0_sel:WORD_1
	v_cvt_f32_f16_e32 v26, v16
	v_cvt_f32_f16_sdwa v27, v16 dst_sel:DWORD dst_unused:UNUSED_PAD src0_sel:WORD_1
	v_cvt_f32_f16_e32 v16, v17
	v_cvt_f32_f16_sdwa v17, v17 dst_sel:DWORD dst_unused:UNUSED_PAD src0_sel:WORD_1
	v_pk_fma_f32 v[20:21], v[126:127], s[12:13], v[20:21] op_sel_hi:[1,0,1]
	v_pk_fma_f32 v[28:29], v[128:129], s[12:13], v[10:11] op_sel_hi:[1,0,1]
	v_pk_fma_f32 v[24:25], v[118:119], s[12:13], v[24:25] op_sel_hi:[1,0,1]
	v_pk_fma_f32 v[14:15], v[120:121], s[12:13], v[14:15] op_sel_hi:[1,0,1]
	v_pk_fma_f32 v[22:23], v[122:123], s[12:13], v[22:23] op_sel_hi:[1,0,1]
	v_pk_fma_f32 v[30:31], v[124:125], s[12:13], v[12:13] op_sel_hi:[1,0,1]
	v_pk_fma_f32 v[26:27], v[114:115], s[12:13], v[26:27] op_sel_hi:[1,0,1]
	v_pk_mul_f32 v[12:13], v[20:21], v[20:21]
	v_pk_mul_f32 v[32:33], v[28:29], v[28:29]
	v_cvt_pk_f16_f32 v10, v20, v21
	v_cvt_pk_f16_f32 v11, v28, v29
	v_pk_mul_f32 v[20:21], v[24:25], v[24:25]
	v_pk_mul_f32 v[28:29], v[14:15], v[14:15]
	v_pk_fma_f32 v[16:17], v[116:117], s[12:13], v[16:17] op_sel_hi:[1,0,1]
	v_pk_mul_f32 v[114:115], v[22:23], v[22:23]
	v_pk_mul_f32 v[118:119], v[26:27], v[26:27]
	v_add_f32_e32 v5, v28, v29
	v_add_f32_e32 v20, v20, v21
	v_add_f32_e32 v29, v32, v33
	v_add_f32_e32 v12, v12, v13
	v_pk_mul_f32 v[116:117], v[30:31], v[30:31]
	v_pk_mul_f32 v[120:121], v[16:17], v[16:17]
	v_add_f32_e32 v21, v118, v119
	v_add_f32_e32 v13, v114, v115
	v_add_f32_e32 v5, v20, v5
	v_add_f32_e32 v12, v12, v29
	v_add_f32_e32 v28, v120, v121
	v_add_f32_e32 v32, v116, v117
	v_add_f32_e32 v5, v21, v5
	v_add_f32_e32 v12, v13, v12
	v_add_f32_e32 v5, v28, v5
	v_add_f32_e32 v12, v32, v12
	v_add_f32_e32 v5, v12, v5
	ds_bpermute_b32 v20, v8, v5
	v_cvt_pk_f16_f32 v12, v22, v23
	v_cvt_pk_f16_f32 v13, v30, v31
	global_store_dwordx4 v[18:19], v[10:13], off sc1
	s_waitcnt lgkmcnt(0)
	v_add_f32_e32 v5, v5, v20
	ds_bpermute_b32 v10, v9, v5
	v_cvt_pk_f16_f32 v12, v24, v25
	v_cvt_pk_f16_f32 v13, v14, v15
	v_cvt_pk_f16_f32 v14, v26, v27
	v_cvt_pk_f16_f32 v15, v16, v17
	global_store_dwordx4 v[18:19], v[12:15], off offset:256 sc1
	s_and_saveexec_b64 s[2:3], vcc
	s_cbranch_execz .LBB0_1332
	v_lshl_add_u64 v[6:7], v[6:7], 2, s[18:19]
	s_waitcnt lgkmcnt(0)
	v_add_f32_e32 v5, v5, v10
	global_atomic_add_f32 v[6:7], v5, off
.LBB0_1332:
	s_or_b64 exec, exec, s[2:3]
	v_add_u32_e32 v6, 48, v4
	v_ashrrev_i32_e32 v7, 31, v6
	s_waitcnt lgkmcnt(0)
	v_lshlrev_b64 v[10:11], 11, v[6:7]
	v_lshl_add_u64 v[10:11], s[90:91], 0, v[10:11]
	v_lshl_add_u64 v[18:19], v[2:3], 1, v[10:11]
	global_load_dwordx4 v[10:13], v[18:19], off
	global_load_dwordx4 v[14:17], v[18:19], off offset:256
	s_waitcnt vmcnt(1)
	v_cvt_f32_f16_e32 v20, v10
	v_cvt_f32_f16_sdwa v21, v10 dst_sel:DWORD dst_unused:UNUSED_PAD src0_sel:WORD_1
	v_cvt_f32_f16_e32 v10, v11
	v_cvt_f32_f16_sdwa v11, v11 dst_sel:DWORD dst_unused:UNUSED_PAD src0_sel:WORD_1
	s_waitcnt vmcnt(0)
	v_cvt_f32_f16_e32 v24, v14
	v_cvt_f32_f16_sdwa v25, v14 dst_sel:DWORD dst_unused:UNUSED_PAD src0_sel:WORD_1
	v_cvt_f32_f16_e32 v14, v15
	v_cvt_f32_f16_sdwa v15, v15 dst_sel:DWORD dst_unused:UNUSED_PAD src0_sel:WORD_1
	v_cvt_f32_f16_e32 v22, v12
	v_cvt_f32_f16_sdwa v23, v12 dst_sel:DWORD dst_unused:UNUSED_PAD src0_sel:WORD_1
	v_cvt_f32_f16_e32 v12, v13
	v_cvt_f32_f16_sdwa v13, v13 dst_sel:DWORD dst_unused:UNUSED_PAD src0_sel:WORD_1
	v_cvt_f32_f16_e32 v26, v16
	v_cvt_f32_f16_sdwa v27, v16 dst_sel:DWORD dst_unused:UNUSED_PAD src0_sel:WORD_1
	v_cvt_f32_f16_e32 v16, v17
	v_cvt_f32_f16_sdwa v17, v17 dst_sel:DWORD dst_unused:UNUSED_PAD src0_sel:WORD_1
	v_pk_fma_f32 v[20:21], v[110:111], s[12:13], v[20:21] op_sel_hi:[1,0,1]
	v_pk_fma_f32 v[28:29], v[112:113], s[12:13], v[10:11] op_sel_hi:[1,0,1]
	v_pk_fma_f32 v[24:25], v[102:103], s[12:13], v[24:25] op_sel_hi:[1,0,1]
	v_pk_fma_f32 v[14:15], v[104:105], s[12:13], v[14:15] op_sel_hi:[1,0,1]
	v_pk_fma_f32 v[22:23], v[106:107], s[12:13], v[22:23] op_sel_hi:[1,0,1]
	v_pk_fma_f32 v[30:31], v[108:109], s[12:13], v[12:13] op_sel_hi:[1,0,1]
	v_pk_fma_f32 v[26:27], v[98:99], s[12:13], v[26:27] op_sel_hi:[1,0,1]
	v_pk_mul_f32 v[12:13], v[20:21], v[20:21]
	v_pk_mul_f32 v[32:33], v[28:29], v[28:29]
	v_cvt_pk_f16_f32 v10, v20, v21
	v_cvt_pk_f16_f32 v11, v28, v29
	v_pk_mul_f32 v[20:21], v[24:25], v[24:25]
	v_pk_mul_f32 v[28:29], v[14:15], v[14:15]
	v_pk_fma_f32 v[16:17], v[100:101], s[12:13], v[16:17] op_sel_hi:[1,0,1]
	v_pk_mul_f32 v[98:99], v[22:23], v[22:23]
	v_pk_mul_f32 v[102:103], v[26:27], v[26:27]
	v_add_f32_e32 v5, v28, v29
	v_add_f32_e32 v20, v20, v21
	v_add_f32_e32 v29, v32, v33
	v_add_f32_e32 v12, v12, v13
	v_pk_mul_f32 v[100:101], v[30:31], v[30:31]
	v_pk_mul_f32 v[104:105], v[16:17], v[16:17]
	v_add_f32_e32 v21, v102, v103
	v_add_f32_e32 v13, v98, v99
	v_add_f32_e32 v5, v20, v5
	v_add_f32_e32 v12, v12, v29
	v_add_f32_e32 v28, v104, v105
	v_add_f32_e32 v32, v100, v101
	v_add_f32_e32 v5, v21, v5
	v_add_f32_e32 v12, v13, v12
	v_add_f32_e32 v5, v28, v5
	v_add_f32_e32 v12, v32, v12
	v_add_f32_e32 v5, v12, v5
	ds_bpermute_b32 v20, v8, v5
	v_cvt_pk_f16_f32 v12, v22, v23
	v_cvt_pk_f16_f32 v13, v30, v31
	global_store_dwordx4 v[18:19], v[10:13], off sc1
	s_waitcnt lgkmcnt(0)
	v_add_f32_e32 v5, v5, v20
	ds_bpermute_b32 v10, v9, v5
	v_cvt_pk_f16_f32 v12, v24, v25
	v_cvt_pk_f16_f32 v13, v14, v15
	v_cvt_pk_f16_f32 v14, v26, v27
	v_cvt_pk_f16_f32 v15, v16, v17
	global_store_dwordx4 v[18:19], v[12:15], off offset:256 sc1
	s_and_saveexec_b64 s[2:3], vcc
	s_cbranch_execz .LBB0_1334
	v_lshl_add_u64 v[6:7], v[6:7], 2, s[18:19]
	s_waitcnt lgkmcnt(0)
	v_add_f32_e32 v5, v5, v10
	global_atomic_add_f32 v[6:7], v5, off
; __device__ __forceinline__ unsigned pkh(float lo, float hi) { f32x2 v = {lo, hi}; h16x2 h = __builtin_convertvector(v, h16x2); return __builtin_bit_cast(unsigned, h); }
; __device__ __forceinline__ unsigned pk8(float a, float b, float c, float d) { int w = __builtin_amdgcn_cvt_pk_fp8_f32(a, b, 0, false); w = __builtin_amdgcn_cvt_pk_fp8_f32(c, d, w, true); return (unsigned)w; }
;     __device__ __forceinline__ void operator()(f32x4 (&acc)[2][2][4][2], const Unit& u, const Order& S, int wr, int wc, int fr_, int fq_, LAS unsigned char*, int) const {
;     ...
;         for (int ai = 0; ai < 2; ++ai)
; #pragma unroll
;             for (int m = 0; m < 4; ++m) {
;                 const int row = row0 + ai * HALF + m * 16; const size_t off = (size_t)row * DM + col0;
;                 float sq = 0.f;
; #pragma unroll
;                 for (int bj = 0; bj < 2; ++bj) {
;                     const h16x8 bs = *(const h16x8*)(h16 + off + bj * HALF);
;                     f32x4 o0 = acc[ai][bj][m][0] * pre, o1 = acc[ai][bj][m][1] * pre;
; #pragma unroll
;                     for (int e = 0; e < 4; ++e) { o0[e] += (float)bs[e]; o1[e] += (float)bs[4 + e]; }
;                     if (out32) { if (!dry) { __builtin_nontemporal_store(o0, (f32x4*)(out32 + off + bj * HALF)); __builtin_nontemporal_store(o1, (f32x4*)(out32 + off + bj * HALF + 4)); } }
;                     else if (!dry) {
;                         sq += (o0[0] * o0[0] + o0[1] * o0[1]) + (o0[2] * o0[2] + o0[3] * o0[3]) + (o1[0] * o1[0] + o1[1] * o1[1]) + (o1[2] * o1[2] + o1[3] * o1[3]);
;                         u32x4 w; w.x = pkh(o0[0], o0[1]); w.y = pkh(o0[2], o0[3]); w.z = pkh(o1[0], o1[1]); w.w = pkh(o1[2], o1[3]);
;                         *(u32x4*)(h16 + off + bj * HALF) = w;
;                         if (h8) { u32x2 q; q.x = pk8(o0[0] * F8_SA, o0[1] * F8_SA, o0[2] * F8_SA, o0[3] * F8_SA); q.y = pk8(o1[0] * F8_SA, o1[1] * F8_SA, o1[2] * F8_SA, o1[3] * F8_SA); *(u32x2*)(h8 + off + bj * HALF) = q; } }
;                 }
;                 if (!out32 && !dry) { sq += __shfl_xor(sq, 16); sq += __shfl_xor(sq, 32); if (fq == 0) atomicAdd(ss_out + row, sq); }
.LBB0_1334:
	s_or_b64 exec, exec, s[2:3]
	v_add_u32_e32 v6, 0x80, v4
	v_ashrrev_i32_e32 v7, 31, v6
	s_waitcnt lgkmcnt(0)
	v_lshlrev_b64 v[10:11], 11, v[6:7]
	v_lshl_add_u64 v[10:11], s[90:91], 0, v[10:11]
	v_lshl_add_u64 v[18:19], v[2:3], 1, v[10:11]
	global_load_dwordx4 v[10:13], v[18:19], off
	global_load_dwordx4 v[14:17], v[18:19], off offset:256
	s_waitcnt vmcnt(1)
	v_cvt_f32_f16_e32 v20, v10
	v_cvt_f32_f16_sdwa v21, v10 dst_sel:DWORD dst_unused:UNUSED_PAD src0_sel:WORD_1
	v_cvt_f32_f16_e32 v10, v11
	v_cvt_f32_f16_sdwa v11, v11 dst_sel:DWORD dst_unused:UNUSED_PAD src0_sel:WORD_1
	s_waitcnt vmcnt(0)
	v_cvt_f32_f16_e32 v24, v14
	v_cvt_f32_f16_sdwa v25, v14 dst_sel:DWORD dst_unused:UNUSED_PAD src0_sel:WORD_1
	v_cvt_f32_f16_e32 v14, v15
	v_cvt_f32_f16_sdwa v15, v15 dst_sel:DWORD dst_unused:UNUSED_PAD src0_sel:WORD_1
	v_cvt_f32_f16_e32 v22, v12
	v_cvt_f32_f16_sdwa v23, v12 dst_sel:DWORD dst_unused:UNUSED_PAD src0_sel:WORD_1
	v_cvt_f32_f16_e32 v12, v13
	v_cvt_f32_f16_sdwa v13, v13 dst_sel:DWORD dst_unused:UNUSED_PAD src0_sel:WORD_1
	v_cvt_f32_f16_e32 v26, v16
	v_cvt_f32_f16_sdwa v27, v16 dst_sel:DWORD dst_unused:UNUSED_PAD src0_sel:WORD_1
	v_cvt_f32_f16_e32 v16, v17
	v_cvt_f32_f16_sdwa v17, v17 dst_sel:DWORD dst_unused:UNUSED_PAD src0_sel:WORD_1
	v_pk_fma_f32 v[20:21], v[94:95], s[12:13], v[20:21] op_sel_hi:[1,0,1]
	v_pk_fma_f32 v[28:29], v[96:97], s[12:13], v[10:11] op_sel_hi:[1,0,1]
	v_pk_fma_f32 v[24:25], v[86:87], s[12:13], v[24:25] op_sel_hi:[1,0,1]
	v_pk_fma_f32 v[14:15], v[88:89], s[12:13], v[14:15] op_sel_hi:[1,0,1]
	v_pk_fma_f32 v[22:23], v[90:91], s[12:13], v[22:23] op_sel_hi:[1,0,1]
	v_pk_fma_f32 v[30:31], v[92:93], s[12:13], v[12:13] op_sel_hi:[1,0,1]
	v_pk_fma_f32 v[26:27], v[82:83], s[12:13], v[26:27] op_sel_hi:[1,0,1]
	v_pk_mul_f32 v[12:13], v[20:21], v[20:21]
	v_pk_mul_f32 v[32:33], v[28:29], v[28:29]
	v_cvt_pk_f16_f32 v10, v20, v21
	v_cvt_pk_f16_f32 v11, v28, v29
	v_pk_mul_f32 v[20:21], v[24:25], v[24:25]
	v_pk_mul_f32 v[28:29], v[14:15], v[14:15]
	v_pk_fma_f32 v[16:17], v[84:85], s[12:13], v[16:17] op_sel_hi:[1,0,1]
	v_pk_mul_f32 v[82:83], v[22:23], v[22:23]
	v_pk_mul_f32 v[86:87], v[26:27], v[26:27]
	v_add_f32_e32 v5, v28, v29
	v_add_f32_e32 v20, v20, v21
	v_add_f32_e32 v29, v32, v33
	v_add_f32_e32 v12, v12, v13
	v_pk_mul_f32 v[84:85], v[30:31], v[30:31]
	v_pk_mul_f32 v[88:89], v[16:17], v[16:17]
	v_add_f32_e32 v21, v86, v87
	v_add_f32_e32 v13, v82, v83
	v_add_f32_e32 v5, v20, v5
	v_add_f32_e32 v12, v12, v29
	v_add_f32_e32 v28, v88, v89
	v_add_f32_e32 v32, v84, v85
	v_add_f32_e32 v5, v21, v5
	v_add_f32_e32 v12, v13, v12
	v_add_f32_e32 v5, v28, v5
	v_add_f32_e32 v12, v32, v12
	v_add_f32_e32 v5, v12, v5
	ds_bpermute_b32 v20, v8, v5
	v_cvt_pk_f16_f32 v12, v22, v23
	v_cvt_pk_f16_f32 v13, v30, v31
	global_store_dwordx4 v[18:19], v[10:13], off sc1
	s_waitcnt lgkmcnt(0)
	v_add_f32_e32 v5, v5, v20
	ds_bpermute_b32 v10, v9, v5
	v_cvt_pk_f16_f32 v12, v24, v25
	v_cvt_pk_f16_f32 v13, v14, v15
	v_cvt_pk_f16_f32 v14, v26, v27
	v_cvt_pk_f16_f32 v15, v16, v17
	global_store_dwordx4 v[18:19], v[12:15], off offset:256 sc1
	s_and_saveexec_b64 s[2:3], vcc
	s_cbranch_execz .LBB0_1336
	v_lshl_add_u64 v[6:7], v[6:7], 2, s[18:19]
	s_waitcnt lgkmcnt(0)
	v_add_f32_e32 v5, v5, v10
	global_atomic_add_f32 v[6:7], v5, off
.LBB0_1336:
	s_or_b64 exec, exec, s[2:3]
	v_add_u32_e32 v6, 0x90, v4
	v_ashrrev_i32_e32 v7, 31, v6
	s_waitcnt lgkmcnt(0)
	v_lshlrev_b64 v[10:11], 11, v[6:7]
	v_lshl_add_u64 v[10:11], s[90:91], 0, v[10:11]
	v_lshl_add_u64 v[18:19], v[2:3], 1, v[10:11]
	global_load_dwordx4 v[10:13], v[18:19], off
	global_load_dwordx4 v[14:17], v[18:19], off offset:256
	s_waitcnt vmcnt(1)
	v_cvt_f32_f16_e32 v20, v10
	v_cvt_f32_f16_sdwa v21, v10 dst_sel:DWORD dst_unused:UNUSED_PAD src0_sel:WORD_1
	v_cvt_f32_f16_e32 v10, v11
	v_cvt_f32_f16_sdwa v11, v11 dst_sel:DWORD dst_unused:UNUSED_PAD src0_sel:WORD_1
	s_waitcnt vmcnt(0)
	v_cvt_f32_f16_e32 v24, v14
	v_cvt_f32_f16_sdwa v25, v14 dst_sel:DWORD dst_unused:UNUSED_PAD src0_sel:WORD_1
	v_cvt_f32_f16_e32 v14, v15
	v_cvt_f32_f16_sdwa v15, v15 dst_sel:DWORD dst_unused:UNUSED_PAD src0_sel:WORD_1
	v_cvt_f32_f16_e32 v22, v12
	v_cvt_f32_f16_sdwa v23, v12 dst_sel:DWORD dst_unused:UNUSED_PAD src0_sel:WORD_1
	v_cvt_f32_f16_e32 v12, v13
	v_cvt_f32_f16_sdwa v13, v13 dst_sel:DWORD dst_unused:UNUSED_PAD src0_sel:WORD_1
	v_cvt_f32_f16_e32 v26, v16
	v_cvt_f32_f16_sdwa v27, v16 dst_sel:DWORD dst_unused:UNUSED_PAD src0_sel:WORD_1
	v_cvt_f32_f16_e32 v16, v17
	v_cvt_f32_f16_sdwa v17, v17 dst_sel:DWORD dst_unused:UNUSED_PAD src0_sel:WORD_1
	v_pk_fma_f32 v[20:21], v[78:79], s[12:13], v[20:21] op_sel_hi:[1,0,1]
	v_pk_fma_f32 v[28:29], v[80:81], s[12:13], v[10:11] op_sel_hi:[1,0,1]
	v_pk_fma_f32 v[24:25], v[70:71], s[12:13], v[24:25] op_sel_hi:[1,0,1]
	v_pk_fma_f32 v[14:15], v[72:73], s[12:13], v[14:15] op_sel_hi:[1,0,1]
	v_pk_fma_f32 v[22:23], v[74:75], s[12:13], v[22:23] op_sel_hi:[1,0,1]
	v_pk_fma_f32 v[30:31], v[76:77], s[12:13], v[12:13] op_sel_hi:[1,0,1]
	v_pk_fma_f32 v[26:27], v[66:67], s[12:13], v[26:27] op_sel_hi:[1,0,1]
	v_pk_mul_f32 v[12:13], v[20:21], v[20:21]
	v_pk_mul_f32 v[32:33], v[28:29], v[28:29]
	v_cvt_pk_f16_f32 v10, v20, v21
	v_cvt_pk_f16_f32 v11, v28, v29
	v_pk_mul_f32 v[20:21], v[24:25], v[24:25]
	v_pk_mul_f32 v[28:29], v[14:15], v[14:15]
	v_pk_fma_f32 v[16:17], v[68:69], s[12:13], v[16:17] op_sel_hi:[1,0,1]
	v_pk_mul_f32 v[66:67], v[22:23], v[22:23]
	v_pk_mul_f32 v[70:71], v[26:27], v[26:27]
	v_add_f32_e32 v5, v28, v29
	v_add_f32_e32 v20, v20, v21
	v_add_f32_e32 v29, v32, v33
	v_add_f32_e32 v12, v12, v13
	v_pk_mul_f32 v[68:69], v[30:31], v[30:31]
	v_pk_mul_f32 v[72:73], v[16:17], v[16:17]
	v_add_f32_e32 v21, v70, v71
	v_add_f32_e32 v13, v66, v67
	v_add_f32_e32 v5, v20, v5
	v_add_f32_e32 v12, v12, v29
	v_add_f32_e32 v28, v72, v73
	v_add_f32_e32 v32, v68, v69
	v_add_f32_e32 v5, v21, v5
	v_add_f32_e32 v12, v13, v12
	v_add_f32_e32 v5, v28, v5
	v_add_f32_e32 v12, v32, v12
	v_add_f32_e32 v5, v12, v5
	ds_bpermute_b32 v20, v8, v5
	v_cvt_pk_f16_f32 v12, v22, v23
	v_cvt_pk_f16_f32 v13, v30, v31
	global_store_dwordx4 v[18:19], v[10:13], off sc1
	s_waitcnt lgkmcnt(0)
	v_add_f32_e32 v5, v5, v20
	ds_bpermute_b32 v10, v9, v5
	v_cvt_pk_f16_f32 v12, v24, v25
	v_cvt_pk_f16_f32 v13, v14, v15
	v_cvt_pk_f16_f32 v14, v26, v27
	v_cvt_pk_f16_f32 v15, v16, v17
	global_store_dwordx4 v[18:19], v[12:15], off offset:256 sc1
	s_and_saveexec_b64 s[2:3], vcc
	s_cbranch_execz .LBB0_1338
	v_lshl_add_u64 v[6:7], v[6:7], 2, s[18:19]
	s_waitcnt lgkmcnt(0)
	v_add_f32_e32 v5, v5, v10
	global_atomic_add_f32 v[6:7], v5, off
; __device__ __forceinline__ unsigned pkh(float lo, float hi) { f32x2 v = {lo, hi}; h16x2 h = __builtin_convertvector(v, h16x2); return __builtin_bit_cast(unsigned, h); }
; __device__ __forceinline__ unsigned pk8(float a, float b, float c, float d) { int w = __builtin_amdgcn_cvt_pk_fp8_f32(a, b, 0, false); w = __builtin_amdgcn_cvt_pk_fp8_f32(c, d, w, true); return (unsigned)w; }
;     __device__ __forceinline__ void operator()(f32x4 (&acc)[2][2][4][2], const Unit& u, const Order& S, int wr, int wc, int fr_, int fq_, LAS unsigned char*, int) const {
;     ...
;         for (int ai = 0; ai < 2; ++ai)
; #pragma unroll
;             for (int m = 0; m < 4; ++m) {
;                 const int row = row0 + ai * HALF + m * 16; const size_t off = (size_t)row * DM + col0;
;                 float sq = 0.f;
; #pragma unroll
;                 for (int bj = 0; bj < 2; ++bj) {
;                     const h16x8 bs = *(const h16x8*)(h16 + off + bj * HALF);
;                     f32x4 o0 = acc[ai][bj][m][0] * pre, o1 = acc[ai][bj][m][1] * pre;
; #pragma unroll
;                     for (int e = 0; e < 4; ++e) { o0[e] += (float)bs[e]; o1[e] += (float)bs[4 + e]; }
;                     if (out32) { if (!dry) { __builtin_nontemporal_store(o0, (f32x4*)(out32 + off + bj * HALF)); __builtin_nontemporal_store(o1, (f32x4*)(out32 + off + bj * HALF + 4)); } }
;                     else if (!dry) {
;                         sq += (o0[0] * o0[0] + o0[1] * o0[1]) + (o0[2] * o0[2] + o0[3] * o0[3]) + (o1[0] * o1[0] + o1[1] * o1[1]) + (o1[2] * o1[2] + o1[3] * o1[3]);
;                         u32x4 w; w.x = pkh(o0[0], o0[1]); w.y = pkh(o0[2], o0[3]); w.z = pkh(o1[0], o1[1]); w.w = pkh(o1[2], o1[3]);
;                         *(u32x4*)(h16 + off + bj * HALF) = w;
;                         if (h8) { u32x2 q; q.x = pk8(o0[0] * F8_SA, o0[1] * F8_SA, o0[2] * F8_SA, o0[3] * F8_SA); q.y = pk8(o1[0] * F8_SA, o1[1] * F8_SA, o1[2] * F8_SA, o1[3] * F8_SA); *(u32x2*)(h8 + off + bj * HALF) = q; } }
;                 }
;                 if (!out32 && !dry) { sq += __shfl_xor(sq, 16); sq += __shfl_xor(sq, 32); if (fq == 0) atomicAdd(ss_out + row, sq); }
.LBB0_1338:
	s_or_b64 exec, exec, s[2:3]
	v_add_u32_e32 v6, 0xa0, v4
	v_ashrrev_i32_e32 v7, 31, v6
	s_waitcnt lgkmcnt(0)
	v_lshlrev_b64 v[10:11], 11, v[6:7]
	v_lshl_add_u64 v[10:11], s[90:91], 0, v[10:11]
	v_lshl_add_u64 v[18:19], v[2:3], 1, v[10:11]
	global_load_dwordx4 v[10:13], v[18:19], off
	global_load_dwordx4 v[14:17], v[18:19], off offset:256
	s_waitcnt vmcnt(1)
	v_cvt_f32_f16_e32 v20, v10
	v_cvt_f32_f16_sdwa v21, v10 dst_sel:DWORD dst_unused:UNUSED_PAD src0_sel:WORD_1
	v_cvt_f32_f16_e32 v10, v11
	v_cvt_f32_f16_sdwa v11, v11 dst_sel:DWORD dst_unused:UNUSED_PAD src0_sel:WORD_1
	s_waitcnt vmcnt(0)
	v_cvt_f32_f16_e32 v24, v14
	v_cvt_f32_f16_sdwa v25, v14 dst_sel:DWORD dst_unused:UNUSED_PAD src0_sel:WORD_1
	v_cvt_f32_f16_e32 v14, v15
	v_cvt_f32_f16_sdwa v15, v15 dst_sel:DWORD dst_unused:UNUSED_PAD src0_sel:WORD_1
	v_cvt_f32_f16_e32 v22, v12
	v_cvt_f32_f16_sdwa v23, v12 dst_sel:DWORD dst_unused:UNUSED_PAD src0_sel:WORD_1
	v_cvt_f32_f16_e32 v12, v13
	v_cvt_f32_f16_sdwa v13, v13 dst_sel:DWORD dst_unused:UNUSED_PAD src0_sel:WORD_1
	v_cvt_f32_f16_e32 v26, v16
	v_cvt_f32_f16_sdwa v27, v16 dst_sel:DWORD dst_unused:UNUSED_PAD src0_sel:WORD_1
	v_cvt_f32_f16_e32 v16, v17
	v_cvt_f32_f16_sdwa v17, v17 dst_sel:DWORD dst_unused:UNUSED_PAD src0_sel:WORD_1
	v_pk_fma_f32 v[20:21], v[62:63], s[12:13], v[20:21] op_sel_hi:[1,0,1]
	v_pk_fma_f32 v[28:29], v[64:65], s[12:13], v[10:11] op_sel_hi:[1,0,1]
	v_pk_fma_f32 v[24:25], v[54:55], s[12:13], v[24:25] op_sel_hi:[1,0,1]
	v_pk_fma_f32 v[14:15], v[56:57], s[12:13], v[14:15] op_sel_hi:[1,0,1]
	v_pk_fma_f32 v[22:23], v[58:59], s[12:13], v[22:23] op_sel_hi:[1,0,1]
	v_pk_fma_f32 v[30:31], v[60:61], s[12:13], v[12:13] op_sel_hi:[1,0,1]
	v_pk_fma_f32 v[26:27], v[50:51], s[12:13], v[26:27] op_sel_hi:[1,0,1]
	v_pk_mul_f32 v[12:13], v[20:21], v[20:21]
	v_pk_mul_f32 v[32:33], v[28:29], v[28:29]
	v_cvt_pk_f16_f32 v10, v20, v21
	v_cvt_pk_f16_f32 v11, v28, v29
	v_pk_mul_f32 v[20:21], v[24:25], v[24:25]
	v_pk_mul_f32 v[28:29], v[14:15], v[14:15]
	v_pk_fma_f32 v[16:17], v[52:53], s[12:13], v[16:17] op_sel_hi:[1,0,1]
	v_pk_mul_f32 v[50:51], v[22:23], v[22:23]
	v_pk_mul_f32 v[54:55], v[26:27], v[26:27]
	v_add_f32_e32 v5, v28, v29
	v_add_f32_e32 v20, v20, v21
	v_add_f32_e32 v29, v32, v33
	v_add_f32_e32 v12, v12, v13
	v_pk_mul_f32 v[52:53], v[30:31], v[30:31]
	v_pk_mul_f32 v[56:57], v[16:17], v[16:17]
	v_add_f32_e32 v21, v54, v55
	v_add_f32_e32 v13, v50, v51
	v_add_f32_e32 v5, v20, v5
	v_add_f32_e32 v12, v12, v29
	v_add_f32_e32 v28, v56, v57
	v_add_f32_e32 v32, v52, v53
	v_add_f32_e32 v5, v21, v5
	v_add_f32_e32 v12, v13, v12
	v_add_f32_e32 v5, v28, v5
	v_add_f32_e32 v12, v32, v12
	v_add_f32_e32 v5, v12, v5
	ds_bpermute_b32 v20, v8, v5
	v_cvt_pk_f16_f32 v12, v22, v23
	v_cvt_pk_f16_f32 v13, v30, v31
	global_store_dwordx4 v[18:19], v[10:13], off sc1
	s_waitcnt lgkmcnt(0)
	v_add_f32_e32 v5, v5, v20
	ds_bpermute_b32 v10, v9, v5
	v_cvt_pk_f16_f32 v12, v24, v25
	v_cvt_pk_f16_f32 v13, v14, v15
	v_cvt_pk_f16_f32 v14, v26, v27
	v_cvt_pk_f16_f32 v15, v16, v17
	global_store_dwordx4 v[18:19], v[12:15], off offset:256 sc1
	s_and_saveexec_b64 s[2:3], vcc
	s_cbranch_execz .LBB0_1340
	v_lshl_add_u64 v[6:7], v[6:7], 2, s[18:19]
	s_waitcnt lgkmcnt(0)
	v_add_f32_e32 v5, v5, v10
	global_atomic_add_f32 v[6:7], v5, off
.LBB0_1340:
	s_or_b64 exec, exec, s[2:3]
	v_add_u32_e32 v4, 0xb0, v4
	v_ashrrev_i32_e32 v5, 31, v4
	v_lshlrev_b64 v[6:7], 11, v[4:5]
	v_lshl_add_u64 v[6:7], s[90:91], 0, v[6:7]
	v_lshl_add_u64 v[18:19], v[2:3], 1, v[6:7]
	s_waitcnt lgkmcnt(0)
	global_load_dwordx4 v[10:13], v[18:19], off
	global_load_dwordx4 v[14:17], v[18:19], off offset:256
	s_waitcnt vmcnt(1)
	v_cvt_f32_f16_e32 v2, v10
	v_cvt_f32_f16_sdwa v3, v10 dst_sel:DWORD dst_unused:UNUSED_PAD src0_sel:WORD_1
	v_cvt_f32_f16_e32 v10, v11
	v_cvt_f32_f16_sdwa v11, v11 dst_sel:DWORD dst_unused:UNUSED_PAD src0_sel:WORD_1
	s_waitcnt vmcnt(0)
	v_cvt_f32_f16_e32 v20, v14
	v_cvt_f32_f16_sdwa v21, v14 dst_sel:DWORD dst_unused:UNUSED_PAD src0_sel:WORD_1
	v_cvt_f32_f16_e32 v14, v15
	v_cvt_f32_f16_sdwa v15, v15 dst_sel:DWORD dst_unused:UNUSED_PAD src0_sel:WORD_1
	v_cvt_f32_f16_e32 v6, v12
	v_cvt_f32_f16_sdwa v7, v12 dst_sel:DWORD dst_unused:UNUSED_PAD src0_sel:WORD_1
	v_cvt_f32_f16_e32 v12, v13
	v_cvt_f32_f16_sdwa v13, v13 dst_sel:DWORD dst_unused:UNUSED_PAD src0_sel:WORD_1
	v_cvt_f32_f16_e32 v22, v16
	v_cvt_f32_f16_sdwa v23, v16 dst_sel:DWORD dst_unused:UNUSED_PAD src0_sel:WORD_1
	v_cvt_f32_f16_e32 v16, v17
	v_cvt_f32_f16_sdwa v17, v17 dst_sel:DWORD dst_unused:UNUSED_PAD src0_sel:WORD_1
	v_pk_fma_f32 v[2:3], v[46:47], s[12:13], v[2:3] op_sel_hi:[1,0,1]
	v_pk_fma_f32 v[24:25], v[48:49], s[12:13], v[10:11] op_sel_hi:[1,0,1]
	v_pk_fma_f32 v[20:21], v[38:39], s[12:13], v[20:21] op_sel_hi:[1,0,1]
	v_pk_fma_f32 v[14:15], v[40:41], s[12:13], v[14:15] op_sel_hi:[1,0,1]
	v_pk_fma_f32 v[6:7], v[42:43], s[12:13], v[6:7] op_sel_hi:[1,0,1]
	v_pk_fma_f32 v[26:27], v[44:45], s[12:13], v[12:13] op_sel_hi:[1,0,1]
	v_pk_fma_f32 v[22:23], v[34:35], s[12:13], v[22:23] op_sel_hi:[1,0,1]
	v_pk_mul_f32 v[12:13], v[2:3], v[2:3]
	v_pk_mul_f32 v[28:29], v[24:25], v[24:25]
	v_cvt_pk_f16_f32 v10, v2, v3
	v_cvt_pk_f16_f32 v11, v24, v25
	v_pk_mul_f32 v[2:3], v[20:21], v[20:21]
	v_pk_mul_f32 v[24:25], v[14:15], v[14:15]
	v_pk_fma_f32 v[16:17], v[36:37], s[12:13], v[16:17] op_sel_hi:[1,0,1]
	v_pk_mul_f32 v[30:31], v[6:7], v[6:7]
	v_pk_mul_f32 v[34:35], v[22:23], v[22:23]
	v_add_f32_e32 v24, v24, v25
	v_add_f32_e32 v2, v2, v3
	v_add_f32_e32 v28, v28, v29
	v_add_f32_e32 v12, v12, v13
	v_pk_mul_f32 v[32:33], v[26:27], v[26:27]
	v_pk_mul_f32 v[36:37], v[16:17], v[16:17]
	v_add_f32_e32 v3, v34, v35
	v_add_f32_e32 v13, v30, v31
	v_add_f32_e32 v2, v2, v24
	v_add_f32_e32 v12, v12, v28
	v_add_f32_e32 v25, v36, v37
	v_add_f32_e32 v29, v32, v33
	v_add_f32_e32 v2, v3, v2
	v_add_f32_e32 v3, v13, v12
	v_add_f32_e32 v2, v25, v2
	v_add_f32_e32 v3, v29, v3
	v_add_f32_e32 v2, v3, v2
	ds_bpermute_b32 v3, v8, v2
	v_cvt_pk_f16_f32 v12, v6, v7
	v_cvt_pk_f16_f32 v13, v26, v27
	v_cvt_pk_f16_f32 v6, v20, v21
	v_cvt_pk_f16_f32 v7, v14, v15
	s_waitcnt lgkmcnt(0)
	v_add_f32_e32 v2, v2, v3
	ds_bpermute_b32 v3, v9, v2
	v_cvt_pk_f16_f32 v8, v22, v23
	v_cvt_pk_f16_f32 v9, v16, v17
	global_store_dwordx4 v[18:19], v[10:13], off sc1
	global_store_dwordx4 v[18:19], v[6:9], off offset:256 sc1
	s_and_saveexec_b64 s[2:3], vcc
	s_cbranch_execz .LBB0_1342
	v_lshl_add_u64 v[4:5], v[4:5], 2, s[18:19]
	s_waitcnt lgkmcnt(0)
	v_add_f32_e32 v2, v2, v3
	global_atomic_add_f32 v[4:5], v2, off
